# GEMM K-loops: satisfied second lgkmcnt(0) behind each pre-MFMA barrier removed; s_setprio 0 moved behind the post-MFMA barrier
# speedup vs baseline: 1.0110x; 1.0020x over previous
.LBB0_270:
	s_ashr_i32 s25, s24, 31
	s_lshl_b64 s[22:23], s[24:25], 19
	s_add_u32 s26, s16, s22
	s_addc_u32 s27, s17, s23
	s_and_b64 s[22:23], s[4:5], exec
	s_cselect_b32 s25, s27, s15
	s_cselect_b32 s56, s26, s14
	s_ashr_i32 s21, s20, 31
	s_lshl_b64 s[22:23], s[20:21], 19
	s_add_u32 s28, s34, s22
	s_addc_u32 s29, s35, s23
	s_and_b64 s[22:23], s[4:5], exec
	s_cselect_b32 s21, s29, s3
	s_cselect_b32 s57, s28, s2
	s_add_u32 s14, s14, 0x40080
	s_addc_u32 s15, s15, 0
	s_add_u32 s58, s2, 0x100
	s_addc_u32 s59, s3, 0
	s_mov_b32 s64, -2
	s_waitcnt lgkmcnt(0)
	s_waitcnt vmcnt(0)
	ds_read_b128 v[136:139], v159
	ds_read_b128 v[164:167], v159 offset:1024
	ds_read_b128 v[180:183], v159 offset:2048
	ds_read_b128 v[184:187], v159 offset:3072
	ds_read_b128 v[188:191], v160
	ds_read_b128 v[196:199], v160 offset:1024
	ds_read_b128 v[200:203], v160 offset:2048
	ds_read_b128 v[204:207], v160 offset:3072
	s_add_u32 s2, s14, 0xfffc0080
	s_addc_u32 s3, s15, -1
	s_cmp_eq_u32 s64, 12
	s_cselect_b32 s23, s25, s3
	s_cselect_b32 s22, s56, s2
	s_cselect_b32 s3, s21, s59
	s_cselect_b32 s2, s57, s58
	v_lshl_add_u64 v[168:169], s[14:15], 0, v[128:129]
	s_add_i32 m0, s31, 0xc000
	ds_read_b128 v[208:211], v161
	ds_read_b128 v[212:215], v161 offset:1024
	ds_read_b128 v[216:219], v161 offset:2048
	ds_read_b128 v[220:223], v161 offset:3072
	ds_read_b128 v[224:227], v161 offset:4096
	ds_read_b128 v[228:231], v161 offset:5120
	ds_read_b128 v[232:235], v161 offset:6144
	ds_read_b128 v[236:239], v161 offset:7168
	global_load_lds_dwordx4 v[168:169], off
	v_lshl_add_u64 v[168:169], s[14:15], 0, v[130:131]
	s_add_i32 m0, s31, 0xe000
	s_nop 0
	global_load_lds_dwordx4 v[168:169], off
	s_waitcnt vmcnt(8)
	s_waitcnt lgkmcnt(0)
	s_barrier
	s_setprio 1
	v_mfma_f32_16x16x32_bf16 v[116:119], v[136:139], v[208:211], 0
	v_mfma_f32_16x16x32_bf16 v[112:115], v[180:183], v[208:211], 0
	v_mfma_f32_16x16x32_bf16 v[108:111], v[136:139], v[216:219], 0
	v_mfma_f32_16x16x32_bf16 v[104:107], v[180:183], v[216:219], 0
	v_mfma_f32_16x16x32_bf16 v[92:95], v[136:139], v[224:227], 0
	v_mfma_f32_16x16x32_bf16 v[88:91], v[180:183], v[224:227], 0
	v_mfma_f32_16x16x32_bf16 v[76:79], v[136:139], v[232:235], 0
	v_mfma_f32_16x16x32_bf16 v[72:75], v[180:183], v[232:235], 0
	v_mfma_f32_16x16x32_bf16 v[116:119], v[164:167], v[212:215], v[116:119]
	v_mfma_f32_16x16x32_bf16 v[112:115], v[184:187], v[212:215], v[112:115]
	v_mfma_f32_16x16x32_bf16 v[108:111], v[164:167], v[220:223], v[108:111]
	v_mfma_f32_16x16x32_bf16 v[104:107], v[184:187], v[220:223], v[104:107]
	v_mfma_f32_16x16x32_bf16 v[92:95], v[164:167], v[228:231], v[92:95]
	v_mfma_f32_16x16x32_bf16 v[88:91], v[184:187], v[228:231], v[88:91]
	v_mfma_f32_16x16x32_bf16 v[76:79], v[164:167], v[236:239], v[76:79]
	v_mfma_f32_16x16x32_bf16 v[72:75], v[184:187], v[236:239], v[72:75]
	v_mfma_f32_16x16x32_bf16 v[124:127], v[188:191], v[208:211], 0
	v_mfma_f32_16x16x32_bf16 v[120:123], v[200:203], v[208:211], 0
	v_mfma_f32_16x16x32_bf16 v[100:103], v[188:191], v[216:219], 0
	v_mfma_f32_16x16x32_bf16 v[96:99], v[200:203], v[216:219], 0
	v_mfma_f32_16x16x32_bf16 v[84:87], v[188:191], v[224:227], 0
	v_mfma_f32_16x16x32_bf16 v[80:83], v[200:203], v[224:227], 0
	v_mfma_f32_16x16x32_bf16 v[68:71], v[188:191], v[232:235], 0
	v_mfma_f32_16x16x32_bf16 v[64:67], v[200:203], v[232:235], 0
	v_mfma_f32_16x16x32_bf16 v[124:127], v[196:199], v[212:215], v[124:127]
	v_mfma_f32_16x16x32_bf16 v[120:123], v[204:207], v[212:215], v[120:123]
	v_mfma_f32_16x16x32_bf16 v[100:103], v[196:199], v[220:223], v[100:103]
	v_mfma_f32_16x16x32_bf16 v[96:99], v[204:207], v[220:223], v[96:99]
	v_mfma_f32_16x16x32_bf16 v[84:87], v[196:199], v[228:231], v[84:87]
	v_mfma_f32_16x16x32_bf16 v[80:83], v[204:207], v[228:231], v[80:83]
	v_mfma_f32_16x16x32_bf16 v[68:71], v[196:199], v[236:239], v[68:71]
	v_mfma_f32_16x16x32_bf16 v[64:67], v[204:207], v[236:239], v[64:67]
	s_barrier
	s_setprio 0
	s_add_i32 s65, s49, s37
	v_lshl_add_u64 v[168:169], s[2:3], 0, v[142:143]
	s_mov_b32 m0, s65
	ds_read_b128 v[208:211], v161 offset:16384
	ds_read_b128 v[212:215], v161 offset:17408
	ds_read_b128 v[216:219], v161 offset:18432
	ds_read_b128 v[220:223], v161 offset:19456
	ds_read_b128 v[224:227], v161 offset:20480
	ds_read_b128 v[228:231], v161 offset:21504
	ds_read_b128 v[232:235], v161 offset:22528
	ds_read_b128 v[236:239], v161 offset:23552
	global_load_lds_dwordx4 v[168:169], off
	s_add_i32 m0, s65, 0x2000
	s_add_u32 s66, s2, 0x40000
	v_lshl_add_u64 v[192:193], s[2:3], 0, v[146:147]
	s_addc_u32 s67, s3, 0
	s_add_i32 s65, s50, s37
	global_load_lds_dwordx4 v[192:193], off
	v_lshl_add_u64 v[240:241], s[66:67], 0, v[142:143]
	s_mov_b32 m0, s65
	v_lshl_add_u64 v[242:243], s[22:23], 0, v[144:145]
	global_load_lds_dwordx4 v[240:241], off
	v_lshl_add_u64 v[240:241], s[66:67], 0, v[146:147]
	s_add_i32 m0, s65, 0x2000
	s_nop 0
	global_load_lds_dwordx4 v[240:241], off
	v_lshl_add_u64 v[240:241], s[22:23], 0, v[140:141]
	s_mov_b32 m0, s31
	s_nop 0
	global_load_lds_dwordx4 v[240:241], off
	s_mov_b32 m0, s38
	s_nop 0
	global_load_lds_dwordx4 v[242:243], off
	s_waitcnt vmcnt(8)
	s_waitcnt lgkmcnt(0)
	s_barrier
	s_setprio 1
	v_mfma_f32_16x16x32_bf16 v[52:55], v[136:139], v[208:211], 0
	v_mfma_f32_16x16x32_bf16 v[48:51], v[180:183], v[208:211], 0
	v_mfma_f32_16x16x32_bf16 v[44:47], v[136:139], v[216:219], 0
	v_mfma_f32_16x16x32_bf16 v[40:43], v[180:183], v[216:219], 0
	v_mfma_f32_16x16x32_bf16 v[28:31], v[136:139], v[224:227], 0
	v_mfma_f32_16x16x32_bf16 v[24:27], v[180:183], v[224:227], 0
	v_mfma_f32_16x16x32_bf16 v[12:15], v[136:139], v[232:235], 0
	v_mfma_f32_16x16x32_bf16 v[8:11], v[180:183], v[232:235], 0
	v_mfma_f32_16x16x32_bf16 v[52:55], v[164:167], v[212:215], v[52:55]
	v_mfma_f32_16x16x32_bf16 v[48:51], v[184:187], v[212:215], v[48:51]
	v_mfma_f32_16x16x32_bf16 v[44:47], v[164:167], v[220:223], v[44:47]
	v_mfma_f32_16x16x32_bf16 v[40:43], v[184:187], v[220:223], v[40:43]
	v_mfma_f32_16x16x32_bf16 v[28:31], v[164:167], v[228:231], v[28:31]
	v_mfma_f32_16x16x32_bf16 v[24:27], v[184:187], v[228:231], v[24:27]
	v_mfma_f32_16x16x32_bf16 v[12:15], v[164:167], v[236:239], v[12:15]
	v_mfma_f32_16x16x32_bf16 v[8:11], v[184:187], v[236:239], v[8:11]
	v_mfma_f32_16x16x32_bf16 v[60:63], v[188:191], v[208:211], 0
	v_mfma_f32_16x16x32_bf16 v[56:59], v[200:203], v[208:211], 0
	v_mfma_f32_16x16x32_bf16 v[36:39], v[188:191], v[216:219], 0
	v_mfma_f32_16x16x32_bf16 v[32:35], v[200:203], v[216:219], 0
	v_mfma_f32_16x16x32_bf16 v[20:23], v[188:191], v[224:227], 0
	v_mfma_f32_16x16x32_bf16 v[16:19], v[200:203], v[224:227], 0
	v_mfma_f32_16x16x32_bf16 v[4:7], v[188:191], v[232:235], 0
	v_mfma_f32_16x16x32_bf16 v[0:3], v[200:203], v[232:235], 0
	v_mfma_f32_16x16x32_bf16 v[60:63], v[196:199], v[212:215], v[60:63]
	v_mfma_f32_16x16x32_bf16 v[56:59], v[204:207], v[212:215], v[56:59]
	v_mfma_f32_16x16x32_bf16 v[36:39], v[196:199], v[220:223], v[36:39]
	v_mfma_f32_16x16x32_bf16 v[32:35], v[204:207], v[220:223], v[32:35]
	v_mfma_f32_16x16x32_bf16 v[20:23], v[196:199], v[228:231], v[20:23]
	v_mfma_f32_16x16x32_bf16 v[16:19], v[204:207], v[228:231], v[16:19]
	v_mfma_f32_16x16x32_bf16 v[4:7], v[196:199], v[236:239], v[4:7]
	v_mfma_f32_16x16x32_bf16 v[0:3], v[204:207], v[236:239], v[0:3]
	s_barrier
	s_setprio 0
	s_add_i32 s65, 0, 0x18000
	v_add_u32_e32 v163, s65, v156
	s_add_i32 s66, 0, 0x1c000
	ds_read_b128 v[136:139], v163
	ds_read_b128 v[164:167], v163 offset:1024
	ds_read_b128 v[180:183], v163 offset:2048
	ds_read_b128 v[184:187], v163 offset:3072
	v_add_u32_e32 v163, s66, v156
	ds_read_b128 v[188:191], v163
	ds_read_b128 v[196:199], v163 offset:1024
	ds_read_b128 v[200:203], v163 offset:2048
	ds_read_b128 v[204:207], v163 offset:3072
	s_add_u32 s22, s22, 0x40000
	s_addc_u32 s23, s23, 0
	s_mov_b32 m0, s39
	v_lshl_add_u64 v[244:245], s[22:23], 0, v[140:141]
	ds_read_b128 v[208:211], v161 offset:32768
	ds_read_b128 v[212:215], v161 offset:33792
	ds_read_b128 v[216:219], v161 offset:34816
	ds_read_b128 v[220:223], v161 offset:35840
	ds_read_b128 v[224:227], v161 offset:36864
	ds_read_b128 v[228:231], v161 offset:37888
	ds_read_b128 v[232:235], v161 offset:38912
	ds_read_b128 v[236:239], v161 offset:39936
	global_load_lds_dwordx4 v[244:245], off
	v_lshl_add_u64 v[244:245], s[22:23], 0, v[144:145]
	s_mov_b32 m0, s40
	s_nop 0
	global_load_lds_dwordx4 v[244:245], off
	s_waitcnt vmcnt(8)
	s_waitcnt lgkmcnt(0)
	s_barrier
	s_setprio 1
	v_mfma_f32_16x16x32_bf16 v[116:119], v[136:139], v[208:211], v[116:119]
	v_mfma_f32_16x16x32_bf16 v[112:115], v[180:183], v[208:211], v[112:115]
	v_mfma_f32_16x16x32_bf16 v[108:111], v[136:139], v[216:219], v[108:111]
	v_mfma_f32_16x16x32_bf16 v[104:107], v[180:183], v[216:219], v[104:107]
	v_mfma_f32_16x16x32_bf16 v[92:95], v[136:139], v[224:227], v[92:95]
	v_mfma_f32_16x16x32_bf16 v[88:91], v[180:183], v[224:227], v[88:91]
	v_mfma_f32_16x16x32_bf16 v[76:79], v[136:139], v[232:235], v[76:79]
	v_mfma_f32_16x16x32_bf16 v[72:75], v[180:183], v[232:235], v[72:75]
	v_mfma_f32_16x16x32_bf16 v[116:119], v[164:167], v[212:215], v[116:119]
	v_mfma_f32_16x16x32_bf16 v[112:115], v[184:187], v[212:215], v[112:115]
	v_mfma_f32_16x16x32_bf16 v[108:111], v[164:167], v[220:223], v[108:111]
	v_mfma_f32_16x16x32_bf16 v[104:107], v[184:187], v[220:223], v[104:107]
	v_mfma_f32_16x16x32_bf16 v[92:95], v[164:167], v[228:231], v[92:95]
	v_mfma_f32_16x16x32_bf16 v[88:91], v[184:187], v[228:231], v[88:91]
	v_mfma_f32_16x16x32_bf16 v[76:79], v[164:167], v[236:239], v[76:79]
	v_mfma_f32_16x16x32_bf16 v[72:75], v[184:187], v[236:239], v[72:75]
	v_mfma_f32_16x16x32_bf16 v[124:127], v[188:191], v[208:211], v[124:127]
	v_mfma_f32_16x16x32_bf16 v[120:123], v[200:203], v[208:211], v[120:123]
	v_mfma_f32_16x16x32_bf16 v[100:103], v[188:191], v[216:219], v[100:103]
	v_mfma_f32_16x16x32_bf16 v[96:99], v[200:203], v[216:219], v[96:99]
	v_mfma_f32_16x16x32_bf16 v[84:87], v[188:191], v[224:227], v[84:87]
	v_mfma_f32_16x16x32_bf16 v[80:83], v[200:203], v[224:227], v[80:83]
	v_mfma_f32_16x16x32_bf16 v[68:71], v[188:191], v[232:235], v[68:71]
	v_mfma_f32_16x16x32_bf16 v[64:67], v[200:203], v[232:235], v[64:67]
	v_mfma_f32_16x16x32_bf16 v[124:127], v[196:199], v[212:215], v[124:127]
	v_mfma_f32_16x16x32_bf16 v[120:123], v[204:207], v[212:215], v[120:123]
	v_mfma_f32_16x16x32_bf16 v[100:103], v[196:199], v[220:223], v[100:103]
	v_mfma_f32_16x16x32_bf16 v[96:99], v[204:207], v[220:223], v[96:99]
	v_mfma_f32_16x16x32_bf16 v[84:87], v[196:199], v[228:231], v[84:87]
	v_mfma_f32_16x16x32_bf16 v[80:83], v[204:207], v[228:231], v[80:83]
	v_mfma_f32_16x16x32_bf16 v[68:71], v[196:199], v[236:239], v[68:71]
	v_mfma_f32_16x16x32_bf16 v[64:67], v[204:207], v[236:239], v[64:67]
	s_barrier
	s_setprio 0
	s_add_i32 s22, s65, s37
	v_lshl_add_u64 v[168:169], v[168:169], 0, s[10:11]
	s_mov_b32 m0, s22
	ds_read_b128 v[208:211], v161 offset:49152
	ds_read_b128 v[212:215], v161 offset:50176
	ds_read_b128 v[216:219], v161 offset:51200
	ds_read_b128 v[220:223], v161 offset:52224
	ds_read_b128 v[224:227], v161 offset:53248
	ds_read_b128 v[228:231], v161 offset:54272
	ds_read_b128 v[232:235], v161 offset:55296
	ds_read_b128 v[236:239], v161 offset:56320
	global_load_lds_dwordx4 v[168:169], off
	s_add_i32 m0, s22, 0x2000
	s_add_u32 s2, s2, 0x40080
	v_lshl_add_u64 v[168:169], v[192:193], 0, s[10:11]
	s_addc_u32 s3, s3, 0
	s_add_i32 s22, s66, s37
	global_load_lds_dwordx4 v[168:169], off
	v_lshl_add_u64 v[168:169], s[2:3], 0, v[142:143]
	s_mov_b32 m0, s22
	s_nop 0
	global_load_lds_dwordx4 v[168:169], off
	v_lshl_add_u64 v[168:169], s[2:3], 0, v[146:147]
	s_add_i32 m0, s22, 0x2000
	s_nop 0
	global_load_lds_dwordx4 v[168:169], off
	v_lshl_add_u64 v[168:169], v[240:241], 0, s[10:11]
	s_mov_b32 m0, s43
	s_nop 0
	global_load_lds_dwordx4 v[168:169], off
	v_lshl_add_u64 v[168:169], v[242:243], 0, s[10:11]
	s_mov_b32 m0, s44
	s_nop 0
	global_load_lds_dwordx4 v[168:169], off
	s_waitcnt vmcnt(8)
	s_waitcnt lgkmcnt(0)
	s_barrier
	s_setprio 1
	v_mfma_f32_16x16x32_bf16 v[52:55], v[136:139], v[208:211], v[52:55]
	v_mfma_f32_16x16x32_bf16 v[48:51], v[180:183], v[208:211], v[48:51]
	v_mfma_f32_16x16x32_bf16 v[44:47], v[136:139], v[216:219], v[44:47]
	v_mfma_f32_16x16x32_bf16 v[40:43], v[180:183], v[216:219], v[40:43]
	v_mfma_f32_16x16x32_bf16 v[28:31], v[136:139], v[224:227], v[28:31]
	v_mfma_f32_16x16x32_bf16 v[24:27], v[180:183], v[224:227], v[24:27]
	v_mfma_f32_16x16x32_bf16 v[12:15], v[136:139], v[232:235], v[12:15]
	v_mfma_f32_16x16x32_bf16 v[8:11], v[180:183], v[232:235], v[8:11]
	v_mfma_f32_16x16x32_bf16 v[52:55], v[164:167], v[212:215], v[52:55]
	v_mfma_f32_16x16x32_bf16 v[48:51], v[184:187], v[212:215], v[48:51]
	v_mfma_f32_16x16x32_bf16 v[44:47], v[164:167], v[220:223], v[44:47]
	v_mfma_f32_16x16x32_bf16 v[40:43], v[184:187], v[220:223], v[40:43]
	v_mfma_f32_16x16x32_bf16 v[28:31], v[164:167], v[228:231], v[28:31]
	v_mfma_f32_16x16x32_bf16 v[24:27], v[184:187], v[228:231], v[24:27]
	v_mfma_f32_16x16x32_bf16 v[12:15], v[164:167], v[236:239], v[12:15]
	v_mfma_f32_16x16x32_bf16 v[8:11], v[184:187], v[236:239], v[8:11]
	v_mfma_f32_16x16x32_bf16 v[60:63], v[188:191], v[208:211], v[60:63]
	v_mfma_f32_16x16x32_bf16 v[56:59], v[200:203], v[208:211], v[56:59]
	v_mfma_f32_16x16x32_bf16 v[36:39], v[188:191], v[216:219], v[36:39]
	v_mfma_f32_16x16x32_bf16 v[32:35], v[200:203], v[216:219], v[32:35]
	v_mfma_f32_16x16x32_bf16 v[20:23], v[188:191], v[224:227], v[20:23]
	v_mfma_f32_16x16x32_bf16 v[16:19], v[200:203], v[224:227], v[16:19]
	v_mfma_f32_16x16x32_bf16 v[4:7], v[188:191], v[232:235], v[4:7]
	v_mfma_f32_16x16x32_bf16 v[0:3], v[200:203], v[232:235], v[0:3]
	v_mfma_f32_16x16x32_bf16 v[60:63], v[196:199], v[212:215], v[60:63]
	v_mfma_f32_16x16x32_bf16 v[56:59], v[204:207], v[212:215], v[56:59]
	v_mfma_f32_16x16x32_bf16 v[36:39], v[196:199], v[220:223], v[36:39]
	v_mfma_f32_16x16x32_bf16 v[32:35], v[204:207], v[220:223], v[32:35]
	v_mfma_f32_16x16x32_bf16 v[20:23], v[196:199], v[228:231], v[20:23]
	v_mfma_f32_16x16x32_bf16 v[16:19], v[204:207], v[228:231], v[16:19]
	v_mfma_f32_16x16x32_bf16 v[4:7], v[196:199], v[236:239], v[4:7]
	v_mfma_f32_16x16x32_bf16 v[0:3], v[204:207], v[236:239], v[0:3]
	s_barrier
	s_setprio 0
	s_add_i32 s64, s64, 2
	s_add_u32 s14, s14, 0x100
	s_addc_u32 s15, s15, 0
	s_add_u32 s58, s58, 0x100
	s_addc_u32 s59, s59, 0
	s_cmp_gt_u32 s64, 13
	s_cbranch_scc1 .Lgemm_kdone_0
.LBB0_271:
	ds_read_b128 v[136:139], v159
	ds_read_b128 v[164:167], v159 offset:1024
	ds_read_b128 v[180:183], v159 offset:2048
	ds_read_b128 v[184:187], v159 offset:3072
	ds_read_b128 v[188:191], v160
	ds_read_b128 v[196:199], v160 offset:1024
	ds_read_b128 v[200:203], v160 offset:2048
	ds_read_b128 v[204:207], v160 offset:3072
	s_add_u32 s2, s14, 0xfffc0080
	s_addc_u32 s3, s15, -1
	s_cmp_eq_u32 s64, 12
	s_cselect_b32 s23, s25, s3
	s_cselect_b32 s22, s56, s2
	s_cselect_b32 s3, s21, s59
	s_cselect_b32 s2, s57, s58
	v_lshl_add_u64 v[168:169], s[14:15], 0, v[128:129]
	s_add_i32 m0, s31, 0xc000
	ds_read_b128 v[208:211], v161
	ds_read_b128 v[212:215], v161 offset:1024
	ds_read_b128 v[216:219], v161 offset:2048
	ds_read_b128 v[220:223], v161 offset:3072
	ds_read_b128 v[224:227], v161 offset:4096
	ds_read_b128 v[228:231], v161 offset:5120
	ds_read_b128 v[232:235], v161 offset:6144
	ds_read_b128 v[236:239], v161 offset:7168
	global_load_lds_dwordx4 v[168:169], off
	v_lshl_add_u64 v[168:169], s[14:15], 0, v[130:131]
	s_add_i32 m0, s31, 0xe000
	s_nop 0
	global_load_lds_dwordx4 v[168:169], off
	s_waitcnt vmcnt(8)
	s_waitcnt lgkmcnt(0)
	s_barrier
	s_setprio 1
	v_mfma_f32_16x16x32_bf16 v[116:119], v[136:139], v[208:211], v[116:119]
	v_mfma_f32_16x16x32_bf16 v[112:115], v[180:183], v[208:211], v[112:115]
	v_mfma_f32_16x16x32_bf16 v[108:111], v[136:139], v[216:219], v[108:111]
	v_mfma_f32_16x16x32_bf16 v[104:107], v[180:183], v[216:219], v[104:107]
	v_mfma_f32_16x16x32_bf16 v[92:95], v[136:139], v[224:227], v[92:95]
	v_mfma_f32_16x16x32_bf16 v[88:91], v[180:183], v[224:227], v[88:91]
	v_mfma_f32_16x16x32_bf16 v[76:79], v[136:139], v[232:235], v[76:79]
	v_mfma_f32_16x16x32_bf16 v[72:75], v[180:183], v[232:235], v[72:75]
	v_mfma_f32_16x16x32_bf16 v[116:119], v[164:167], v[212:215], v[116:119]
	v_mfma_f32_16x16x32_bf16 v[112:115], v[184:187], v[212:215], v[112:115]
	v_mfma_f32_16x16x32_bf16 v[108:111], v[164:167], v[220:223], v[108:111]
	v_mfma_f32_16x16x32_bf16 v[104:107], v[184:187], v[220:223], v[104:107]
	v_mfma_f32_16x16x32_bf16 v[92:95], v[164:167], v[228:231], v[92:95]
	v_mfma_f32_16x16x32_bf16 v[88:91], v[184:187], v[228:231], v[88:91]
	v_mfma_f32_16x16x32_bf16 v[76:79], v[164:167], v[236:239], v[76:79]
	v_mfma_f32_16x16x32_bf16 v[72:75], v[184:187], v[236:239], v[72:75]
	v_mfma_f32_16x16x32_bf16 v[124:127], v[188:191], v[208:211], v[124:127]
	v_mfma_f32_16x16x32_bf16 v[120:123], v[200:203], v[208:211], v[120:123]
	v_mfma_f32_16x16x32_bf16 v[100:103], v[188:191], v[216:219], v[100:103]
	v_mfma_f32_16x16x32_bf16 v[96:99], v[200:203], v[216:219], v[96:99]
	v_mfma_f32_16x16x32_bf16 v[84:87], v[188:191], v[224:227], v[84:87]
	v_mfma_f32_16x16x32_bf16 v[80:83], v[200:203], v[224:227], v[80:83]
	v_mfma_f32_16x16x32_bf16 v[68:71], v[188:191], v[232:235], v[68:71]
	v_mfma_f32_16x16x32_bf16 v[64:67], v[200:203], v[232:235], v[64:67]
	v_mfma_f32_16x16x32_bf16 v[124:127], v[196:199], v[212:215], v[124:127]
	v_mfma_f32_16x16x32_bf16 v[120:123], v[204:207], v[212:215], v[120:123]
	v_mfma_f32_16x16x32_bf16 v[100:103], v[196:199], v[220:223], v[100:103]
	v_mfma_f32_16x16x32_bf16 v[96:99], v[204:207], v[220:223], v[96:99]
	v_mfma_f32_16x16x32_bf16 v[84:87], v[196:199], v[228:231], v[84:87]
	v_mfma_f32_16x16x32_bf16 v[80:83], v[204:207], v[228:231], v[80:83]
	v_mfma_f32_16x16x32_bf16 v[68:71], v[196:199], v[236:239], v[68:71]
	v_mfma_f32_16x16x32_bf16 v[64:67], v[204:207], v[236:239], v[64:67]
	s_barrier
	s_setprio 0
	s_add_i32 s65, s49, s37
	v_lshl_add_u64 v[168:169], s[2:3], 0, v[142:143]
	s_mov_b32 m0, s65
	ds_read_b128 v[208:211], v161 offset:16384
	ds_read_b128 v[212:215], v161 offset:17408
	ds_read_b128 v[216:219], v161 offset:18432
	ds_read_b128 v[220:223], v161 offset:19456
	ds_read_b128 v[224:227], v161 offset:20480
	ds_read_b128 v[228:231], v161 offset:21504
	ds_read_b128 v[232:235], v161 offset:22528
	ds_read_b128 v[236:239], v161 offset:23552
	global_load_lds_dwordx4 v[168:169], off
	s_add_i32 m0, s65, 0x2000
	s_add_u32 s66, s2, 0x40000
	v_lshl_add_u64 v[192:193], s[2:3], 0, v[146:147]
	s_addc_u32 s67, s3, 0
	s_add_i32 s65, s50, s37
	global_load_lds_dwordx4 v[192:193], off
	v_lshl_add_u64 v[240:241], s[66:67], 0, v[142:143]
	s_mov_b32 m0, s65
	v_lshl_add_u64 v[242:243], s[22:23], 0, v[144:145]
	global_load_lds_dwordx4 v[240:241], off
	v_lshl_add_u64 v[240:241], s[66:67], 0, v[146:147]
	s_add_i32 m0, s65, 0x2000
	s_nop 0
	global_load_lds_dwordx4 v[240:241], off
	v_lshl_add_u64 v[240:241], s[22:23], 0, v[140:141]
	s_mov_b32 m0, s31
	s_nop 0
	global_load_lds_dwordx4 v[240:241], off
	s_mov_b32 m0, s38
	s_nop 0
	global_load_lds_dwordx4 v[242:243], off
	s_waitcnt vmcnt(8)
	s_waitcnt lgkmcnt(0)
	s_barrier
	s_setprio 1
	v_mfma_f32_16x16x32_bf16 v[52:55], v[136:139], v[208:211], v[52:55]
	v_mfma_f32_16x16x32_bf16 v[48:51], v[180:183], v[208:211], v[48:51]
	v_mfma_f32_16x16x32_bf16 v[44:47], v[136:139], v[216:219], v[44:47]
	v_mfma_f32_16x16x32_bf16 v[40:43], v[180:183], v[216:219], v[40:43]
	v_mfma_f32_16x16x32_bf16 v[28:31], v[136:139], v[224:227], v[28:31]
	v_mfma_f32_16x16x32_bf16 v[24:27], v[180:183], v[224:227], v[24:27]
	v_mfma_f32_16x16x32_bf16 v[12:15], v[136:139], v[232:235], v[12:15]
	v_mfma_f32_16x16x32_bf16 v[8:11], v[180:183], v[232:235], v[8:11]
	v_mfma_f32_16x16x32_bf16 v[52:55], v[164:167], v[212:215], v[52:55]
	v_mfma_f32_16x16x32_bf16 v[48:51], v[184:187], v[212:215], v[48:51]
	v_mfma_f32_16x16x32_bf16 v[44:47], v[164:167], v[220:223], v[44:47]
	v_mfma_f32_16x16x32_bf16 v[40:43], v[184:187], v[220:223], v[40:43]
	v_mfma_f32_16x16x32_bf16 v[28:31], v[164:167], v[228:231], v[28:31]
	v_mfma_f32_16x16x32_bf16 v[24:27], v[184:187], v[228:231], v[24:27]
	v_mfma_f32_16x16x32_bf16 v[12:15], v[164:167], v[236:239], v[12:15]
	v_mfma_f32_16x16x32_bf16 v[8:11], v[184:187], v[236:239], v[8:11]
	v_mfma_f32_16x16x32_bf16 v[60:63], v[188:191], v[208:211], v[60:63]
	v_mfma_f32_16x16x32_bf16 v[56:59], v[200:203], v[208:211], v[56:59]
	v_mfma_f32_16x16x32_bf16 v[36:39], v[188:191], v[216:219], v[36:39]
	v_mfma_f32_16x16x32_bf16 v[32:35], v[200:203], v[216:219], v[32:35]
	v_mfma_f32_16x16x32_bf16 v[20:23], v[188:191], v[224:227], v[20:23]
	v_mfma_f32_16x16x32_bf16 v[16:19], v[200:203], v[224:227], v[16:19]
	v_mfma_f32_16x16x32_bf16 v[4:7], v[188:191], v[232:235], v[4:7]
	v_mfma_f32_16x16x32_bf16 v[0:3], v[200:203], v[232:235], v[0:3]
	v_mfma_f32_16x16x32_bf16 v[60:63], v[196:199], v[212:215], v[60:63]
	v_mfma_f32_16x16x32_bf16 v[56:59], v[204:207], v[212:215], v[56:59]
	v_mfma_f32_16x16x32_bf16 v[36:39], v[196:199], v[220:223], v[36:39]
	v_mfma_f32_16x16x32_bf16 v[32:35], v[204:207], v[220:223], v[32:35]
	v_mfma_f32_16x16x32_bf16 v[20:23], v[196:199], v[228:231], v[20:23]
	v_mfma_f32_16x16x32_bf16 v[16:19], v[204:207], v[228:231], v[16:19]
	v_mfma_f32_16x16x32_bf16 v[4:7], v[196:199], v[236:239], v[4:7]
	v_mfma_f32_16x16x32_bf16 v[0:3], v[204:207], v[236:239], v[0:3]
	s_barrier
	s_setprio 0
	s_add_i32 s65, 0, 0x18000
	v_add_u32_e32 v163, s65, v156
	s_add_i32 s66, 0, 0x1c000
	ds_read_b128 v[136:139], v163
	ds_read_b128 v[164:167], v163 offset:1024
	ds_read_b128 v[180:183], v163 offset:2048
	ds_read_b128 v[184:187], v163 offset:3072
	v_add_u32_e32 v163, s66, v156
	ds_read_b128 v[188:191], v163
	ds_read_b128 v[196:199], v163 offset:1024
	ds_read_b128 v[200:203], v163 offset:2048
	ds_read_b128 v[204:207], v163 offset:3072
	s_add_u32 s22, s22, 0x40000
	s_addc_u32 s23, s23, 0
	s_mov_b32 m0, s39
	v_lshl_add_u64 v[244:245], s[22:23], 0, v[140:141]
	ds_read_b128 v[208:211], v161 offset:32768
	ds_read_b128 v[212:215], v161 offset:33792
	ds_read_b128 v[216:219], v161 offset:34816
	ds_read_b128 v[220:223], v161 offset:35840
	ds_read_b128 v[224:227], v161 offset:36864
	ds_read_b128 v[228:231], v161 offset:37888
	ds_read_b128 v[232:235], v161 offset:38912
	ds_read_b128 v[236:239], v161 offset:39936
	global_load_lds_dwordx4 v[244:245], off
	v_lshl_add_u64 v[244:245], s[22:23], 0, v[144:145]
	s_mov_b32 m0, s40
	s_nop 0
	global_load_lds_dwordx4 v[244:245], off
	s_waitcnt vmcnt(8)
	s_waitcnt lgkmcnt(0)
	s_barrier
	s_setprio 1
	v_mfma_f32_16x16x32_bf16 v[116:119], v[136:139], v[208:211], v[116:119]
	v_mfma_f32_16x16x32_bf16 v[112:115], v[180:183], v[208:211], v[112:115]
	v_mfma_f32_16x16x32_bf16 v[108:111], v[136:139], v[216:219], v[108:111]
	v_mfma_f32_16x16x32_bf16 v[104:107], v[180:183], v[216:219], v[104:107]
	v_mfma_f32_16x16x32_bf16 v[92:95], v[136:139], v[224:227], v[92:95]
	v_mfma_f32_16x16x32_bf16 v[88:91], v[180:183], v[224:227], v[88:91]
	v_mfma_f32_16x16x32_bf16 v[76:79], v[136:139], v[232:235], v[76:79]
	v_mfma_f32_16x16x32_bf16 v[72:75], v[180:183], v[232:235], v[72:75]
	v_mfma_f32_16x16x32_bf16 v[116:119], v[164:167], v[212:215], v[116:119]
	v_mfma_f32_16x16x32_bf16 v[112:115], v[184:187], v[212:215], v[112:115]
	v_mfma_f32_16x16x32_bf16 v[108:111], v[164:167], v[220:223], v[108:111]
	v_mfma_f32_16x16x32_bf16 v[104:107], v[184:187], v[220:223], v[104:107]
	v_mfma_f32_16x16x32_bf16 v[92:95], v[164:167], v[228:231], v[92:95]
	v_mfma_f32_16x16x32_bf16 v[88:91], v[184:187], v[228:231], v[88:91]
	v_mfma_f32_16x16x32_bf16 v[76:79], v[164:167], v[236:239], v[76:79]
	v_mfma_f32_16x16x32_bf16 v[72:75], v[184:187], v[236:239], v[72:75]
	v_mfma_f32_16x16x32_bf16 v[124:127], v[188:191], v[208:211], v[124:127]
	v_mfma_f32_16x16x32_bf16 v[120:123], v[200:203], v[208:211], v[120:123]
	v_mfma_f32_16x16x32_bf16 v[100:103], v[188:191], v[216:219], v[100:103]
	v_mfma_f32_16x16x32_bf16 v[96:99], v[200:203], v[216:219], v[96:99]
	v_mfma_f32_16x16x32_bf16 v[84:87], v[188:191], v[224:227], v[84:87]
	v_mfma_f32_16x16x32_bf16 v[80:83], v[200:203], v[224:227], v[80:83]
	v_mfma_f32_16x16x32_bf16 v[68:71], v[188:191], v[232:235], v[68:71]
	v_mfma_f32_16x16x32_bf16 v[64:67], v[200:203], v[232:235], v[64:67]
	v_mfma_f32_16x16x32_bf16 v[124:127], v[196:199], v[212:215], v[124:127]
	v_mfma_f32_16x16x32_bf16 v[120:123], v[204:207], v[212:215], v[120:123]
	v_mfma_f32_16x16x32_bf16 v[100:103], v[196:199], v[220:223], v[100:103]
	v_mfma_f32_16x16x32_bf16 v[96:99], v[204:207], v[220:223], v[96:99]
	v_mfma_f32_16x16x32_bf16 v[84:87], v[196:199], v[228:231], v[84:87]
	v_mfma_f32_16x16x32_bf16 v[80:83], v[204:207], v[228:231], v[80:83]
	v_mfma_f32_16x16x32_bf16 v[68:71], v[196:199], v[236:239], v[68:71]
	v_mfma_f32_16x16x32_bf16 v[64:67], v[204:207], v[236:239], v[64:67]
	s_barrier
	s_setprio 0
	s_add_i32 s22, s65, s37
	v_lshl_add_u64 v[168:169], v[168:169], 0, s[10:11]
	s_mov_b32 m0, s22
	ds_read_b128 v[208:211], v161 offset:49152
	ds_read_b128 v[212:215], v161 offset:50176
	ds_read_b128 v[216:219], v161 offset:51200
	ds_read_b128 v[220:223], v161 offset:52224
	ds_read_b128 v[224:227], v161 offset:53248
	ds_read_b128 v[228:231], v161 offset:54272
	ds_read_b128 v[232:235], v161 offset:55296
	ds_read_b128 v[236:239], v161 offset:56320
	global_load_lds_dwordx4 v[168:169], off
	s_add_i32 m0, s22, 0x2000
	s_add_u32 s2, s2, 0x40080
	v_lshl_add_u64 v[168:169], v[192:193], 0, s[10:11]
	s_addc_u32 s3, s3, 0
	s_add_i32 s22, s66, s37
	global_load_lds_dwordx4 v[168:169], off
	v_lshl_add_u64 v[168:169], s[2:3], 0, v[142:143]
	s_mov_b32 m0, s22
	s_nop 0
	global_load_lds_dwordx4 v[168:169], off
	v_lshl_add_u64 v[168:169], s[2:3], 0, v[146:147]
	s_add_i32 m0, s22, 0x2000
	s_nop 0
	global_load_lds_dwordx4 v[168:169], off
	v_lshl_add_u64 v[168:169], v[240:241], 0, s[10:11]
	s_mov_b32 m0, s43
	s_nop 0
	global_load_lds_dwordx4 v[168:169], off
	v_lshl_add_u64 v[168:169], v[242:243], 0, s[10:11]
	s_mov_b32 m0, s44
	s_nop 0
	global_load_lds_dwordx4 v[168:169], off
	s_waitcnt vmcnt(8)
	s_waitcnt lgkmcnt(0)
	s_barrier
	s_setprio 1
	v_mfma_f32_16x16x32_bf16 v[52:55], v[136:139], v[208:211], v[52:55]
	v_mfma_f32_16x16x32_bf16 v[48:51], v[180:183], v[208:211], v[48:51]
	v_mfma_f32_16x16x32_bf16 v[44:47], v[136:139], v[216:219], v[44:47]
	v_mfma_f32_16x16x32_bf16 v[40:43], v[180:183], v[216:219], v[40:43]
	v_mfma_f32_16x16x32_bf16 v[28:31], v[136:139], v[224:227], v[28:31]
	v_mfma_f32_16x16x32_bf16 v[24:27], v[180:183], v[224:227], v[24:27]
	v_mfma_f32_16x16x32_bf16 v[12:15], v[136:139], v[232:235], v[12:15]
	v_mfma_f32_16x16x32_bf16 v[8:11], v[180:183], v[232:235], v[8:11]
	v_mfma_f32_16x16x32_bf16 v[52:55], v[164:167], v[212:215], v[52:55]
	v_mfma_f32_16x16x32_bf16 v[48:51], v[184:187], v[212:215], v[48:51]
	v_mfma_f32_16x16x32_bf16 v[44:47], v[164:167], v[220:223], v[44:47]
	v_mfma_f32_16x16x32_bf16 v[40:43], v[184:187], v[220:223], v[40:43]
	v_mfma_f32_16x16x32_bf16 v[28:31], v[164:167], v[228:231], v[28:31]
	v_mfma_f32_16x16x32_bf16 v[24:27], v[184:187], v[228:231], v[24:27]
	v_mfma_f32_16x16x32_bf16 v[12:15], v[164:167], v[236:239], v[12:15]
	v_mfma_f32_16x16x32_bf16 v[8:11], v[184:187], v[236:239], v[8:11]
	v_mfma_f32_16x16x32_bf16 v[60:63], v[188:191], v[208:211], v[60:63]
	v_mfma_f32_16x16x32_bf16 v[56:59], v[200:203], v[208:211], v[56:59]
	v_mfma_f32_16x16x32_bf16 v[36:39], v[188:191], v[216:219], v[36:39]
	v_mfma_f32_16x16x32_bf16 v[32:35], v[200:203], v[216:219], v[32:35]
	v_mfma_f32_16x16x32_bf16 v[20:23], v[188:191], v[224:227], v[20:23]
	v_mfma_f32_16x16x32_bf16 v[16:19], v[200:203], v[224:227], v[16:19]
	v_mfma_f32_16x16x32_bf16 v[4:7], v[188:191], v[232:235], v[4:7]
	v_mfma_f32_16x16x32_bf16 v[0:3], v[200:203], v[232:235], v[0:3]
	v_mfma_f32_16x16x32_bf16 v[60:63], v[196:199], v[212:215], v[60:63]
	v_mfma_f32_16x16x32_bf16 v[56:59], v[204:207], v[212:215], v[56:59]
	v_mfma_f32_16x16x32_bf16 v[36:39], v[196:199], v[220:223], v[36:39]
	v_mfma_f32_16x16x32_bf16 v[32:35], v[204:207], v[220:223], v[32:35]
	v_mfma_f32_16x16x32_bf16 v[20:23], v[196:199], v[228:231], v[20:23]
	v_mfma_f32_16x16x32_bf16 v[16:19], v[204:207], v[228:231], v[16:19]
	v_mfma_f32_16x16x32_bf16 v[4:7], v[196:199], v[236:239], v[4:7]
	v_mfma_f32_16x16x32_bf16 v[0:3], v[204:207], v[236:239], v[0:3]
	s_barrier
	s_setprio 0
	s_add_i32 s64, s64, 2
	s_add_u32 s14, s14, 0x100
	s_addc_u32 s15, s15, 0
	s_add_u32 s58, s58, 0x100
	s_addc_u32 s59, s59, 0
	s_cmp_gt_u32 s64, 13
	s_cbranch_scc0 .LBB0_271

.LBB0_367:
	s_ashr_i32 s25, s24, 31
	s_lshl_b64 s[22:23], s[24:25], 19
	s_add_u32 s26, s84, s22
	s_addc_u32 s27, s85, s23
	s_and_b64 s[22:23], s[0:1], exec
	s_cselect_b32 s25, s27, s15
	s_cselect_b32 s50, s26, s14
	s_ashr_i32 s21, s20, 31
	s_lshl_b64 s[22:23], s[20:21], 19
	s_add_u32 s28, s30, s22
	s_addc_u32 s29, s31, s23
	s_and_b64 s[22:23], s[0:1], exec
	s_cselect_b32 s21, s29, s3
	s_cselect_b32 s51, s28, s2
	s_add_u32 s14, s14, 0x40080
	s_addc_u32 s15, s15, 0
	s_add_u32 s52, s2, 0x100
	s_addc_u32 s53, s3, 0
	s_mov_b32 s54, -2
	s_waitcnt vmcnt(0)
	ds_read_b128 v[158:161], v154
	ds_read_b128 v[162:165], v154 offset:1024
	ds_read_b128 v[166:169], v154 offset:2048
	ds_read_b128 v[182:185], v154 offset:3072
	ds_read_b128 v[186:189], v155
	ds_read_b128 v[190:193], v155 offset:1024
	ds_read_b128 v[196:199], v155 offset:2048
	ds_read_b128 v[200:203], v155 offset:3072
	s_add_u32 s2, s14, 0xfffc0080
	s_addc_u32 s3, s15, -1
	s_cmp_eq_u32 s54, 12
	s_cselect_b32 s23, s25, s3
	s_cselect_b32 s22, s50, s2
	s_cselect_b32 s3, s21, s53
	s_cselect_b32 s2, s51, s52
	v_lshl_add_u64 v[136:137], s[14:15], 0, v[128:129]
	s_add_i32 m0, s37, 0xc000
	ds_read_b128 v[204:207], v156
	ds_read_b128 v[208:211], v156 offset:1024
	ds_read_b128 v[212:215], v156 offset:2048
	ds_read_b128 v[216:219], v156 offset:3072
	ds_read_b128 v[220:223], v156 offset:4096
	ds_read_b128 v[224:227], v156 offset:5120
	ds_read_b128 v[228:231], v156 offset:6144
	ds_read_b128 v[232:235], v156 offset:7168
	global_load_lds_dwordx4 v[136:137], off
	v_lshl_add_u64 v[136:137], s[14:15], 0, v[130:131]
	s_add_i32 m0, s37, 0xe000
	s_nop 0
	global_load_lds_dwordx4 v[136:137], off
	s_waitcnt vmcnt(8)
	s_waitcnt lgkmcnt(0)
	s_barrier
	s_setprio 1
	v_mfma_f32_16x16x32_bf16 v[112:115], v[158:161], v[204:207], 0
	v_mfma_f32_16x16x32_bf16 v[108:111], v[166:169], v[204:207], 0
	v_mfma_f32_16x16x32_bf16 v[104:107], v[158:161], v[212:215], 0
	v_mfma_f32_16x16x32_bf16 v[100:103], v[166:169], v[212:215], 0
	v_mfma_f32_16x16x32_bf16 v[92:95], v[158:161], v[220:223], 0
	v_mfma_f32_16x16x32_bf16 v[84:87], v[166:169], v[220:223], 0
	v_mfma_f32_16x16x32_bf16 v[76:79], v[158:161], v[228:231], 0
	v_mfma_f32_16x16x32_bf16 v[68:71], v[166:169], v[228:231], 0
	v_mfma_f32_16x16x32_bf16 v[112:115], v[162:165], v[208:211], v[112:115]
	v_mfma_f32_16x16x32_bf16 v[108:111], v[182:185], v[208:211], v[108:111]
	v_mfma_f32_16x16x32_bf16 v[104:107], v[162:165], v[216:219], v[104:107]
	v_mfma_f32_16x16x32_bf16 v[100:103], v[182:185], v[216:219], v[100:103]
	v_mfma_f32_16x16x32_bf16 v[92:95], v[162:165], v[224:227], v[92:95]
	v_mfma_f32_16x16x32_bf16 v[84:87], v[182:185], v[224:227], v[84:87]
	v_mfma_f32_16x16x32_bf16 v[76:79], v[162:165], v[232:235], v[76:79]
	v_mfma_f32_16x16x32_bf16 v[68:71], v[182:185], v[232:235], v[68:71]
	v_mfma_f32_16x16x32_bf16 v[124:127], v[186:189], v[204:207], 0
	v_mfma_f32_16x16x32_bf16 v[120:123], v[196:199], v[204:207], 0
	v_mfma_f32_16x16x32_bf16 v[116:119], v[186:189], v[212:215], 0
	v_mfma_f32_16x16x32_bf16 v[96:99], v[196:199], v[212:215], 0
	v_mfma_f32_16x16x32_bf16 v[88:91], v[186:189], v[220:223], 0
	v_mfma_f32_16x16x32_bf16 v[80:83], v[196:199], v[220:223], 0
	v_mfma_f32_16x16x32_bf16 v[72:75], v[186:189], v[228:231], 0
	v_mfma_f32_16x16x32_bf16 v[64:67], v[196:199], v[228:231], 0
	v_mfma_f32_16x16x32_bf16 v[124:127], v[190:193], v[208:211], v[124:127]
	v_mfma_f32_16x16x32_bf16 v[120:123], v[200:203], v[208:211], v[120:123]
	v_mfma_f32_16x16x32_bf16 v[116:119], v[190:193], v[216:219], v[116:119]
	v_mfma_f32_16x16x32_bf16 v[96:99], v[200:203], v[216:219], v[96:99]
	v_mfma_f32_16x16x32_bf16 v[88:91], v[190:193], v[224:227], v[88:91]
	v_mfma_f32_16x16x32_bf16 v[80:83], v[200:203], v[224:227], v[80:83]
	v_mfma_f32_16x16x32_bf16 v[72:75], v[190:193], v[232:235], v[72:75]
	v_mfma_f32_16x16x32_bf16 v[64:67], v[200:203], v[232:235], v[64:67]
	s_barrier
	s_setprio 0
	s_add_i32 s55, s46, s34
	v_lshl_add_u64 v[136:137], s[2:3], 0, v[142:143]
	s_mov_b32 m0, s55
	ds_read_b128 v[204:207], v156 offset:16384
	ds_read_b128 v[208:211], v156 offset:17408
	ds_read_b128 v[212:215], v156 offset:18432
	ds_read_b128 v[216:219], v156 offset:19456
	ds_read_b128 v[220:223], v156 offset:20480
	ds_read_b128 v[224:227], v156 offset:21504
	ds_read_b128 v[228:231], v156 offset:22528
	ds_read_b128 v[232:235], v156 offset:23552
	global_load_lds_dwordx4 v[136:137], off
	s_add_i32 m0, s55, 0x2000
	s_add_u32 s56, s2, 0x40000
	v_lshl_add_u64 v[236:237], s[2:3], 0, v[146:147]
	s_addc_u32 s57, s3, 0
	s_add_i32 s55, s47, s34
	global_load_lds_dwordx4 v[236:237], off
	v_lshl_add_u64 v[238:239], s[56:57], 0, v[142:143]
	s_mov_b32 m0, s55
	v_lshl_add_u64 v[240:241], s[22:23], 0, v[144:145]
	global_load_lds_dwordx4 v[238:239], off
	v_lshl_add_u64 v[238:239], s[56:57], 0, v[146:147]
	s_add_i32 m0, s55, 0x2000
	s_nop 0
	global_load_lds_dwordx4 v[238:239], off
	v_lshl_add_u64 v[238:239], s[22:23], 0, v[140:141]
	s_mov_b32 m0, s37
	s_nop 0
	global_load_lds_dwordx4 v[238:239], off
	s_mov_b32 m0, s38
	s_nop 0
	global_load_lds_dwordx4 v[240:241], off
	s_waitcnt vmcnt(8)
	s_waitcnt lgkmcnt(0)
	s_barrier
	s_setprio 1
	v_mfma_f32_16x16x32_bf16 v[60:63], v[158:161], v[204:207], 0
	v_mfma_f32_16x16x32_bf16 v[52:55], v[166:169], v[204:207], 0
	v_mfma_f32_16x16x32_bf16 v[44:47], v[158:161], v[212:215], 0
	v_mfma_f32_16x16x32_bf16 v[36:39], v[166:169], v[212:215], 0
	v_mfma_f32_16x16x32_bf16 v[28:31], v[158:161], v[220:223], 0
	v_mfma_f32_16x16x32_bf16 v[20:23], v[166:169], v[220:223], 0
	v_mfma_f32_16x16x32_bf16 v[12:15], v[158:161], v[228:231], 0
	v_mfma_f32_16x16x32_bf16 v[4:7], v[166:169], v[228:231], 0
	v_mfma_f32_16x16x32_bf16 v[60:63], v[162:165], v[208:211], v[60:63]
	v_mfma_f32_16x16x32_bf16 v[52:55], v[182:185], v[208:211], v[52:55]
	v_mfma_f32_16x16x32_bf16 v[44:47], v[162:165], v[216:219], v[44:47]
	v_mfma_f32_16x16x32_bf16 v[36:39], v[182:185], v[216:219], v[36:39]
	v_mfma_f32_16x16x32_bf16 v[28:31], v[162:165], v[224:227], v[28:31]
	v_mfma_f32_16x16x32_bf16 v[20:23], v[182:185], v[224:227], v[20:23]
	v_mfma_f32_16x16x32_bf16 v[12:15], v[162:165], v[232:235], v[12:15]
	v_mfma_f32_16x16x32_bf16 v[4:7], v[182:185], v[232:235], v[4:7]
	v_mfma_f32_16x16x32_bf16 v[56:59], v[186:189], v[204:207], 0
	v_mfma_f32_16x16x32_bf16 v[48:51], v[196:199], v[204:207], 0
	v_mfma_f32_16x16x32_bf16 v[40:43], v[186:189], v[212:215], 0
	v_mfma_f32_16x16x32_bf16 v[32:35], v[196:199], v[212:215], 0
	v_mfma_f32_16x16x32_bf16 v[24:27], v[186:189], v[220:223], 0
	v_mfma_f32_16x16x32_bf16 v[16:19], v[196:199], v[220:223], 0
	v_mfma_f32_16x16x32_bf16 v[8:11], v[186:189], v[228:231], 0
	v_mfma_f32_16x16x32_bf16 v[0:3], v[196:199], v[228:231], 0
	v_mfma_f32_16x16x32_bf16 v[56:59], v[190:193], v[208:211], v[56:59]
	v_mfma_f32_16x16x32_bf16 v[48:51], v[200:203], v[208:211], v[48:51]
	v_mfma_f32_16x16x32_bf16 v[40:43], v[190:193], v[216:219], v[40:43]
	v_mfma_f32_16x16x32_bf16 v[32:35], v[200:203], v[216:219], v[32:35]
	v_mfma_f32_16x16x32_bf16 v[24:27], v[190:193], v[224:227], v[24:27]
	v_mfma_f32_16x16x32_bf16 v[16:19], v[200:203], v[224:227], v[16:19]
	v_mfma_f32_16x16x32_bf16 v[8:11], v[190:193], v[232:235], v[8:11]
	v_mfma_f32_16x16x32_bf16 v[0:3], v[200:203], v[232:235], v[0:3]
	s_barrier
	s_setprio 0
	s_add_i32 s55, 0, 0x18000
	s_add_i32 s56, 0, 0x1c000
	v_add_u32_e32 v182, s55, v139
	v_add_u32_e32 v200, s56, v139
	ds_read_b128 v[158:161], v182
	ds_read_b128 v[162:165], v182 offset:1024
	ds_read_b128 v[166:169], v182 offset:2048
	ds_read_b128 v[182:185], v182 offset:3072
	ds_read_b128 v[186:189], v200
	ds_read_b128 v[190:193], v200 offset:1024
	ds_read_b128 v[196:199], v200 offset:2048
	ds_read_b128 v[200:203], v200 offset:3072
	s_add_u32 s22, s22, 0x40000
	s_addc_u32 s23, s23, 0
	s_mov_b32 m0, s39
	v_lshl_add_u64 v[242:243], s[22:23], 0, v[140:141]
	ds_read_b128 v[204:207], v156 offset:32768
	ds_read_b128 v[208:211], v156 offset:33792
	ds_read_b128 v[212:215], v156 offset:34816
	ds_read_b128 v[216:219], v156 offset:35840
	ds_read_b128 v[220:223], v156 offset:36864
	ds_read_b128 v[224:227], v156 offset:37888
	ds_read_b128 v[228:231], v156 offset:38912
	ds_read_b128 v[232:235], v156 offset:39936
	global_load_lds_dwordx4 v[242:243], off
	v_lshl_add_u64 v[242:243], s[22:23], 0, v[144:145]
	s_mov_b32 m0, s40
	s_nop 0
	global_load_lds_dwordx4 v[242:243], off
	s_waitcnt vmcnt(8)
	s_waitcnt lgkmcnt(0)
	s_barrier
	s_setprio 1
	v_mfma_f32_16x16x32_bf16 v[112:115], v[158:161], v[204:207], v[112:115]
	v_mfma_f32_16x16x32_bf16 v[108:111], v[166:169], v[204:207], v[108:111]
	v_mfma_f32_16x16x32_bf16 v[104:107], v[158:161], v[212:215], v[104:107]
	v_mfma_f32_16x16x32_bf16 v[100:103], v[166:169], v[212:215], v[100:103]
	v_mfma_f32_16x16x32_bf16 v[92:95], v[158:161], v[220:223], v[92:95]
	v_mfma_f32_16x16x32_bf16 v[84:87], v[166:169], v[220:223], v[84:87]
	v_mfma_f32_16x16x32_bf16 v[76:79], v[158:161], v[228:231], v[76:79]
	v_mfma_f32_16x16x32_bf16 v[68:71], v[166:169], v[228:231], v[68:71]
	v_mfma_f32_16x16x32_bf16 v[112:115], v[162:165], v[208:211], v[112:115]
	v_mfma_f32_16x16x32_bf16 v[108:111], v[182:185], v[208:211], v[108:111]
	v_mfma_f32_16x16x32_bf16 v[104:107], v[162:165], v[216:219], v[104:107]
	v_mfma_f32_16x16x32_bf16 v[100:103], v[182:185], v[216:219], v[100:103]
	v_mfma_f32_16x16x32_bf16 v[92:95], v[162:165], v[224:227], v[92:95]
	v_mfma_f32_16x16x32_bf16 v[84:87], v[182:185], v[224:227], v[84:87]
	v_mfma_f32_16x16x32_bf16 v[76:79], v[162:165], v[232:235], v[76:79]
	v_mfma_f32_16x16x32_bf16 v[68:71], v[182:185], v[232:235], v[68:71]
	v_mfma_f32_16x16x32_bf16 v[124:127], v[186:189], v[204:207], v[124:127]
	v_mfma_f32_16x16x32_bf16 v[120:123], v[196:199], v[204:207], v[120:123]
	v_mfma_f32_16x16x32_bf16 v[116:119], v[186:189], v[212:215], v[116:119]
	v_mfma_f32_16x16x32_bf16 v[96:99], v[196:199], v[212:215], v[96:99]
	v_mfma_f32_16x16x32_bf16 v[88:91], v[186:189], v[220:223], v[88:91]
	v_mfma_f32_16x16x32_bf16 v[80:83], v[196:199], v[220:223], v[80:83]
	v_mfma_f32_16x16x32_bf16 v[72:75], v[186:189], v[228:231], v[72:75]
	v_mfma_f32_16x16x32_bf16 v[64:67], v[196:199], v[228:231], v[64:67]
	v_mfma_f32_16x16x32_bf16 v[124:127], v[190:193], v[208:211], v[124:127]
	v_mfma_f32_16x16x32_bf16 v[120:123], v[200:203], v[208:211], v[120:123]
	v_mfma_f32_16x16x32_bf16 v[116:119], v[190:193], v[216:219], v[116:119]
	v_mfma_f32_16x16x32_bf16 v[96:99], v[200:203], v[216:219], v[96:99]
	v_mfma_f32_16x16x32_bf16 v[88:91], v[190:193], v[224:227], v[88:91]
	v_mfma_f32_16x16x32_bf16 v[80:83], v[200:203], v[224:227], v[80:83]
	v_mfma_f32_16x16x32_bf16 v[72:75], v[190:193], v[232:235], v[72:75]
	v_mfma_f32_16x16x32_bf16 v[64:67], v[200:203], v[232:235], v[64:67]
	s_barrier
	s_setprio 0
	s_add_i32 s22, s55, s34
	v_lshl_add_u64 v[136:137], v[136:137], 0, s[8:9]
	s_mov_b32 m0, s22
	ds_read_b128 v[204:207], v156 offset:49152
	ds_read_b128 v[208:211], v156 offset:50176
	ds_read_b128 v[212:215], v156 offset:51200
	ds_read_b128 v[216:219], v156 offset:52224
	ds_read_b128 v[220:223], v156 offset:53248
	ds_read_b128 v[224:227], v156 offset:54272
	ds_read_b128 v[228:231], v156 offset:55296
	ds_read_b128 v[232:235], v156 offset:56320
	global_load_lds_dwordx4 v[136:137], off
	s_add_i32 m0, s22, 0x2000
	s_add_u32 s2, s2, 0x40080
	v_lshl_add_u64 v[136:137], v[236:237], 0, s[8:9]
	s_addc_u32 s3, s3, 0
	s_add_i32 s22, s56, s34
	global_load_lds_dwordx4 v[136:137], off
	v_lshl_add_u64 v[136:137], s[2:3], 0, v[142:143]
	s_mov_b32 m0, s22
	s_nop 0
	global_load_lds_dwordx4 v[136:137], off
	v_lshl_add_u64 v[136:137], s[2:3], 0, v[146:147]
	s_add_i32 m0, s22, 0x2000
	s_nop 0
	global_load_lds_dwordx4 v[136:137], off
	v_lshl_add_u64 v[136:137], v[238:239], 0, s[8:9]
	s_mov_b32 m0, s42
	s_nop 0
	global_load_lds_dwordx4 v[136:137], off
	v_lshl_add_u64 v[136:137], v[240:241], 0, s[8:9]
	s_mov_b32 m0, s43
	s_nop 0
	global_load_lds_dwordx4 v[136:137], off
	s_waitcnt vmcnt(8)
	s_waitcnt lgkmcnt(0)
	s_barrier
	s_setprio 1
	v_mfma_f32_16x16x32_bf16 v[60:63], v[158:161], v[204:207], v[60:63]
	v_mfma_f32_16x16x32_bf16 v[52:55], v[166:169], v[204:207], v[52:55]
	v_mfma_f32_16x16x32_bf16 v[44:47], v[158:161], v[212:215], v[44:47]
	v_mfma_f32_16x16x32_bf16 v[36:39], v[166:169], v[212:215], v[36:39]
	v_mfma_f32_16x16x32_bf16 v[28:31], v[158:161], v[220:223], v[28:31]
	v_mfma_f32_16x16x32_bf16 v[20:23], v[166:169], v[220:223], v[20:23]
	v_mfma_f32_16x16x32_bf16 v[12:15], v[158:161], v[228:231], v[12:15]
	v_mfma_f32_16x16x32_bf16 v[4:7], v[166:169], v[228:231], v[4:7]
	v_mfma_f32_16x16x32_bf16 v[60:63], v[162:165], v[208:211], v[60:63]
	v_mfma_f32_16x16x32_bf16 v[52:55], v[182:185], v[208:211], v[52:55]
	v_mfma_f32_16x16x32_bf16 v[44:47], v[162:165], v[216:219], v[44:47]
	v_mfma_f32_16x16x32_bf16 v[36:39], v[182:185], v[216:219], v[36:39]
	v_mfma_f32_16x16x32_bf16 v[28:31], v[162:165], v[224:227], v[28:31]
	v_mfma_f32_16x16x32_bf16 v[20:23], v[182:185], v[224:227], v[20:23]
	v_mfma_f32_16x16x32_bf16 v[12:15], v[162:165], v[232:235], v[12:15]
	v_mfma_f32_16x16x32_bf16 v[4:7], v[182:185], v[232:235], v[4:7]
	v_mfma_f32_16x16x32_bf16 v[56:59], v[186:189], v[204:207], v[56:59]
	v_mfma_f32_16x16x32_bf16 v[48:51], v[196:199], v[204:207], v[48:51]
	v_mfma_f32_16x16x32_bf16 v[40:43], v[186:189], v[212:215], v[40:43]
	v_mfma_f32_16x16x32_bf16 v[32:35], v[196:199], v[212:215], v[32:35]
	v_mfma_f32_16x16x32_bf16 v[24:27], v[186:189], v[220:223], v[24:27]
	v_mfma_f32_16x16x32_bf16 v[16:19], v[196:199], v[220:223], v[16:19]
	v_mfma_f32_16x16x32_bf16 v[8:11], v[186:189], v[228:231], v[8:11]
	v_mfma_f32_16x16x32_bf16 v[0:3], v[196:199], v[228:231], v[0:3]
	v_mfma_f32_16x16x32_bf16 v[56:59], v[190:193], v[208:211], v[56:59]
	v_mfma_f32_16x16x32_bf16 v[48:51], v[200:203], v[208:211], v[48:51]
	v_mfma_f32_16x16x32_bf16 v[40:43], v[190:193], v[216:219], v[40:43]
	v_mfma_f32_16x16x32_bf16 v[32:35], v[200:203], v[216:219], v[32:35]
	v_mfma_f32_16x16x32_bf16 v[24:27], v[190:193], v[224:227], v[24:27]
	v_mfma_f32_16x16x32_bf16 v[16:19], v[200:203], v[224:227], v[16:19]
	v_mfma_f32_16x16x32_bf16 v[8:11], v[190:193], v[232:235], v[8:11]
	v_mfma_f32_16x16x32_bf16 v[0:3], v[200:203], v[232:235], v[0:3]
	s_barrier
	s_setprio 0
	s_add_i32 s54, s54, 2
	s_add_u32 s14, s14, 0x100
	s_addc_u32 s15, s15, 0
	s_add_u32 s52, s52, 0x100
	s_addc_u32 s53, s53, 0
	s_cmp_gt_u32 s54, 13
	s_cbranch_scc1 .Lgemm_kdone_1
.LBB0_368:
	ds_read_b128 v[158:161], v154
	ds_read_b128 v[162:165], v154 offset:1024
	ds_read_b128 v[166:169], v154 offset:2048
	ds_read_b128 v[182:185], v154 offset:3072
	ds_read_b128 v[186:189], v155
	ds_read_b128 v[190:193], v155 offset:1024
	ds_read_b128 v[196:199], v155 offset:2048
	ds_read_b128 v[200:203], v155 offset:3072
	s_add_u32 s2, s14, 0xfffc0080
	s_addc_u32 s3, s15, -1
	s_cmp_eq_u32 s54, 12
	s_cselect_b32 s23, s25, s3
	s_cselect_b32 s22, s50, s2
	s_cselect_b32 s3, s21, s53
	s_cselect_b32 s2, s51, s52
	v_lshl_add_u64 v[136:137], s[14:15], 0, v[128:129]
	s_add_i32 m0, s37, 0xc000
	ds_read_b128 v[204:207], v156
	ds_read_b128 v[208:211], v156 offset:1024
	ds_read_b128 v[212:215], v156 offset:2048
	ds_read_b128 v[216:219], v156 offset:3072
	ds_read_b128 v[220:223], v156 offset:4096
	ds_read_b128 v[224:227], v156 offset:5120
	ds_read_b128 v[228:231], v156 offset:6144
	ds_read_b128 v[232:235], v156 offset:7168
	global_load_lds_dwordx4 v[136:137], off
	v_lshl_add_u64 v[136:137], s[14:15], 0, v[130:131]
	s_add_i32 m0, s37, 0xe000
	s_nop 0
	global_load_lds_dwordx4 v[136:137], off
	s_waitcnt vmcnt(8)
	s_waitcnt lgkmcnt(0)
	s_barrier
	s_setprio 1
	v_mfma_f32_16x16x32_bf16 v[112:115], v[158:161], v[204:207], v[112:115]
	v_mfma_f32_16x16x32_bf16 v[108:111], v[166:169], v[204:207], v[108:111]
	v_mfma_f32_16x16x32_bf16 v[104:107], v[158:161], v[212:215], v[104:107]
	v_mfma_f32_16x16x32_bf16 v[100:103], v[166:169], v[212:215], v[100:103]
	v_mfma_f32_16x16x32_bf16 v[92:95], v[158:161], v[220:223], v[92:95]
	v_mfma_f32_16x16x32_bf16 v[84:87], v[166:169], v[220:223], v[84:87]
	v_mfma_f32_16x16x32_bf16 v[76:79], v[158:161], v[228:231], v[76:79]
	v_mfma_f32_16x16x32_bf16 v[68:71], v[166:169], v[228:231], v[68:71]
	v_mfma_f32_16x16x32_bf16 v[112:115], v[162:165], v[208:211], v[112:115]
	v_mfma_f32_16x16x32_bf16 v[108:111], v[182:185], v[208:211], v[108:111]
	v_mfma_f32_16x16x32_bf16 v[104:107], v[162:165], v[216:219], v[104:107]
	v_mfma_f32_16x16x32_bf16 v[100:103], v[182:185], v[216:219], v[100:103]
	v_mfma_f32_16x16x32_bf16 v[92:95], v[162:165], v[224:227], v[92:95]
	v_mfma_f32_16x16x32_bf16 v[84:87], v[182:185], v[224:227], v[84:87]
	v_mfma_f32_16x16x32_bf16 v[76:79], v[162:165], v[232:235], v[76:79]
	v_mfma_f32_16x16x32_bf16 v[68:71], v[182:185], v[232:235], v[68:71]
	v_mfma_f32_16x16x32_bf16 v[124:127], v[186:189], v[204:207], v[124:127]
	v_mfma_f32_16x16x32_bf16 v[120:123], v[196:199], v[204:207], v[120:123]
	v_mfma_f32_16x16x32_bf16 v[116:119], v[186:189], v[212:215], v[116:119]
	v_mfma_f32_16x16x32_bf16 v[96:99], v[196:199], v[212:215], v[96:99]
	v_mfma_f32_16x16x32_bf16 v[88:91], v[186:189], v[220:223], v[88:91]
	v_mfma_f32_16x16x32_bf16 v[80:83], v[196:199], v[220:223], v[80:83]
	v_mfma_f32_16x16x32_bf16 v[72:75], v[186:189], v[228:231], v[72:75]
	v_mfma_f32_16x16x32_bf16 v[64:67], v[196:199], v[228:231], v[64:67]
	v_mfma_f32_16x16x32_bf16 v[124:127], v[190:193], v[208:211], v[124:127]
	v_mfma_f32_16x16x32_bf16 v[120:123], v[200:203], v[208:211], v[120:123]
	v_mfma_f32_16x16x32_bf16 v[116:119], v[190:193], v[216:219], v[116:119]
	v_mfma_f32_16x16x32_bf16 v[96:99], v[200:203], v[216:219], v[96:99]
	v_mfma_f32_16x16x32_bf16 v[88:91], v[190:193], v[224:227], v[88:91]
	v_mfma_f32_16x16x32_bf16 v[80:83], v[200:203], v[224:227], v[80:83]
	v_mfma_f32_16x16x32_bf16 v[72:75], v[190:193], v[232:235], v[72:75]
	v_mfma_f32_16x16x32_bf16 v[64:67], v[200:203], v[232:235], v[64:67]
	s_barrier
	s_setprio 0
	s_add_i32 s55, s46, s34
	v_lshl_add_u64 v[136:137], s[2:3], 0, v[142:143]
	s_mov_b32 m0, s55
	ds_read_b128 v[204:207], v156 offset:16384
	ds_read_b128 v[208:211], v156 offset:17408
	ds_read_b128 v[212:215], v156 offset:18432
	ds_read_b128 v[216:219], v156 offset:19456
	ds_read_b128 v[220:223], v156 offset:20480
	ds_read_b128 v[224:227], v156 offset:21504
	ds_read_b128 v[228:231], v156 offset:22528
	ds_read_b128 v[232:235], v156 offset:23552
	global_load_lds_dwordx4 v[136:137], off
	s_add_i32 m0, s55, 0x2000
	s_add_u32 s56, s2, 0x40000
	v_lshl_add_u64 v[236:237], s[2:3], 0, v[146:147]
	s_addc_u32 s57, s3, 0
	s_add_i32 s55, s47, s34
	global_load_lds_dwordx4 v[236:237], off
	v_lshl_add_u64 v[238:239], s[56:57], 0, v[142:143]
	s_mov_b32 m0, s55
	v_lshl_add_u64 v[240:241], s[22:23], 0, v[144:145]
	global_load_lds_dwordx4 v[238:239], off
	v_lshl_add_u64 v[238:239], s[56:57], 0, v[146:147]
	s_add_i32 m0, s55, 0x2000
	s_nop 0
	global_load_lds_dwordx4 v[238:239], off
	v_lshl_add_u64 v[238:239], s[22:23], 0, v[140:141]
	s_mov_b32 m0, s37
	s_nop 0
	global_load_lds_dwordx4 v[238:239], off
	s_mov_b32 m0, s38
	s_nop 0
	global_load_lds_dwordx4 v[240:241], off
	s_waitcnt vmcnt(8)
	s_waitcnt lgkmcnt(0)
	s_barrier
	s_setprio 1
	v_mfma_f32_16x16x32_bf16 v[60:63], v[158:161], v[204:207], v[60:63]
	v_mfma_f32_16x16x32_bf16 v[52:55], v[166:169], v[204:207], v[52:55]
	v_mfma_f32_16x16x32_bf16 v[44:47], v[158:161], v[212:215], v[44:47]
	v_mfma_f32_16x16x32_bf16 v[36:39], v[166:169], v[212:215], v[36:39]
	v_mfma_f32_16x16x32_bf16 v[28:31], v[158:161], v[220:223], v[28:31]
	v_mfma_f32_16x16x32_bf16 v[20:23], v[166:169], v[220:223], v[20:23]
	v_mfma_f32_16x16x32_bf16 v[12:15], v[158:161], v[228:231], v[12:15]
	v_mfma_f32_16x16x32_bf16 v[4:7], v[166:169], v[228:231], v[4:7]
	v_mfma_f32_16x16x32_bf16 v[60:63], v[162:165], v[208:211], v[60:63]
	v_mfma_f32_16x16x32_bf16 v[52:55], v[182:185], v[208:211], v[52:55]
	v_mfma_f32_16x16x32_bf16 v[44:47], v[162:165], v[216:219], v[44:47]
	v_mfma_f32_16x16x32_bf16 v[36:39], v[182:185], v[216:219], v[36:39]
	v_mfma_f32_16x16x32_bf16 v[28:31], v[162:165], v[224:227], v[28:31]
	v_mfma_f32_16x16x32_bf16 v[20:23], v[182:185], v[224:227], v[20:23]
	v_mfma_f32_16x16x32_bf16 v[12:15], v[162:165], v[232:235], v[12:15]
	v_mfma_f32_16x16x32_bf16 v[4:7], v[182:185], v[232:235], v[4:7]
	v_mfma_f32_16x16x32_bf16 v[56:59], v[186:189], v[204:207], v[56:59]
	v_mfma_f32_16x16x32_bf16 v[48:51], v[196:199], v[204:207], v[48:51]
	v_mfma_f32_16x16x32_bf16 v[40:43], v[186:189], v[212:215], v[40:43]
	v_mfma_f32_16x16x32_bf16 v[32:35], v[196:199], v[212:215], v[32:35]
	v_mfma_f32_16x16x32_bf16 v[24:27], v[186:189], v[220:223], v[24:27]
	v_mfma_f32_16x16x32_bf16 v[16:19], v[196:199], v[220:223], v[16:19]
	v_mfma_f32_16x16x32_bf16 v[8:11], v[186:189], v[228:231], v[8:11]
	v_mfma_f32_16x16x32_bf16 v[0:3], v[196:199], v[228:231], v[0:3]
	v_mfma_f32_16x16x32_bf16 v[56:59], v[190:193], v[208:211], v[56:59]
	v_mfma_f32_16x16x32_bf16 v[48:51], v[200:203], v[208:211], v[48:51]
	v_mfma_f32_16x16x32_bf16 v[40:43], v[190:193], v[216:219], v[40:43]
	v_mfma_f32_16x16x32_bf16 v[32:35], v[200:203], v[216:219], v[32:35]
	v_mfma_f32_16x16x32_bf16 v[24:27], v[190:193], v[224:227], v[24:27]
	v_mfma_f32_16x16x32_bf16 v[16:19], v[200:203], v[224:227], v[16:19]
	v_mfma_f32_16x16x32_bf16 v[8:11], v[190:193], v[232:235], v[8:11]
	v_mfma_f32_16x16x32_bf16 v[0:3], v[200:203], v[232:235], v[0:3]
	s_barrier
	s_setprio 0
	s_add_i32 s55, 0, 0x18000
	s_add_i32 s56, 0, 0x1c000
	v_add_u32_e32 v182, s55, v139
	v_add_u32_e32 v200, s56, v139
	ds_read_b128 v[158:161], v182
	ds_read_b128 v[162:165], v182 offset:1024
	ds_read_b128 v[166:169], v182 offset:2048
	ds_read_b128 v[182:185], v182 offset:3072
	ds_read_b128 v[186:189], v200
	ds_read_b128 v[190:193], v200 offset:1024
	ds_read_b128 v[196:199], v200 offset:2048
	ds_read_b128 v[200:203], v200 offset:3072
	s_add_u32 s22, s22, 0x40000
	s_addc_u32 s23, s23, 0
	s_mov_b32 m0, s39
	v_lshl_add_u64 v[242:243], s[22:23], 0, v[140:141]
	ds_read_b128 v[204:207], v156 offset:32768
	ds_read_b128 v[208:211], v156 offset:33792
	ds_read_b128 v[212:215], v156 offset:34816
	ds_read_b128 v[216:219], v156 offset:35840
	ds_read_b128 v[220:223], v156 offset:36864
	ds_read_b128 v[224:227], v156 offset:37888
	ds_read_b128 v[228:231], v156 offset:38912
	ds_read_b128 v[232:235], v156 offset:39936
	global_load_lds_dwordx4 v[242:243], off
	v_lshl_add_u64 v[242:243], s[22:23], 0, v[144:145]
	s_mov_b32 m0, s40
	s_nop 0
	global_load_lds_dwordx4 v[242:243], off
	s_waitcnt vmcnt(8)
	s_waitcnt lgkmcnt(0)
	s_barrier
	s_setprio 1
	v_mfma_f32_16x16x32_bf16 v[112:115], v[158:161], v[204:207], v[112:115]
	v_mfma_f32_16x16x32_bf16 v[108:111], v[166:169], v[204:207], v[108:111]
	v_mfma_f32_16x16x32_bf16 v[104:107], v[158:161], v[212:215], v[104:107]
	v_mfma_f32_16x16x32_bf16 v[100:103], v[166:169], v[212:215], v[100:103]
	v_mfma_f32_16x16x32_bf16 v[92:95], v[158:161], v[220:223], v[92:95]
	v_mfma_f32_16x16x32_bf16 v[84:87], v[166:169], v[220:223], v[84:87]
	v_mfma_f32_16x16x32_bf16 v[76:79], v[158:161], v[228:231], v[76:79]
	v_mfma_f32_16x16x32_bf16 v[68:71], v[166:169], v[228:231], v[68:71]
	v_mfma_f32_16x16x32_bf16 v[112:115], v[162:165], v[208:211], v[112:115]
	v_mfma_f32_16x16x32_bf16 v[108:111], v[182:185], v[208:211], v[108:111]
	v_mfma_f32_16x16x32_bf16 v[104:107], v[162:165], v[216:219], v[104:107]
	v_mfma_f32_16x16x32_bf16 v[100:103], v[182:185], v[216:219], v[100:103]
	v_mfma_f32_16x16x32_bf16 v[92:95], v[162:165], v[224:227], v[92:95]
	v_mfma_f32_16x16x32_bf16 v[84:87], v[182:185], v[224:227], v[84:87]
	v_mfma_f32_16x16x32_bf16 v[76:79], v[162:165], v[232:235], v[76:79]
	v_mfma_f32_16x16x32_bf16 v[68:71], v[182:185], v[232:235], v[68:71]
	v_mfma_f32_16x16x32_bf16 v[124:127], v[186:189], v[204:207], v[124:127]
	v_mfma_f32_16x16x32_bf16 v[120:123], v[196:199], v[204:207], v[120:123]
	v_mfma_f32_16x16x32_bf16 v[116:119], v[186:189], v[212:215], v[116:119]
	v_mfma_f32_16x16x32_bf16 v[96:99], v[196:199], v[212:215], v[96:99]
	v_mfma_f32_16x16x32_bf16 v[88:91], v[186:189], v[220:223], v[88:91]
	v_mfma_f32_16x16x32_bf16 v[80:83], v[196:199], v[220:223], v[80:83]
	v_mfma_f32_16x16x32_bf16 v[72:75], v[186:189], v[228:231], v[72:75]
	v_mfma_f32_16x16x32_bf16 v[64:67], v[196:199], v[228:231], v[64:67]
	v_mfma_f32_16x16x32_bf16 v[124:127], v[190:193], v[208:211], v[124:127]
	v_mfma_f32_16x16x32_bf16 v[120:123], v[200:203], v[208:211], v[120:123]
	v_mfma_f32_16x16x32_bf16 v[116:119], v[190:193], v[216:219], v[116:119]
	v_mfma_f32_16x16x32_bf16 v[96:99], v[200:203], v[216:219], v[96:99]
	v_mfma_f32_16x16x32_bf16 v[88:91], v[190:193], v[224:227], v[88:91]
	v_mfma_f32_16x16x32_bf16 v[80:83], v[200:203], v[224:227], v[80:83]
	v_mfma_f32_16x16x32_bf16 v[72:75], v[190:193], v[232:235], v[72:75]
	v_mfma_f32_16x16x32_bf16 v[64:67], v[200:203], v[232:235], v[64:67]
	s_barrier
	s_setprio 0
	s_add_i32 s22, s55, s34
	v_lshl_add_u64 v[136:137], v[136:137], 0, s[8:9]
	s_mov_b32 m0, s22
	ds_read_b128 v[204:207], v156 offset:49152
	ds_read_b128 v[208:211], v156 offset:50176
	ds_read_b128 v[212:215], v156 offset:51200
	ds_read_b128 v[216:219], v156 offset:52224
	ds_read_b128 v[220:223], v156 offset:53248
	ds_read_b128 v[224:227], v156 offset:54272
	ds_read_b128 v[228:231], v156 offset:55296
	ds_read_b128 v[232:235], v156 offset:56320
	global_load_lds_dwordx4 v[136:137], off
	s_add_i32 m0, s22, 0x2000
	s_add_u32 s2, s2, 0x40080
	v_lshl_add_u64 v[136:137], v[236:237], 0, s[8:9]
	s_addc_u32 s3, s3, 0
	s_add_i32 s22, s56, s34
	global_load_lds_dwordx4 v[136:137], off
	v_lshl_add_u64 v[136:137], s[2:3], 0, v[142:143]
	s_mov_b32 m0, s22
	s_nop 0
	global_load_lds_dwordx4 v[136:137], off
	v_lshl_add_u64 v[136:137], s[2:3], 0, v[146:147]
	s_add_i32 m0, s22, 0x2000
	s_nop 0
	global_load_lds_dwordx4 v[136:137], off
	v_lshl_add_u64 v[136:137], v[238:239], 0, s[8:9]
	s_mov_b32 m0, s42
	s_nop 0
	global_load_lds_dwordx4 v[136:137], off
	v_lshl_add_u64 v[136:137], v[240:241], 0, s[8:9]
	s_mov_b32 m0, s43
	s_nop 0
	global_load_lds_dwordx4 v[136:137], off
	s_waitcnt vmcnt(8)
	s_waitcnt lgkmcnt(0)
	s_barrier
	s_setprio 1
	v_mfma_f32_16x16x32_bf16 v[60:63], v[158:161], v[204:207], v[60:63]
	v_mfma_f32_16x16x32_bf16 v[52:55], v[166:169], v[204:207], v[52:55]
	v_mfma_f32_16x16x32_bf16 v[44:47], v[158:161], v[212:215], v[44:47]
	v_mfma_f32_16x16x32_bf16 v[36:39], v[166:169], v[212:215], v[36:39]
	v_mfma_f32_16x16x32_bf16 v[28:31], v[158:161], v[220:223], v[28:31]
	v_mfma_f32_16x16x32_bf16 v[20:23], v[166:169], v[220:223], v[20:23]
	v_mfma_f32_16x16x32_bf16 v[12:15], v[158:161], v[228:231], v[12:15]
	v_mfma_f32_16x16x32_bf16 v[4:7], v[166:169], v[228:231], v[4:7]
	v_mfma_f32_16x16x32_bf16 v[60:63], v[162:165], v[208:211], v[60:63]
	v_mfma_f32_16x16x32_bf16 v[52:55], v[182:185], v[208:211], v[52:55]
	v_mfma_f32_16x16x32_bf16 v[44:47], v[162:165], v[216:219], v[44:47]
	v_mfma_f32_16x16x32_bf16 v[36:39], v[182:185], v[216:219], v[36:39]
	v_mfma_f32_16x16x32_bf16 v[28:31], v[162:165], v[224:227], v[28:31]
	v_mfma_f32_16x16x32_bf16 v[20:23], v[182:185], v[224:227], v[20:23]
	v_mfma_f32_16x16x32_bf16 v[12:15], v[162:165], v[232:235], v[12:15]
	v_mfma_f32_16x16x32_bf16 v[4:7], v[182:185], v[232:235], v[4:7]
	v_mfma_f32_16x16x32_bf16 v[56:59], v[186:189], v[204:207], v[56:59]
	v_mfma_f32_16x16x32_bf16 v[48:51], v[196:199], v[204:207], v[48:51]
	v_mfma_f32_16x16x32_bf16 v[40:43], v[186:189], v[212:215], v[40:43]
	v_mfma_f32_16x16x32_bf16 v[32:35], v[196:199], v[212:215], v[32:35]
	v_mfma_f32_16x16x32_bf16 v[24:27], v[186:189], v[220:223], v[24:27]
	v_mfma_f32_16x16x32_bf16 v[16:19], v[196:199], v[220:223], v[16:19]
	v_mfma_f32_16x16x32_bf16 v[8:11], v[186:189], v[228:231], v[8:11]
	v_mfma_f32_16x16x32_bf16 v[0:3], v[196:199], v[228:231], v[0:3]
	v_mfma_f32_16x16x32_bf16 v[56:59], v[190:193], v[208:211], v[56:59]
	v_mfma_f32_16x16x32_bf16 v[48:51], v[200:203], v[208:211], v[48:51]
	v_mfma_f32_16x16x32_bf16 v[40:43], v[190:193], v[216:219], v[40:43]
	v_mfma_f32_16x16x32_bf16 v[32:35], v[200:203], v[216:219], v[32:35]
	v_mfma_f32_16x16x32_bf16 v[24:27], v[190:193], v[224:227], v[24:27]
	v_mfma_f32_16x16x32_bf16 v[16:19], v[200:203], v[224:227], v[16:19]
	v_mfma_f32_16x16x32_bf16 v[8:11], v[190:193], v[232:235], v[8:11]
	v_mfma_f32_16x16x32_bf16 v[0:3], v[200:203], v[232:235], v[0:3]
	s_barrier
	s_setprio 0
	s_add_i32 s54, s54, 2
	s_add_u32 s14, s14, 0x100
	s_addc_u32 s15, s15, 0
	s_add_u32 s52, s52, 0x100
	s_addc_u32 s53, s53, 0
	s_cmp_gt_u32 s54, 13
	s_cbranch_scc0 .LBB0_368

.LBB0_454:
	s_add_u32 s14, s14, 0xb0080
	s_addc_u32 s15, s15, 0
	s_add_u32 s65, s2, 0x100
	s_addc_u32 s66, s3, 0
	s_mov_b32 s67, -2
	s_waitcnt lgkmcnt(0)
	s_waitcnt vmcnt(0)
	ds_read_b128 v[128:131], v147
	ds_read_b128 v[132:135], v147 offset:1024
	ds_read_b128 v[136:139], v147 offset:2048
	ds_read_b128 v[164:167], v147 offset:3072
	ds_read_b128 v[188:191], v184
	ds_read_b128 v[196:199], v184 offset:1024
	ds_read_b128 v[200:203], v184 offset:2048
	ds_read_b128 v[204:207], v184 offset:3072
	s_add_u32 s2, s14, 0xfff50080
	s_addc_u32 s3, s15, -1
	s_cmp_eq_u32 s67, 40
	s_cselect_b32 s23, s1, s3
	s_cselect_b32 s22, s0, s2
	s_cselect_b32 s3, s31, s66
	s_cselect_b32 s2, s30, s65
	v_lshl_add_u64 v[168:169], s[14:15], 0, v[156:157]
	s_add_i32 m0, s37, 0xc000
	ds_read_b128 v[208:211], v185
	ds_read_b128 v[212:215], v185 offset:1024
	ds_read_b128 v[216:219], v185 offset:2048
	ds_read_b128 v[220:223], v185 offset:3072
	ds_read_b128 v[224:227], v185 offset:4096
	ds_read_b128 v[228:231], v185 offset:5120
	ds_read_b128 v[232:235], v185 offset:6144
	ds_read_b128 v[236:239], v185 offset:7168
	global_load_lds_dwordx4 v[168:169], off
	v_lshl_add_u64 v[168:169], s[14:15], 0, v[158:159]
	s_add_i32 m0, s37, 0xe000
	s_nop 0
	global_load_lds_dwordx4 v[168:169], off
	s_waitcnt vmcnt(8)
	s_waitcnt lgkmcnt(0)
	s_barrier
	s_setprio 1
	v_mfma_f32_16x16x32_bf16 v[124:127], v[128:131], v[208:211], 0
	v_mfma_f32_16x16x32_bf16 v[120:123], v[136:139], v[208:211], 0
	v_mfma_f32_16x16x32_bf16 v[108:111], v[128:131], v[216:219], 0
	v_mfma_f32_16x16x32_bf16 v[104:107], v[136:139], v[216:219], 0
	v_mfma_f32_16x16x32_bf16 v[92:95], v[128:131], v[224:227], 0
	v_mfma_f32_16x16x32_bf16 v[88:91], v[136:139], v[224:227], 0
	v_mfma_f32_16x16x32_bf16 v[76:79], v[128:131], v[232:235], 0
	v_mfma_f32_16x16x32_bf16 v[72:75], v[136:139], v[232:235], 0
	v_mfma_f32_16x16x32_bf16 v[124:127], v[132:135], v[212:215], v[124:127]
	v_mfma_f32_16x16x32_bf16 v[120:123], v[164:167], v[212:215], v[120:123]
	v_mfma_f32_16x16x32_bf16 v[108:111], v[132:135], v[220:223], v[108:111]
	v_mfma_f32_16x16x32_bf16 v[104:107], v[164:167], v[220:223], v[104:107]
	v_mfma_f32_16x16x32_bf16 v[92:95], v[132:135], v[228:231], v[92:95]
	v_mfma_f32_16x16x32_bf16 v[88:91], v[164:167], v[228:231], v[88:91]
	v_mfma_f32_16x16x32_bf16 v[76:79], v[132:135], v[236:239], v[76:79]
	v_mfma_f32_16x16x32_bf16 v[72:75], v[164:167], v[236:239], v[72:75]
	v_mfma_f32_16x16x32_bf16 v[116:119], v[188:191], v[208:211], 0
	v_mfma_f32_16x16x32_bf16 v[112:115], v[200:203], v[208:211], 0
	v_mfma_f32_16x16x32_bf16 v[100:103], v[188:191], v[216:219], 0
	v_mfma_f32_16x16x32_bf16 v[96:99], v[200:203], v[216:219], 0
	v_mfma_f32_16x16x32_bf16 v[84:87], v[188:191], v[224:227], 0
	v_mfma_f32_16x16x32_bf16 v[80:83], v[200:203], v[224:227], 0
	v_mfma_f32_16x16x32_bf16 v[68:71], v[188:191], v[232:235], 0
	v_mfma_f32_16x16x32_bf16 v[64:67], v[200:203], v[232:235], 0
	v_mfma_f32_16x16x32_bf16 v[116:119], v[196:199], v[212:215], v[116:119]
	v_mfma_f32_16x16x32_bf16 v[112:115], v[204:207], v[212:215], v[112:115]
	v_mfma_f32_16x16x32_bf16 v[100:103], v[196:199], v[220:223], v[100:103]
	v_mfma_f32_16x16x32_bf16 v[96:99], v[204:207], v[220:223], v[96:99]
	v_mfma_f32_16x16x32_bf16 v[84:87], v[196:199], v[228:231], v[84:87]
	v_mfma_f32_16x16x32_bf16 v[80:83], v[204:207], v[228:231], v[80:83]
	v_mfma_f32_16x16x32_bf16 v[68:71], v[196:199], v[236:239], v[68:71]
	v_mfma_f32_16x16x32_bf16 v[64:67], v[204:207], v[236:239], v[64:67]
	s_barrier
	s_setprio 0
	s_add_i32 s68, s51, s36
	v_lshl_add_u64 v[168:169], s[2:3], 0, v[150:151]
	s_mov_b32 m0, s68
	ds_read_b128 v[208:211], v185 offset:16384
	ds_read_b128 v[212:215], v185 offset:17408
	ds_read_b128 v[216:219], v185 offset:18432
	ds_read_b128 v[220:223], v185 offset:19456
	ds_read_b128 v[224:227], v185 offset:20480
	ds_read_b128 v[228:231], v185 offset:21504
	ds_read_b128 v[232:235], v185 offset:22528
	ds_read_b128 v[236:239], v185 offset:23552
	global_load_lds_dwordx4 v[168:169], off
	s_add_i32 m0, s68, 0x2000
	s_add_u32 s68, s2, 0xb0000
	v_lshl_add_u64 v[192:193], s[2:3], 0, v[154:155]
	s_addc_u32 s69, s3, 0
	s_add_i32 s70, s52, s36
	global_load_lds_dwordx4 v[192:193], off
	v_lshl_add_u64 v[240:241], s[68:69], 0, v[150:151]
	s_mov_b32 m0, s70
	v_lshl_add_u64 v[242:243], s[22:23], 0, v[152:153]
	global_load_lds_dwordx4 v[240:241], off
	v_lshl_add_u64 v[240:241], s[68:69], 0, v[154:155]
	s_add_i32 m0, s70, 0x2000
	s_nop 0
	global_load_lds_dwordx4 v[240:241], off
	v_lshl_add_u64 v[240:241], s[22:23], 0, v[148:149]
	s_mov_b32 m0, s37
	s_nop 0
	global_load_lds_dwordx4 v[240:241], off
	s_mov_b32 m0, s38
	s_nop 0
	global_load_lds_dwordx4 v[242:243], off
	s_waitcnt vmcnt(8)
	s_waitcnt lgkmcnt(0)
	s_barrier
	s_setprio 1
	v_mfma_f32_16x16x32_bf16 v[60:63], v[128:131], v[208:211], 0
	v_mfma_f32_16x16x32_bf16 v[56:59], v[136:139], v[208:211], 0
	v_mfma_f32_16x16x32_bf16 v[44:47], v[128:131], v[216:219], 0
	v_mfma_f32_16x16x32_bf16 v[40:43], v[136:139], v[216:219], 0
	v_mfma_f32_16x16x32_bf16 v[28:31], v[128:131], v[224:227], 0
	v_mfma_f32_16x16x32_bf16 v[24:27], v[136:139], v[224:227], 0
	v_mfma_f32_16x16x32_bf16 v[12:15], v[128:131], v[232:235], 0
	v_mfma_f32_16x16x32_bf16 v[8:11], v[136:139], v[232:235], 0
	v_mfma_f32_16x16x32_bf16 v[60:63], v[132:135], v[212:215], v[60:63]
	v_mfma_f32_16x16x32_bf16 v[56:59], v[164:167], v[212:215], v[56:59]
	v_mfma_f32_16x16x32_bf16 v[44:47], v[132:135], v[220:223], v[44:47]
	v_mfma_f32_16x16x32_bf16 v[40:43], v[164:167], v[220:223], v[40:43]
	v_mfma_f32_16x16x32_bf16 v[28:31], v[132:135], v[228:231], v[28:31]
	v_mfma_f32_16x16x32_bf16 v[24:27], v[164:167], v[228:231], v[24:27]
	v_mfma_f32_16x16x32_bf16 v[12:15], v[132:135], v[236:239], v[12:15]
	v_mfma_f32_16x16x32_bf16 v[8:11], v[164:167], v[236:239], v[8:11]
	v_mfma_f32_16x16x32_bf16 v[52:55], v[188:191], v[208:211], 0
	v_mfma_f32_16x16x32_bf16 v[48:51], v[200:203], v[208:211], 0
	v_mfma_f32_16x16x32_bf16 v[36:39], v[188:191], v[216:219], 0
	v_mfma_f32_16x16x32_bf16 v[32:35], v[200:203], v[216:219], 0
	v_mfma_f32_16x16x32_bf16 v[20:23], v[188:191], v[224:227], 0
	v_mfma_f32_16x16x32_bf16 v[16:19], v[200:203], v[224:227], 0
	v_mfma_f32_16x16x32_bf16 v[4:7], v[188:191], v[232:235], 0
	v_mfma_f32_16x16x32_bf16 v[0:3], v[200:203], v[232:235], 0
	v_mfma_f32_16x16x32_bf16 v[52:55], v[196:199], v[212:215], v[52:55]
	v_mfma_f32_16x16x32_bf16 v[48:51], v[204:207], v[212:215], v[48:51]
	v_mfma_f32_16x16x32_bf16 v[36:39], v[196:199], v[220:223], v[36:39]
	v_mfma_f32_16x16x32_bf16 v[32:35], v[204:207], v[220:223], v[32:35]
	v_mfma_f32_16x16x32_bf16 v[20:23], v[196:199], v[228:231], v[20:23]
	v_mfma_f32_16x16x32_bf16 v[16:19], v[204:207], v[228:231], v[16:19]
	v_mfma_f32_16x16x32_bf16 v[4:7], v[196:199], v[236:239], v[4:7]
	v_mfma_f32_16x16x32_bf16 v[0:3], v[204:207], v[236:239], v[0:3]
	s_barrier
	s_setprio 0
	s_add_i32 s68, 0, 0x18000
	s_add_i32 s69, 0, 0x1c000
	v_add_u32_e32 v164, s68, v141
	v_add_u32_e32 v187, s69, v141
	ds_read_b128 v[128:131], v164
	ds_read_b128 v[132:135], v164 offset:1024
	ds_read_b128 v[136:139], v164 offset:2048
	ds_read_b128 v[164:167], v164 offset:3072
	ds_read_b128 v[188:191], v187
	ds_read_b128 v[196:199], v187 offset:1024
	ds_read_b128 v[200:203], v187 offset:2048
	ds_read_b128 v[204:207], v187 offset:3072
	s_add_u32 s22, s22, 0xb0000
	s_addc_u32 s23, s23, 0
	s_mov_b32 m0, s39
	v_lshl_add_u64 v[244:245], s[22:23], 0, v[148:149]
	ds_read_b128 v[208:211], v185 offset:32768
	ds_read_b128 v[212:215], v185 offset:33792
	ds_read_b128 v[216:219], v185 offset:34816
	ds_read_b128 v[220:223], v185 offset:35840
	ds_read_b128 v[224:227], v185 offset:36864
	ds_read_b128 v[228:231], v185 offset:37888
	ds_read_b128 v[232:235], v185 offset:38912
	ds_read_b128 v[236:239], v185 offset:39936
	global_load_lds_dwordx4 v[244:245], off
	v_lshl_add_u64 v[244:245], s[22:23], 0, v[152:153]
	s_mov_b32 m0, s40
	s_nop 0
	global_load_lds_dwordx4 v[244:245], off
	s_waitcnt vmcnt(8)
	s_waitcnt lgkmcnt(0)
	s_barrier
	s_setprio 1
	v_mfma_f32_16x16x32_bf16 v[124:127], v[128:131], v[208:211], v[124:127]
	v_mfma_f32_16x16x32_bf16 v[120:123], v[136:139], v[208:211], v[120:123]
	v_mfma_f32_16x16x32_bf16 v[108:111], v[128:131], v[216:219], v[108:111]
	v_mfma_f32_16x16x32_bf16 v[104:107], v[136:139], v[216:219], v[104:107]
	v_mfma_f32_16x16x32_bf16 v[92:95], v[128:131], v[224:227], v[92:95]
	v_mfma_f32_16x16x32_bf16 v[88:91], v[136:139], v[224:227], v[88:91]
	v_mfma_f32_16x16x32_bf16 v[76:79], v[128:131], v[232:235], v[76:79]
	v_mfma_f32_16x16x32_bf16 v[72:75], v[136:139], v[232:235], v[72:75]
	v_mfma_f32_16x16x32_bf16 v[124:127], v[132:135], v[212:215], v[124:127]
	v_mfma_f32_16x16x32_bf16 v[120:123], v[164:167], v[212:215], v[120:123]
	v_mfma_f32_16x16x32_bf16 v[108:111], v[132:135], v[220:223], v[108:111]
	v_mfma_f32_16x16x32_bf16 v[104:107], v[164:167], v[220:223], v[104:107]
	v_mfma_f32_16x16x32_bf16 v[92:95], v[132:135], v[228:231], v[92:95]
	v_mfma_f32_16x16x32_bf16 v[88:91], v[164:167], v[228:231], v[88:91]
	v_mfma_f32_16x16x32_bf16 v[76:79], v[132:135], v[236:239], v[76:79]
	v_mfma_f32_16x16x32_bf16 v[72:75], v[164:167], v[236:239], v[72:75]
	v_mfma_f32_16x16x32_bf16 v[116:119], v[188:191], v[208:211], v[116:119]
	v_mfma_f32_16x16x32_bf16 v[112:115], v[200:203], v[208:211], v[112:115]
	v_mfma_f32_16x16x32_bf16 v[100:103], v[188:191], v[216:219], v[100:103]
	v_mfma_f32_16x16x32_bf16 v[96:99], v[200:203], v[216:219], v[96:99]
	v_mfma_f32_16x16x32_bf16 v[84:87], v[188:191], v[224:227], v[84:87]
	v_mfma_f32_16x16x32_bf16 v[80:83], v[200:203], v[224:227], v[80:83]
	v_mfma_f32_16x16x32_bf16 v[68:71], v[188:191], v[232:235], v[68:71]
	v_mfma_f32_16x16x32_bf16 v[64:67], v[200:203], v[232:235], v[64:67]
	v_mfma_f32_16x16x32_bf16 v[116:119], v[196:199], v[212:215], v[116:119]
	v_mfma_f32_16x16x32_bf16 v[112:115], v[204:207], v[212:215], v[112:115]
	v_mfma_f32_16x16x32_bf16 v[100:103], v[196:199], v[220:223], v[100:103]
	v_mfma_f32_16x16x32_bf16 v[96:99], v[204:207], v[220:223], v[96:99]
	v_mfma_f32_16x16x32_bf16 v[84:87], v[196:199], v[228:231], v[84:87]
	v_mfma_f32_16x16x32_bf16 v[80:83], v[204:207], v[228:231], v[80:83]
	v_mfma_f32_16x16x32_bf16 v[68:71], v[196:199], v[236:239], v[68:71]
	v_mfma_f32_16x16x32_bf16 v[64:67], v[204:207], v[236:239], v[64:67]
	s_barrier
	s_setprio 0
	s_add_i32 s22, s68, s36
	v_lshl_add_u64 v[168:169], v[168:169], 0, s[26:27]
	s_mov_b32 m0, s22
	ds_read_b128 v[208:211], v185 offset:49152
	ds_read_b128 v[212:215], v185 offset:50176
	ds_read_b128 v[216:219], v185 offset:51200
	ds_read_b128 v[220:223], v185 offset:52224
	ds_read_b128 v[224:227], v185 offset:53248
	ds_read_b128 v[228:231], v185 offset:54272
	ds_read_b128 v[232:235], v185 offset:55296
	ds_read_b128 v[236:239], v185 offset:56320
	global_load_lds_dwordx4 v[168:169], off
	s_add_i32 m0, s22, 0x2000
	s_add_u32 s2, s2, 0xb0080
	v_lshl_add_u64 v[168:169], v[192:193], 0, s[26:27]
	s_addc_u32 s3, s3, 0
	s_add_i32 s22, s69, s36
	global_load_lds_dwordx4 v[168:169], off
	v_lshl_add_u64 v[168:169], s[2:3], 0, v[150:151]
	s_mov_b32 m0, s22
	s_nop 0
	global_load_lds_dwordx4 v[168:169], off
	v_lshl_add_u64 v[168:169], s[2:3], 0, v[154:155]
	s_add_i32 m0, s22, 0x2000
	s_nop 0
	global_load_lds_dwordx4 v[168:169], off
	v_lshl_add_u64 v[168:169], v[240:241], 0, s[26:27]
	s_mov_b32 m0, s44
	s_nop 0
	global_load_lds_dwordx4 v[168:169], off
	v_lshl_add_u64 v[168:169], v[242:243], 0, s[26:27]
	s_mov_b32 m0, s45
	s_nop 0
	global_load_lds_dwordx4 v[168:169], off
	s_waitcnt vmcnt(8)
	s_waitcnt lgkmcnt(0)
	s_barrier
	s_setprio 1
	v_mfma_f32_16x16x32_bf16 v[60:63], v[128:131], v[208:211], v[60:63]
	v_mfma_f32_16x16x32_bf16 v[56:59], v[136:139], v[208:211], v[56:59]
	v_mfma_f32_16x16x32_bf16 v[44:47], v[128:131], v[216:219], v[44:47]
	v_mfma_f32_16x16x32_bf16 v[40:43], v[136:139], v[216:219], v[40:43]
	v_mfma_f32_16x16x32_bf16 v[28:31], v[128:131], v[224:227], v[28:31]
	v_mfma_f32_16x16x32_bf16 v[24:27], v[136:139], v[224:227], v[24:27]
	v_mfma_f32_16x16x32_bf16 v[12:15], v[128:131], v[232:235], v[12:15]
	v_mfma_f32_16x16x32_bf16 v[8:11], v[136:139], v[232:235], v[8:11]
	v_mfma_f32_16x16x32_bf16 v[60:63], v[132:135], v[212:215], v[60:63]
	v_mfma_f32_16x16x32_bf16 v[56:59], v[164:167], v[212:215], v[56:59]
	v_mfma_f32_16x16x32_bf16 v[44:47], v[132:135], v[220:223], v[44:47]
	v_mfma_f32_16x16x32_bf16 v[40:43], v[164:167], v[220:223], v[40:43]
	v_mfma_f32_16x16x32_bf16 v[28:31], v[132:135], v[228:231], v[28:31]
	v_mfma_f32_16x16x32_bf16 v[24:27], v[164:167], v[228:231], v[24:27]
	v_mfma_f32_16x16x32_bf16 v[12:15], v[132:135], v[236:239], v[12:15]
	v_mfma_f32_16x16x32_bf16 v[8:11], v[164:167], v[236:239], v[8:11]
	v_mfma_f32_16x16x32_bf16 v[52:55], v[188:191], v[208:211], v[52:55]
	v_mfma_f32_16x16x32_bf16 v[48:51], v[200:203], v[208:211], v[48:51]
	v_mfma_f32_16x16x32_bf16 v[36:39], v[188:191], v[216:219], v[36:39]
	v_mfma_f32_16x16x32_bf16 v[32:35], v[200:203], v[216:219], v[32:35]
	v_mfma_f32_16x16x32_bf16 v[20:23], v[188:191], v[224:227], v[20:23]
	v_mfma_f32_16x16x32_bf16 v[16:19], v[200:203], v[224:227], v[16:19]
	v_mfma_f32_16x16x32_bf16 v[4:7], v[188:191], v[232:235], v[4:7]
	v_mfma_f32_16x16x32_bf16 v[0:3], v[200:203], v[232:235], v[0:3]
	v_mfma_f32_16x16x32_bf16 v[52:55], v[196:199], v[212:215], v[52:55]
	v_mfma_f32_16x16x32_bf16 v[48:51], v[204:207], v[212:215], v[48:51]
	v_mfma_f32_16x16x32_bf16 v[36:39], v[196:199], v[220:223], v[36:39]
	v_mfma_f32_16x16x32_bf16 v[32:35], v[204:207], v[220:223], v[32:35]
	v_mfma_f32_16x16x32_bf16 v[20:23], v[196:199], v[228:231], v[20:23]
	v_mfma_f32_16x16x32_bf16 v[16:19], v[204:207], v[228:231], v[16:19]
	v_mfma_f32_16x16x32_bf16 v[4:7], v[196:199], v[236:239], v[4:7]
	v_mfma_f32_16x16x32_bf16 v[0:3], v[204:207], v[236:239], v[0:3]
	s_barrier
	s_setprio 0
	s_add_i32 s67, s67, 2
	s_add_u32 s14, s14, 0x100
	s_addc_u32 s15, s15, 0
	s_add_u32 s65, s65, 0x100
	s_addc_u32 s66, s66, 0
	s_cmp_gt_u32 s67, 41
	s_cbranch_scc1 .Lgemm_kdone_2
.LBB0_455:
	ds_read_b128 v[128:131], v147
	ds_read_b128 v[132:135], v147 offset:1024
	ds_read_b128 v[136:139], v147 offset:2048
	ds_read_b128 v[164:167], v147 offset:3072
	ds_read_b128 v[188:191], v184
	ds_read_b128 v[196:199], v184 offset:1024
	ds_read_b128 v[200:203], v184 offset:2048
	ds_read_b128 v[204:207], v184 offset:3072
	s_add_u32 s2, s14, 0xfff50080
	s_addc_u32 s3, s15, -1
	s_cmp_eq_u32 s67, 40
	s_cselect_b32 s23, s1, s3
	s_cselect_b32 s22, s0, s2
	s_cselect_b32 s3, s31, s66
	s_cselect_b32 s2, s30, s65
	v_lshl_add_u64 v[168:169], s[14:15], 0, v[156:157]
	s_add_i32 m0, s37, 0xc000
	ds_read_b128 v[208:211], v185
	ds_read_b128 v[212:215], v185 offset:1024
	ds_read_b128 v[216:219], v185 offset:2048
	ds_read_b128 v[220:223], v185 offset:3072
	ds_read_b128 v[224:227], v185 offset:4096
	ds_read_b128 v[228:231], v185 offset:5120
	ds_read_b128 v[232:235], v185 offset:6144
	ds_read_b128 v[236:239], v185 offset:7168
	global_load_lds_dwordx4 v[168:169], off
	v_lshl_add_u64 v[168:169], s[14:15], 0, v[158:159]
	s_add_i32 m0, s37, 0xe000
	s_nop 0
	global_load_lds_dwordx4 v[168:169], off
	s_waitcnt vmcnt(8)
	s_waitcnt lgkmcnt(0)
	s_barrier
	s_setprio 1
	v_mfma_f32_16x16x32_bf16 v[124:127], v[128:131], v[208:211], v[124:127]
	v_mfma_f32_16x16x32_bf16 v[120:123], v[136:139], v[208:211], v[120:123]
	v_mfma_f32_16x16x32_bf16 v[108:111], v[128:131], v[216:219], v[108:111]
	v_mfma_f32_16x16x32_bf16 v[104:107], v[136:139], v[216:219], v[104:107]
	v_mfma_f32_16x16x32_bf16 v[92:95], v[128:131], v[224:227], v[92:95]
	v_mfma_f32_16x16x32_bf16 v[88:91], v[136:139], v[224:227], v[88:91]
	v_mfma_f32_16x16x32_bf16 v[76:79], v[128:131], v[232:235], v[76:79]
	v_mfma_f32_16x16x32_bf16 v[72:75], v[136:139], v[232:235], v[72:75]
	v_mfma_f32_16x16x32_bf16 v[124:127], v[132:135], v[212:215], v[124:127]
	v_mfma_f32_16x16x32_bf16 v[120:123], v[164:167], v[212:215], v[120:123]
	v_mfma_f32_16x16x32_bf16 v[108:111], v[132:135], v[220:223], v[108:111]
	v_mfma_f32_16x16x32_bf16 v[104:107], v[164:167], v[220:223], v[104:107]
	v_mfma_f32_16x16x32_bf16 v[92:95], v[132:135], v[228:231], v[92:95]
	v_mfma_f32_16x16x32_bf16 v[88:91], v[164:167], v[228:231], v[88:91]
	v_mfma_f32_16x16x32_bf16 v[76:79], v[132:135], v[236:239], v[76:79]
	v_mfma_f32_16x16x32_bf16 v[72:75], v[164:167], v[236:239], v[72:75]
	v_mfma_f32_16x16x32_bf16 v[116:119], v[188:191], v[208:211], v[116:119]
	v_mfma_f32_16x16x32_bf16 v[112:115], v[200:203], v[208:211], v[112:115]
	v_mfma_f32_16x16x32_bf16 v[100:103], v[188:191], v[216:219], v[100:103]
	v_mfma_f32_16x16x32_bf16 v[96:99], v[200:203], v[216:219], v[96:99]
	v_mfma_f32_16x16x32_bf16 v[84:87], v[188:191], v[224:227], v[84:87]
	v_mfma_f32_16x16x32_bf16 v[80:83], v[200:203], v[224:227], v[80:83]
	v_mfma_f32_16x16x32_bf16 v[68:71], v[188:191], v[232:235], v[68:71]
	v_mfma_f32_16x16x32_bf16 v[64:67], v[200:203], v[232:235], v[64:67]
	v_mfma_f32_16x16x32_bf16 v[116:119], v[196:199], v[212:215], v[116:119]
	v_mfma_f32_16x16x32_bf16 v[112:115], v[204:207], v[212:215], v[112:115]
	v_mfma_f32_16x16x32_bf16 v[100:103], v[196:199], v[220:223], v[100:103]
	v_mfma_f32_16x16x32_bf16 v[96:99], v[204:207], v[220:223], v[96:99]
	v_mfma_f32_16x16x32_bf16 v[84:87], v[196:199], v[228:231], v[84:87]
	v_mfma_f32_16x16x32_bf16 v[80:83], v[204:207], v[228:231], v[80:83]
	v_mfma_f32_16x16x32_bf16 v[68:71], v[196:199], v[236:239], v[68:71]
	v_mfma_f32_16x16x32_bf16 v[64:67], v[204:207], v[236:239], v[64:67]
	s_barrier
	s_setprio 0
	s_add_i32 s68, s51, s36
	v_lshl_add_u64 v[168:169], s[2:3], 0, v[150:151]
	s_mov_b32 m0, s68
	ds_read_b128 v[208:211], v185 offset:16384
	ds_read_b128 v[212:215], v185 offset:17408
	ds_read_b128 v[216:219], v185 offset:18432
	ds_read_b128 v[220:223], v185 offset:19456
	ds_read_b128 v[224:227], v185 offset:20480
	ds_read_b128 v[228:231], v185 offset:21504
	ds_read_b128 v[232:235], v185 offset:22528
	ds_read_b128 v[236:239], v185 offset:23552
	global_load_lds_dwordx4 v[168:169], off
	s_add_i32 m0, s68, 0x2000
	s_add_u32 s68, s2, 0xb0000
	v_lshl_add_u64 v[192:193], s[2:3], 0, v[154:155]
	s_addc_u32 s69, s3, 0
	s_add_i32 s70, s52, s36
	global_load_lds_dwordx4 v[192:193], off
	v_lshl_add_u64 v[240:241], s[68:69], 0, v[150:151]
	s_mov_b32 m0, s70
	v_lshl_add_u64 v[242:243], s[22:23], 0, v[152:153]
	global_load_lds_dwordx4 v[240:241], off
	v_lshl_add_u64 v[240:241], s[68:69], 0, v[154:155]
	s_add_i32 m0, s70, 0x2000
	s_nop 0
	global_load_lds_dwordx4 v[240:241], off
	v_lshl_add_u64 v[240:241], s[22:23], 0, v[148:149]
	s_mov_b32 m0, s37
	s_nop 0
	global_load_lds_dwordx4 v[240:241], off
	s_mov_b32 m0, s38
	s_nop 0
	global_load_lds_dwordx4 v[242:243], off
	s_waitcnt vmcnt(8)
	s_waitcnt lgkmcnt(0)
	s_barrier
	s_setprio 1
	v_mfma_f32_16x16x32_bf16 v[60:63], v[128:131], v[208:211], v[60:63]
	v_mfma_f32_16x16x32_bf16 v[56:59], v[136:139], v[208:211], v[56:59]
	v_mfma_f32_16x16x32_bf16 v[44:47], v[128:131], v[216:219], v[44:47]
	v_mfma_f32_16x16x32_bf16 v[40:43], v[136:139], v[216:219], v[40:43]
	v_mfma_f32_16x16x32_bf16 v[28:31], v[128:131], v[224:227], v[28:31]
	v_mfma_f32_16x16x32_bf16 v[24:27], v[136:139], v[224:227], v[24:27]
	v_mfma_f32_16x16x32_bf16 v[12:15], v[128:131], v[232:235], v[12:15]
	v_mfma_f32_16x16x32_bf16 v[8:11], v[136:139], v[232:235], v[8:11]
	v_mfma_f32_16x16x32_bf16 v[60:63], v[132:135], v[212:215], v[60:63]
	v_mfma_f32_16x16x32_bf16 v[56:59], v[164:167], v[212:215], v[56:59]
	v_mfma_f32_16x16x32_bf16 v[44:47], v[132:135], v[220:223], v[44:47]
	v_mfma_f32_16x16x32_bf16 v[40:43], v[164:167], v[220:223], v[40:43]
	v_mfma_f32_16x16x32_bf16 v[28:31], v[132:135], v[228:231], v[28:31]
	v_mfma_f32_16x16x32_bf16 v[24:27], v[164:167], v[228:231], v[24:27]
	v_mfma_f32_16x16x32_bf16 v[12:15], v[132:135], v[236:239], v[12:15]
	v_mfma_f32_16x16x32_bf16 v[8:11], v[164:167], v[236:239], v[8:11]
	v_mfma_f32_16x16x32_bf16 v[52:55], v[188:191], v[208:211], v[52:55]
	v_mfma_f32_16x16x32_bf16 v[48:51], v[200:203], v[208:211], v[48:51]
	v_mfma_f32_16x16x32_bf16 v[36:39], v[188:191], v[216:219], v[36:39]
	v_mfma_f32_16x16x32_bf16 v[32:35], v[200:203], v[216:219], v[32:35]
	v_mfma_f32_16x16x32_bf16 v[20:23], v[188:191], v[224:227], v[20:23]
	v_mfma_f32_16x16x32_bf16 v[16:19], v[200:203], v[224:227], v[16:19]
	v_mfma_f32_16x16x32_bf16 v[4:7], v[188:191], v[232:235], v[4:7]
	v_mfma_f32_16x16x32_bf16 v[0:3], v[200:203], v[232:235], v[0:3]
	v_mfma_f32_16x16x32_bf16 v[52:55], v[196:199], v[212:215], v[52:55]
	v_mfma_f32_16x16x32_bf16 v[48:51], v[204:207], v[212:215], v[48:51]
	v_mfma_f32_16x16x32_bf16 v[36:39], v[196:199], v[220:223], v[36:39]
	v_mfma_f32_16x16x32_bf16 v[32:35], v[204:207], v[220:223], v[32:35]
	v_mfma_f32_16x16x32_bf16 v[20:23], v[196:199], v[228:231], v[20:23]
	v_mfma_f32_16x16x32_bf16 v[16:19], v[204:207], v[228:231], v[16:19]
	v_mfma_f32_16x16x32_bf16 v[4:7], v[196:199], v[236:239], v[4:7]
	v_mfma_f32_16x16x32_bf16 v[0:3], v[204:207], v[236:239], v[0:3]
	s_barrier
	s_setprio 0
	s_add_i32 s68, 0, 0x18000
	s_add_i32 s69, 0, 0x1c000
	v_add_u32_e32 v164, s68, v141
	v_add_u32_e32 v187, s69, v141
	ds_read_b128 v[128:131], v164
	ds_read_b128 v[132:135], v164 offset:1024
	ds_read_b128 v[136:139], v164 offset:2048
	ds_read_b128 v[164:167], v164 offset:3072
	ds_read_b128 v[188:191], v187
	ds_read_b128 v[196:199], v187 offset:1024
	ds_read_b128 v[200:203], v187 offset:2048
	ds_read_b128 v[204:207], v187 offset:3072
	s_add_u32 s22, s22, 0xb0000
	s_addc_u32 s23, s23, 0
	s_mov_b32 m0, s39
	v_lshl_add_u64 v[244:245], s[22:23], 0, v[148:149]
	ds_read_b128 v[208:211], v185 offset:32768
	ds_read_b128 v[212:215], v185 offset:33792
	ds_read_b128 v[216:219], v185 offset:34816
	ds_read_b128 v[220:223], v185 offset:35840
	ds_read_b128 v[224:227], v185 offset:36864
	ds_read_b128 v[228:231], v185 offset:37888
	ds_read_b128 v[232:235], v185 offset:38912
	ds_read_b128 v[236:239], v185 offset:39936
	global_load_lds_dwordx4 v[244:245], off
	v_lshl_add_u64 v[244:245], s[22:23], 0, v[152:153]
	s_mov_b32 m0, s40
	s_nop 0
	global_load_lds_dwordx4 v[244:245], off
	s_waitcnt vmcnt(8)
	s_waitcnt lgkmcnt(0)
	s_barrier
	s_setprio 1
	v_mfma_f32_16x16x32_bf16 v[124:127], v[128:131], v[208:211], v[124:127]
	v_mfma_f32_16x16x32_bf16 v[120:123], v[136:139], v[208:211], v[120:123]
	v_mfma_f32_16x16x32_bf16 v[108:111], v[128:131], v[216:219], v[108:111]
	v_mfma_f32_16x16x32_bf16 v[104:107], v[136:139], v[216:219], v[104:107]
	v_mfma_f32_16x16x32_bf16 v[92:95], v[128:131], v[224:227], v[92:95]
	v_mfma_f32_16x16x32_bf16 v[88:91], v[136:139], v[224:227], v[88:91]
	v_mfma_f32_16x16x32_bf16 v[76:79], v[128:131], v[232:235], v[76:79]
	v_mfma_f32_16x16x32_bf16 v[72:75], v[136:139], v[232:235], v[72:75]
	v_mfma_f32_16x16x32_bf16 v[124:127], v[132:135], v[212:215], v[124:127]
	v_mfma_f32_16x16x32_bf16 v[120:123], v[164:167], v[212:215], v[120:123]
	v_mfma_f32_16x16x32_bf16 v[108:111], v[132:135], v[220:223], v[108:111]
	v_mfma_f32_16x16x32_bf16 v[104:107], v[164:167], v[220:223], v[104:107]
	v_mfma_f32_16x16x32_bf16 v[92:95], v[132:135], v[228:231], v[92:95]
	v_mfma_f32_16x16x32_bf16 v[88:91], v[164:167], v[228:231], v[88:91]
	v_mfma_f32_16x16x32_bf16 v[76:79], v[132:135], v[236:239], v[76:79]
	v_mfma_f32_16x16x32_bf16 v[72:75], v[164:167], v[236:239], v[72:75]
	v_mfma_f32_16x16x32_bf16 v[116:119], v[188:191], v[208:211], v[116:119]
	v_mfma_f32_16x16x32_bf16 v[112:115], v[200:203], v[208:211], v[112:115]
	v_mfma_f32_16x16x32_bf16 v[100:103], v[188:191], v[216:219], v[100:103]
	v_mfma_f32_16x16x32_bf16 v[96:99], v[200:203], v[216:219], v[96:99]
	v_mfma_f32_16x16x32_bf16 v[84:87], v[188:191], v[224:227], v[84:87]
	v_mfma_f32_16x16x32_bf16 v[80:83], v[200:203], v[224:227], v[80:83]
	v_mfma_f32_16x16x32_bf16 v[68:71], v[188:191], v[232:235], v[68:71]
	v_mfma_f32_16x16x32_bf16 v[64:67], v[200:203], v[232:235], v[64:67]
	v_mfma_f32_16x16x32_bf16 v[116:119], v[196:199], v[212:215], v[116:119]
	v_mfma_f32_16x16x32_bf16 v[112:115], v[204:207], v[212:215], v[112:115]
	v_mfma_f32_16x16x32_bf16 v[100:103], v[196:199], v[220:223], v[100:103]
	v_mfma_f32_16x16x32_bf16 v[96:99], v[204:207], v[220:223], v[96:99]
	v_mfma_f32_16x16x32_bf16 v[84:87], v[196:199], v[228:231], v[84:87]
	v_mfma_f32_16x16x32_bf16 v[80:83], v[204:207], v[228:231], v[80:83]
	v_mfma_f32_16x16x32_bf16 v[68:71], v[196:199], v[236:239], v[68:71]
	v_mfma_f32_16x16x32_bf16 v[64:67], v[204:207], v[236:239], v[64:67]
	s_barrier
	s_setprio 0
	s_add_i32 s22, s68, s36
	v_lshl_add_u64 v[168:169], v[168:169], 0, s[26:27]
	s_mov_b32 m0, s22
	ds_read_b128 v[208:211], v185 offset:49152
	ds_read_b128 v[212:215], v185 offset:50176
	ds_read_b128 v[216:219], v185 offset:51200
	ds_read_b128 v[220:223], v185 offset:52224
	ds_read_b128 v[224:227], v185 offset:53248
	ds_read_b128 v[228:231], v185 offset:54272
	ds_read_b128 v[232:235], v185 offset:55296
	ds_read_b128 v[236:239], v185 offset:56320
	global_load_lds_dwordx4 v[168:169], off
	s_add_i32 m0, s22, 0x2000
	s_add_u32 s2, s2, 0xb0080
	v_lshl_add_u64 v[168:169], v[192:193], 0, s[26:27]
	s_addc_u32 s3, s3, 0
	s_add_i32 s22, s69, s36
	global_load_lds_dwordx4 v[168:169], off
	v_lshl_add_u64 v[168:169], s[2:3], 0, v[150:151]
	s_mov_b32 m0, s22
	s_nop 0
	global_load_lds_dwordx4 v[168:169], off
	v_lshl_add_u64 v[168:169], s[2:3], 0, v[154:155]
	s_add_i32 m0, s22, 0x2000
	s_nop 0
	global_load_lds_dwordx4 v[168:169], off
	v_lshl_add_u64 v[168:169], v[240:241], 0, s[26:27]
	s_mov_b32 m0, s44
	s_nop 0
	global_load_lds_dwordx4 v[168:169], off
	v_lshl_add_u64 v[168:169], v[242:243], 0, s[26:27]
	s_mov_b32 m0, s45
	s_nop 0
	global_load_lds_dwordx4 v[168:169], off
	s_waitcnt vmcnt(8)
	s_waitcnt lgkmcnt(0)
	s_barrier
	s_setprio 1
	v_mfma_f32_16x16x32_bf16 v[60:63], v[128:131], v[208:211], v[60:63]
	v_mfma_f32_16x16x32_bf16 v[56:59], v[136:139], v[208:211], v[56:59]
	v_mfma_f32_16x16x32_bf16 v[44:47], v[128:131], v[216:219], v[44:47]
	v_mfma_f32_16x16x32_bf16 v[40:43], v[136:139], v[216:219], v[40:43]
	v_mfma_f32_16x16x32_bf16 v[28:31], v[128:131], v[224:227], v[28:31]
	v_mfma_f32_16x16x32_bf16 v[24:27], v[136:139], v[224:227], v[24:27]
	v_mfma_f32_16x16x32_bf16 v[12:15], v[128:131], v[232:235], v[12:15]
	v_mfma_f32_16x16x32_bf16 v[8:11], v[136:139], v[232:235], v[8:11]
	v_mfma_f32_16x16x32_bf16 v[60:63], v[132:135], v[212:215], v[60:63]
	v_mfma_f32_16x16x32_bf16 v[56:59], v[164:167], v[212:215], v[56:59]
	v_mfma_f32_16x16x32_bf16 v[44:47], v[132:135], v[220:223], v[44:47]
	v_mfma_f32_16x16x32_bf16 v[40:43], v[164:167], v[220:223], v[40:43]
	v_mfma_f32_16x16x32_bf16 v[28:31], v[132:135], v[228:231], v[28:31]
	v_mfma_f32_16x16x32_bf16 v[24:27], v[164:167], v[228:231], v[24:27]
	v_mfma_f32_16x16x32_bf16 v[12:15], v[132:135], v[236:239], v[12:15]
	v_mfma_f32_16x16x32_bf16 v[8:11], v[164:167], v[236:239], v[8:11]
	v_mfma_f32_16x16x32_bf16 v[52:55], v[188:191], v[208:211], v[52:55]
	v_mfma_f32_16x16x32_bf16 v[48:51], v[200:203], v[208:211], v[48:51]
	v_mfma_f32_16x16x32_bf16 v[36:39], v[188:191], v[216:219], v[36:39]
	v_mfma_f32_16x16x32_bf16 v[32:35], v[200:203], v[216:219], v[32:35]
	v_mfma_f32_16x16x32_bf16 v[20:23], v[188:191], v[224:227], v[20:23]
	v_mfma_f32_16x16x32_bf16 v[16:19], v[200:203], v[224:227], v[16:19]
	v_mfma_f32_16x16x32_bf16 v[4:7], v[188:191], v[232:235], v[4:7]
	v_mfma_f32_16x16x32_bf16 v[0:3], v[200:203], v[232:235], v[0:3]
	v_mfma_f32_16x16x32_bf16 v[52:55], v[196:199], v[212:215], v[52:55]
	v_mfma_f32_16x16x32_bf16 v[48:51], v[204:207], v[212:215], v[48:51]
	v_mfma_f32_16x16x32_bf16 v[36:39], v[196:199], v[220:223], v[36:39]
	v_mfma_f32_16x16x32_bf16 v[32:35], v[204:207], v[220:223], v[32:35]
	v_mfma_f32_16x16x32_bf16 v[20:23], v[196:199], v[228:231], v[20:23]
	v_mfma_f32_16x16x32_bf16 v[16:19], v[204:207], v[228:231], v[16:19]
	v_mfma_f32_16x16x32_bf16 v[4:7], v[196:199], v[236:239], v[4:7]
	v_mfma_f32_16x16x32_bf16 v[0:3], v[204:207], v[236:239], v[0:3]
	s_barrier
	s_setprio 0
	s_add_i32 s67, s67, 2
	s_add_u32 s14, s14, 0x100
	s_addc_u32 s15, s15, 0
	s_add_u32 s65, s65, 0x100
	s_addc_u32 s66, s66, 0
	s_cmp_gt_u32 s67, 41
	s_cbranch_scc0 .LBB0_455

.LBB0_551:
	s_ashr_i32 s41, s40, 31
	s_lshl_b64 s[22:23], s[40:41], 19
	s_add_u32 s42, s84, s22
	s_addc_u32 s43, s85, s23
	s_and_b64 s[22:23], s[4:5], exec
	s_cselect_b32 s41, s43, s15
	s_cselect_b32 s69, s42, s14
	s_ashr_i32 s39, s38, 31
	s_lshl_b64 s[22:23], s[38:39], 19
	s_add_u32 s44, s34, s22
	s_addc_u32 s45, s35, s23
	s_and_b64 s[22:23], s[4:5], exec
	s_cselect_b32 s39, s45, s3
	s_cselect_b32 s70, s44, s2
	s_add_u32 s14, s14, 0x40080
	s_addc_u32 s15, s15, 0
	s_add_u32 s71, s2, 0x100
	s_addc_u32 s72, s3, 0
	s_mov_b32 s73, -2
	s_waitcnt vmcnt(0)
	ds_read_b128 v[156:159], v155
	ds_read_b128 v[160:163], v155 offset:1024
	ds_read_b128 v[184:187], v155 offset:2048
	ds_read_b128 v[188:191], v155 offset:3072
	ds_read_b128 v[196:199], v166
	ds_read_b128 v[200:203], v166 offset:1024
	ds_read_b128 v[204:207], v166 offset:2048
	ds_read_b128 v[208:211], v166 offset:3072
	s_add_u32 s2, s14, 0xfffc0080
	s_addc_u32 s3, s15, -1
	s_cmp_eq_u32 s73, 12
	s_cselect_b32 s23, s41, s3
	s_cselect_b32 s22, s69, s2
	s_cselect_b32 s3, s39, s72
	s_cselect_b32 s2, s70, s71
	v_lshl_add_u64 v[138:139], s[14:15], 0, v[130:131]
	s_add_i32 m0, s49, 0xc000
	ds_read_b128 v[212:215], v167
	ds_read_b128 v[216:219], v167 offset:1024
	ds_read_b128 v[220:223], v167 offset:2048
	ds_read_b128 v[224:227], v167 offset:3072
	ds_read_b128 v[228:231], v167 offset:4096
	ds_read_b128 v[232:235], v167 offset:5120
	ds_read_b128 v[236:239], v167 offset:6144
	ds_read_b128 v[240:243], v167 offset:7168
	global_load_lds_dwordx4 v[138:139], off
	v_lshl_add_u64 v[138:139], s[14:15], 0, v[132:133]
	s_add_i32 m0, s49, 0xe000
	s_nop 0
	global_load_lds_dwordx4 v[138:139], off
	s_waitcnt vmcnt(8)
	s_waitcnt lgkmcnt(0)
	s_barrier
	s_setprio 1
	v_mfma_f32_16x16x32_bf16 v[124:127], v[156:159], v[212:215], 0
	v_mfma_f32_16x16x32_bf16 v[120:123], v[184:187], v[212:215], 0
	v_mfma_f32_16x16x32_bf16 v[116:119], v[156:159], v[220:223], 0
	v_mfma_f32_16x16x32_bf16 v[112:115], v[184:187], v[220:223], 0
	v_mfma_f32_16x16x32_bf16 v[92:95], v[156:159], v[228:231], 0
	v_mfma_f32_16x16x32_bf16 v[88:91], v[184:187], v[228:231], 0
	v_mfma_f32_16x16x32_bf16 v[76:79], v[156:159], v[236:239], 0
	v_mfma_f32_16x16x32_bf16 v[72:75], v[184:187], v[236:239], 0
	v_mfma_f32_16x16x32_bf16 v[124:127], v[160:163], v[216:219], v[124:127]
	v_mfma_f32_16x16x32_bf16 v[120:123], v[188:191], v[216:219], v[120:123]
	v_mfma_f32_16x16x32_bf16 v[116:119], v[160:163], v[224:227], v[116:119]
	v_mfma_f32_16x16x32_bf16 v[112:115], v[188:191], v[224:227], v[112:115]
	v_mfma_f32_16x16x32_bf16 v[92:95], v[160:163], v[232:235], v[92:95]
	v_mfma_f32_16x16x32_bf16 v[88:91], v[188:191], v[232:235], v[88:91]
	v_mfma_f32_16x16x32_bf16 v[76:79], v[160:163], v[240:243], v[76:79]
	v_mfma_f32_16x16x32_bf16 v[72:75], v[188:191], v[240:243], v[72:75]
	v_mfma_f32_16x16x32_bf16 v[108:111], v[196:199], v[212:215], 0
	v_mfma_f32_16x16x32_bf16 v[104:107], v[204:207], v[212:215], 0
	v_mfma_f32_16x16x32_bf16 v[100:103], v[196:199], v[220:223], 0
	v_mfma_f32_16x16x32_bf16 v[96:99], v[204:207], v[220:223], 0
	v_mfma_f32_16x16x32_bf16 v[84:87], v[196:199], v[228:231], 0
	v_mfma_f32_16x16x32_bf16 v[80:83], v[204:207], v[228:231], 0
	v_mfma_f32_16x16x32_bf16 v[68:71], v[196:199], v[236:239], 0
	v_mfma_f32_16x16x32_bf16 v[64:67], v[204:207], v[236:239], 0
	v_mfma_f32_16x16x32_bf16 v[108:111], v[200:203], v[216:219], v[108:111]
	v_mfma_f32_16x16x32_bf16 v[104:107], v[208:211], v[216:219], v[104:107]
	v_mfma_f32_16x16x32_bf16 v[100:103], v[200:203], v[224:227], v[100:103]
	v_mfma_f32_16x16x32_bf16 v[96:99], v[208:211], v[224:227], v[96:99]
	v_mfma_f32_16x16x32_bf16 v[84:87], v[200:203], v[232:235], v[84:87]
	v_mfma_f32_16x16x32_bf16 v[80:83], v[208:211], v[232:235], v[80:83]
	v_mfma_f32_16x16x32_bf16 v[68:71], v[200:203], v[240:243], v[68:71]
	v_mfma_f32_16x16x32_bf16 v[64:67], v[208:211], v[240:243], v[64:67]
	s_barrier
	s_setprio 0
	s_add_i32 s74, s58, s46
	v_lshl_add_u64 v[138:139], s[2:3], 0, v[142:143]
	s_mov_b32 m0, s74
	ds_read_b128 v[212:215], v167 offset:16384
	ds_read_b128 v[216:219], v167 offset:17408
	ds_read_b128 v[220:223], v167 offset:18432
	ds_read_b128 v[224:227], v167 offset:19456
	ds_read_b128 v[228:231], v167 offset:20480
	ds_read_b128 v[232:235], v167 offset:21504
	ds_read_b128 v[236:239], v167 offset:22528
	ds_read_b128 v[240:243], v167 offset:23552
	global_load_lds_dwordx4 v[138:139], off
	s_add_i32 m0, s74, 0x2000
	s_add_u32 s74, s2, 0x40000
	v_lshl_add_u64 v[164:165], s[2:3], 0, v[146:147]
	s_addc_u32 s75, s3, 0
	s_add_i32 s76, s59, s46
	global_load_lds_dwordx4 v[164:165], off
	v_lshl_add_u64 v[192:193], s[74:75], 0, v[142:143]
	s_mov_b32 m0, s76
	v_lshl_add_u64 v[244:245], s[22:23], 0, v[144:145]
	global_load_lds_dwordx4 v[192:193], off
	v_lshl_add_u64 v[192:193], s[74:75], 0, v[146:147]
	s_add_i32 m0, s76, 0x2000
	s_nop 0
	global_load_lds_dwordx4 v[192:193], off
	v_lshl_add_u64 v[192:193], s[22:23], 0, v[140:141]
	s_mov_b32 m0, s49
	s_nop 0
	global_load_lds_dwordx4 v[192:193], off
	s_mov_b32 m0, s50
	s_nop 0
	global_load_lds_dwordx4 v[244:245], off
	s_waitcnt vmcnt(8)
	s_waitcnt lgkmcnt(0)
	s_barrier
	s_setprio 1
	v_mfma_f32_16x16x32_bf16 v[60:63], v[156:159], v[212:215], 0
	v_mfma_f32_16x16x32_bf16 v[56:59], v[184:187], v[212:215], 0
	v_mfma_f32_16x16x32_bf16 v[44:47], v[156:159], v[220:223], 0
	v_mfma_f32_16x16x32_bf16 v[40:43], v[184:187], v[220:223], 0
	v_mfma_f32_16x16x32_bf16 v[28:31], v[156:159], v[228:231], 0
	v_mfma_f32_16x16x32_bf16 v[24:27], v[184:187], v[228:231], 0
	v_mfma_f32_16x16x32_bf16 v[12:15], v[156:159], v[236:239], 0
	v_mfma_f32_16x16x32_bf16 v[8:11], v[184:187], v[236:239], 0
	v_mfma_f32_16x16x32_bf16 v[60:63], v[160:163], v[216:219], v[60:63]
	v_mfma_f32_16x16x32_bf16 v[56:59], v[188:191], v[216:219], v[56:59]
	v_mfma_f32_16x16x32_bf16 v[44:47], v[160:163], v[224:227], v[44:47]
	v_mfma_f32_16x16x32_bf16 v[40:43], v[188:191], v[224:227], v[40:43]
	v_mfma_f32_16x16x32_bf16 v[28:31], v[160:163], v[232:235], v[28:31]
	v_mfma_f32_16x16x32_bf16 v[24:27], v[188:191], v[232:235], v[24:27]
	v_mfma_f32_16x16x32_bf16 v[12:15], v[160:163], v[240:243], v[12:15]
	v_mfma_f32_16x16x32_bf16 v[8:11], v[188:191], v[240:243], v[8:11]
	v_mfma_f32_16x16x32_bf16 v[52:55], v[196:199], v[212:215], 0
	v_mfma_f32_16x16x32_bf16 v[48:51], v[204:207], v[212:215], 0
	v_mfma_f32_16x16x32_bf16 v[36:39], v[196:199], v[220:223], 0
	v_mfma_f32_16x16x32_bf16 v[32:35], v[204:207], v[220:223], 0
	v_mfma_f32_16x16x32_bf16 v[20:23], v[196:199], v[228:231], 0
	v_mfma_f32_16x16x32_bf16 v[16:19], v[204:207], v[228:231], 0
	v_mfma_f32_16x16x32_bf16 v[4:7], v[196:199], v[236:239], 0
	v_mfma_f32_16x16x32_bf16 v[0:3], v[204:207], v[236:239], 0
	v_mfma_f32_16x16x32_bf16 v[52:55], v[200:203], v[216:219], v[52:55]
	v_mfma_f32_16x16x32_bf16 v[48:51], v[208:211], v[216:219], v[48:51]
	v_mfma_f32_16x16x32_bf16 v[36:39], v[200:203], v[224:227], v[36:39]
	v_mfma_f32_16x16x32_bf16 v[32:35], v[208:211], v[224:227], v[32:35]
	v_mfma_f32_16x16x32_bf16 v[20:23], v[200:203], v[232:235], v[20:23]
	v_mfma_f32_16x16x32_bf16 v[16:19], v[208:211], v[232:235], v[16:19]
	v_mfma_f32_16x16x32_bf16 v[4:7], v[200:203], v[240:243], v[4:7]
	v_mfma_f32_16x16x32_bf16 v[0:3], v[208:211], v[240:243], v[0:3]
	s_barrier
	s_setprio 0
	s_add_i32 s74, 0, 0x18000
	v_add_u32_e32 v128, s74, v151
	s_add_i32 s75, 0, 0x1c000
	ds_read_b128 v[156:159], v128
	ds_read_b128 v[160:163], v128 offset:1024
	ds_read_b128 v[184:187], v128 offset:2048
	ds_read_b128 v[188:191], v128 offset:3072
	v_add_u32_e32 v128, s75, v151
	ds_read_b128 v[196:199], v128
	ds_read_b128 v[200:203], v128 offset:1024
	ds_read_b128 v[204:207], v128 offset:2048
	ds_read_b128 v[208:211], v128 offset:3072
	s_add_u32 s22, s22, 0x40000
	s_addc_u32 s23, s23, 0
	s_mov_b32 m0, s51
	v_lshl_add_u64 v[246:247], s[22:23], 0, v[140:141]
	ds_read_b128 v[212:215], v167 offset:32768
	ds_read_b128 v[216:219], v167 offset:33792
	ds_read_b128 v[220:223], v167 offset:34816
	ds_read_b128 v[224:227], v167 offset:35840
	ds_read_b128 v[228:231], v167 offset:36864
	ds_read_b128 v[232:235], v167 offset:37888
	ds_read_b128 v[236:239], v167 offset:38912
	ds_read_b128 v[240:243], v167 offset:39936
	global_load_lds_dwordx4 v[246:247], off
	v_lshl_add_u64 v[246:247], s[22:23], 0, v[144:145]
	s_mov_b32 m0, s52
	s_nop 0
	global_load_lds_dwordx4 v[246:247], off
	s_waitcnt vmcnt(8)
	s_waitcnt lgkmcnt(0)
	s_barrier
	s_setprio 1
	v_mfma_f32_16x16x32_bf16 v[124:127], v[156:159], v[212:215], v[124:127]
	v_mfma_f32_16x16x32_bf16 v[120:123], v[184:187], v[212:215], v[120:123]
	v_mfma_f32_16x16x32_bf16 v[116:119], v[156:159], v[220:223], v[116:119]
	v_mfma_f32_16x16x32_bf16 v[112:115], v[184:187], v[220:223], v[112:115]
	v_mfma_f32_16x16x32_bf16 v[92:95], v[156:159], v[228:231], v[92:95]
	v_mfma_f32_16x16x32_bf16 v[88:91], v[184:187], v[228:231], v[88:91]
	v_mfma_f32_16x16x32_bf16 v[76:79], v[156:159], v[236:239], v[76:79]
	v_mfma_f32_16x16x32_bf16 v[72:75], v[184:187], v[236:239], v[72:75]
	v_mfma_f32_16x16x32_bf16 v[124:127], v[160:163], v[216:219], v[124:127]
	v_mfma_f32_16x16x32_bf16 v[120:123], v[188:191], v[216:219], v[120:123]
	v_mfma_f32_16x16x32_bf16 v[116:119], v[160:163], v[224:227], v[116:119]
	v_mfma_f32_16x16x32_bf16 v[112:115], v[188:191], v[224:227], v[112:115]
	v_mfma_f32_16x16x32_bf16 v[92:95], v[160:163], v[232:235], v[92:95]
	v_mfma_f32_16x16x32_bf16 v[88:91], v[188:191], v[232:235], v[88:91]
	v_mfma_f32_16x16x32_bf16 v[76:79], v[160:163], v[240:243], v[76:79]
	v_mfma_f32_16x16x32_bf16 v[72:75], v[188:191], v[240:243], v[72:75]
	v_mfma_f32_16x16x32_bf16 v[108:111], v[196:199], v[212:215], v[108:111]
	v_mfma_f32_16x16x32_bf16 v[104:107], v[204:207], v[212:215], v[104:107]
	v_mfma_f32_16x16x32_bf16 v[100:103], v[196:199], v[220:223], v[100:103]
	v_mfma_f32_16x16x32_bf16 v[96:99], v[204:207], v[220:223], v[96:99]
	v_mfma_f32_16x16x32_bf16 v[84:87], v[196:199], v[228:231], v[84:87]
	v_mfma_f32_16x16x32_bf16 v[80:83], v[204:207], v[228:231], v[80:83]
	v_mfma_f32_16x16x32_bf16 v[68:71], v[196:199], v[236:239], v[68:71]
	v_mfma_f32_16x16x32_bf16 v[64:67], v[204:207], v[236:239], v[64:67]
	v_mfma_f32_16x16x32_bf16 v[108:111], v[200:203], v[216:219], v[108:111]
	v_mfma_f32_16x16x32_bf16 v[104:107], v[208:211], v[216:219], v[104:107]
	v_mfma_f32_16x16x32_bf16 v[100:103], v[200:203], v[224:227], v[100:103]
	v_mfma_f32_16x16x32_bf16 v[96:99], v[208:211], v[224:227], v[96:99]
	v_mfma_f32_16x16x32_bf16 v[84:87], v[200:203], v[232:235], v[84:87]
	v_mfma_f32_16x16x32_bf16 v[80:83], v[208:211], v[232:235], v[80:83]
	v_mfma_f32_16x16x32_bf16 v[68:71], v[200:203], v[240:243], v[68:71]
	v_mfma_f32_16x16x32_bf16 v[64:67], v[208:211], v[240:243], v[64:67]
	s_barrier
	s_setprio 0
	s_add_i32 s22, s74, s46
	v_lshl_add_u64 v[138:139], v[138:139], 0, s[24:25]
	s_mov_b32 m0, s22
	ds_read_b128 v[212:215], v167 offset:49152
	ds_read_b128 v[216:219], v167 offset:50176
	ds_read_b128 v[220:223], v167 offset:51200
	ds_read_b128 v[224:227], v167 offset:52224
	ds_read_b128 v[228:231], v167 offset:53248
	ds_read_b128 v[232:235], v167 offset:54272
	ds_read_b128 v[236:239], v167 offset:55296
	ds_read_b128 v[240:243], v167 offset:56320
	global_load_lds_dwordx4 v[138:139], off
	s_add_i32 m0, s22, 0x2000
	s_add_u32 s2, s2, 0x40080
	v_lshl_add_u64 v[138:139], v[164:165], 0, s[24:25]
	s_addc_u32 s3, s3, 0
	s_add_i32 s22, s75, s46
	global_load_lds_dwordx4 v[138:139], off
	v_lshl_add_u64 v[138:139], s[2:3], 0, v[142:143]
	s_mov_b32 m0, s22
	s_nop 0
	global_load_lds_dwordx4 v[138:139], off
	v_lshl_add_u64 v[138:139], s[2:3], 0, v[146:147]
	s_add_i32 m0, s22, 0x2000
	s_nop 0
	global_load_lds_dwordx4 v[138:139], off
	v_lshl_add_u64 v[138:139], v[192:193], 0, s[24:25]
	s_mov_b32 m0, s54
	s_nop 0
	global_load_lds_dwordx4 v[138:139], off
	v_lshl_add_u64 v[138:139], v[244:245], 0, s[24:25]
	s_mov_b32 m0, s55
	s_nop 0
	global_load_lds_dwordx4 v[138:139], off
	s_waitcnt vmcnt(8)
	s_waitcnt lgkmcnt(0)
	s_barrier
	s_setprio 1
	v_mfma_f32_16x16x32_bf16 v[60:63], v[156:159], v[212:215], v[60:63]
	v_mfma_f32_16x16x32_bf16 v[56:59], v[184:187], v[212:215], v[56:59]
	v_mfma_f32_16x16x32_bf16 v[44:47], v[156:159], v[220:223], v[44:47]
	v_mfma_f32_16x16x32_bf16 v[40:43], v[184:187], v[220:223], v[40:43]
	v_mfma_f32_16x16x32_bf16 v[28:31], v[156:159], v[228:231], v[28:31]
	v_mfma_f32_16x16x32_bf16 v[24:27], v[184:187], v[228:231], v[24:27]
	v_mfma_f32_16x16x32_bf16 v[12:15], v[156:159], v[236:239], v[12:15]
	v_mfma_f32_16x16x32_bf16 v[8:11], v[184:187], v[236:239], v[8:11]
	v_mfma_f32_16x16x32_bf16 v[60:63], v[160:163], v[216:219], v[60:63]
	v_mfma_f32_16x16x32_bf16 v[56:59], v[188:191], v[216:219], v[56:59]
	v_mfma_f32_16x16x32_bf16 v[44:47], v[160:163], v[224:227], v[44:47]
	v_mfma_f32_16x16x32_bf16 v[40:43], v[188:191], v[224:227], v[40:43]
	v_mfma_f32_16x16x32_bf16 v[28:31], v[160:163], v[232:235], v[28:31]
	v_mfma_f32_16x16x32_bf16 v[24:27], v[188:191], v[232:235], v[24:27]
	v_mfma_f32_16x16x32_bf16 v[12:15], v[160:163], v[240:243], v[12:15]
	v_mfma_f32_16x16x32_bf16 v[8:11], v[188:191], v[240:243], v[8:11]
	v_mfma_f32_16x16x32_bf16 v[52:55], v[196:199], v[212:215], v[52:55]
	v_mfma_f32_16x16x32_bf16 v[48:51], v[204:207], v[212:215], v[48:51]
	v_mfma_f32_16x16x32_bf16 v[36:39], v[196:199], v[220:223], v[36:39]
	v_mfma_f32_16x16x32_bf16 v[32:35], v[204:207], v[220:223], v[32:35]
	v_mfma_f32_16x16x32_bf16 v[20:23], v[196:199], v[228:231], v[20:23]
	v_mfma_f32_16x16x32_bf16 v[16:19], v[204:207], v[228:231], v[16:19]
	v_mfma_f32_16x16x32_bf16 v[4:7], v[196:199], v[236:239], v[4:7]
	v_mfma_f32_16x16x32_bf16 v[0:3], v[204:207], v[236:239], v[0:3]
	v_mfma_f32_16x16x32_bf16 v[52:55], v[200:203], v[216:219], v[52:55]
	v_mfma_f32_16x16x32_bf16 v[48:51], v[208:211], v[216:219], v[48:51]
	v_mfma_f32_16x16x32_bf16 v[36:39], v[200:203], v[224:227], v[36:39]
	v_mfma_f32_16x16x32_bf16 v[32:35], v[208:211], v[224:227], v[32:35]
	v_mfma_f32_16x16x32_bf16 v[20:23], v[200:203], v[232:235], v[20:23]
	v_mfma_f32_16x16x32_bf16 v[16:19], v[208:211], v[232:235], v[16:19]
	v_mfma_f32_16x16x32_bf16 v[4:7], v[200:203], v[240:243], v[4:7]
	v_mfma_f32_16x16x32_bf16 v[0:3], v[208:211], v[240:243], v[0:3]
	s_barrier
	s_setprio 0
	s_add_i32 s73, s73, 2
	s_add_u32 s14, s14, 0x100
	s_addc_u32 s15, s15, 0
	s_add_u32 s71, s71, 0x100
	s_addc_u32 s72, s72, 0
	s_cmp_gt_u32 s73, 13
	s_cbranch_scc1 .Lgemm_kdone_3
.LBB0_552:
	ds_read_b128 v[156:159], v155
	ds_read_b128 v[160:163], v155 offset:1024
	ds_read_b128 v[184:187], v155 offset:2048
	ds_read_b128 v[188:191], v155 offset:3072
	ds_read_b128 v[196:199], v166
	ds_read_b128 v[200:203], v166 offset:1024
	ds_read_b128 v[204:207], v166 offset:2048
	ds_read_b128 v[208:211], v166 offset:3072
	s_add_u32 s2, s14, 0xfffc0080
	s_addc_u32 s3, s15, -1
	s_cmp_eq_u32 s73, 12
	s_cselect_b32 s23, s41, s3
	s_cselect_b32 s22, s69, s2
	s_cselect_b32 s3, s39, s72
	s_cselect_b32 s2, s70, s71
	v_lshl_add_u64 v[138:139], s[14:15], 0, v[130:131]
	s_add_i32 m0, s49, 0xc000
	ds_read_b128 v[212:215], v167
	ds_read_b128 v[216:219], v167 offset:1024
	ds_read_b128 v[220:223], v167 offset:2048
	ds_read_b128 v[224:227], v167 offset:3072
	ds_read_b128 v[228:231], v167 offset:4096
	ds_read_b128 v[232:235], v167 offset:5120
	ds_read_b128 v[236:239], v167 offset:6144
	ds_read_b128 v[240:243], v167 offset:7168
	global_load_lds_dwordx4 v[138:139], off
	v_lshl_add_u64 v[138:139], s[14:15], 0, v[132:133]
	s_add_i32 m0, s49, 0xe000
	s_nop 0
	global_load_lds_dwordx4 v[138:139], off
	s_waitcnt vmcnt(8)
	s_waitcnt lgkmcnt(0)
	s_barrier
	s_setprio 1
	v_mfma_f32_16x16x32_bf16 v[124:127], v[156:159], v[212:215], v[124:127]
	v_mfma_f32_16x16x32_bf16 v[120:123], v[184:187], v[212:215], v[120:123]
	v_mfma_f32_16x16x32_bf16 v[116:119], v[156:159], v[220:223], v[116:119]
	v_mfma_f32_16x16x32_bf16 v[112:115], v[184:187], v[220:223], v[112:115]
	v_mfma_f32_16x16x32_bf16 v[92:95], v[156:159], v[228:231], v[92:95]
	v_mfma_f32_16x16x32_bf16 v[88:91], v[184:187], v[228:231], v[88:91]
	v_mfma_f32_16x16x32_bf16 v[76:79], v[156:159], v[236:239], v[76:79]
	v_mfma_f32_16x16x32_bf16 v[72:75], v[184:187], v[236:239], v[72:75]
	v_mfma_f32_16x16x32_bf16 v[124:127], v[160:163], v[216:219], v[124:127]
	v_mfma_f32_16x16x32_bf16 v[120:123], v[188:191], v[216:219], v[120:123]
	v_mfma_f32_16x16x32_bf16 v[116:119], v[160:163], v[224:227], v[116:119]
	v_mfma_f32_16x16x32_bf16 v[112:115], v[188:191], v[224:227], v[112:115]
	v_mfma_f32_16x16x32_bf16 v[92:95], v[160:163], v[232:235], v[92:95]
	v_mfma_f32_16x16x32_bf16 v[88:91], v[188:191], v[232:235], v[88:91]
	v_mfma_f32_16x16x32_bf16 v[76:79], v[160:163], v[240:243], v[76:79]
	v_mfma_f32_16x16x32_bf16 v[72:75], v[188:191], v[240:243], v[72:75]
	v_mfma_f32_16x16x32_bf16 v[108:111], v[196:199], v[212:215], v[108:111]
	v_mfma_f32_16x16x32_bf16 v[104:107], v[204:207], v[212:215], v[104:107]
	v_mfma_f32_16x16x32_bf16 v[100:103], v[196:199], v[220:223], v[100:103]
	v_mfma_f32_16x16x32_bf16 v[96:99], v[204:207], v[220:223], v[96:99]
	v_mfma_f32_16x16x32_bf16 v[84:87], v[196:199], v[228:231], v[84:87]
	v_mfma_f32_16x16x32_bf16 v[80:83], v[204:207], v[228:231], v[80:83]
	v_mfma_f32_16x16x32_bf16 v[68:71], v[196:199], v[236:239], v[68:71]
	v_mfma_f32_16x16x32_bf16 v[64:67], v[204:207], v[236:239], v[64:67]
	v_mfma_f32_16x16x32_bf16 v[108:111], v[200:203], v[216:219], v[108:111]
	v_mfma_f32_16x16x32_bf16 v[104:107], v[208:211], v[216:219], v[104:107]
	v_mfma_f32_16x16x32_bf16 v[100:103], v[200:203], v[224:227], v[100:103]
	v_mfma_f32_16x16x32_bf16 v[96:99], v[208:211], v[224:227], v[96:99]
	v_mfma_f32_16x16x32_bf16 v[84:87], v[200:203], v[232:235], v[84:87]
	v_mfma_f32_16x16x32_bf16 v[80:83], v[208:211], v[232:235], v[80:83]
	v_mfma_f32_16x16x32_bf16 v[68:71], v[200:203], v[240:243], v[68:71]
	v_mfma_f32_16x16x32_bf16 v[64:67], v[208:211], v[240:243], v[64:67]
	s_barrier
	s_setprio 0
	s_add_i32 s74, s58, s46
	v_lshl_add_u64 v[138:139], s[2:3], 0, v[142:143]
	s_mov_b32 m0, s74
	ds_read_b128 v[212:215], v167 offset:16384
	ds_read_b128 v[216:219], v167 offset:17408
	ds_read_b128 v[220:223], v167 offset:18432
	ds_read_b128 v[224:227], v167 offset:19456
	ds_read_b128 v[228:231], v167 offset:20480
	ds_read_b128 v[232:235], v167 offset:21504
	ds_read_b128 v[236:239], v167 offset:22528
	ds_read_b128 v[240:243], v167 offset:23552
	global_load_lds_dwordx4 v[138:139], off
	s_add_i32 m0, s74, 0x2000
	s_add_u32 s74, s2, 0x40000
	v_lshl_add_u64 v[164:165], s[2:3], 0, v[146:147]
	s_addc_u32 s75, s3, 0
	s_add_i32 s76, s59, s46
	global_load_lds_dwordx4 v[164:165], off
	v_lshl_add_u64 v[192:193], s[74:75], 0, v[142:143]
	s_mov_b32 m0, s76
	v_lshl_add_u64 v[244:245], s[22:23], 0, v[144:145]
	global_load_lds_dwordx4 v[192:193], off
	v_lshl_add_u64 v[192:193], s[74:75], 0, v[146:147]
	s_add_i32 m0, s76, 0x2000
	s_nop 0
	global_load_lds_dwordx4 v[192:193], off
	v_lshl_add_u64 v[192:193], s[22:23], 0, v[140:141]
	s_mov_b32 m0, s49
	s_nop 0
	global_load_lds_dwordx4 v[192:193], off
	s_mov_b32 m0, s50
	s_nop 0
	global_load_lds_dwordx4 v[244:245], off
	s_waitcnt vmcnt(8)
	s_waitcnt lgkmcnt(0)
	s_barrier
	s_setprio 1
	v_mfma_f32_16x16x32_bf16 v[60:63], v[156:159], v[212:215], v[60:63]
	v_mfma_f32_16x16x32_bf16 v[56:59], v[184:187], v[212:215], v[56:59]
	v_mfma_f32_16x16x32_bf16 v[44:47], v[156:159], v[220:223], v[44:47]
	v_mfma_f32_16x16x32_bf16 v[40:43], v[184:187], v[220:223], v[40:43]
	v_mfma_f32_16x16x32_bf16 v[28:31], v[156:159], v[228:231], v[28:31]
	v_mfma_f32_16x16x32_bf16 v[24:27], v[184:187], v[228:231], v[24:27]
	v_mfma_f32_16x16x32_bf16 v[12:15], v[156:159], v[236:239], v[12:15]
	v_mfma_f32_16x16x32_bf16 v[8:11], v[184:187], v[236:239], v[8:11]
	v_mfma_f32_16x16x32_bf16 v[60:63], v[160:163], v[216:219], v[60:63]
	v_mfma_f32_16x16x32_bf16 v[56:59], v[188:191], v[216:219], v[56:59]
	v_mfma_f32_16x16x32_bf16 v[44:47], v[160:163], v[224:227], v[44:47]
	v_mfma_f32_16x16x32_bf16 v[40:43], v[188:191], v[224:227], v[40:43]
	v_mfma_f32_16x16x32_bf16 v[28:31], v[160:163], v[232:235], v[28:31]
	v_mfma_f32_16x16x32_bf16 v[24:27], v[188:191], v[232:235], v[24:27]
	v_mfma_f32_16x16x32_bf16 v[12:15], v[160:163], v[240:243], v[12:15]
	v_mfma_f32_16x16x32_bf16 v[8:11], v[188:191], v[240:243], v[8:11]
	v_mfma_f32_16x16x32_bf16 v[52:55], v[196:199], v[212:215], v[52:55]
	v_mfma_f32_16x16x32_bf16 v[48:51], v[204:207], v[212:215], v[48:51]
	v_mfma_f32_16x16x32_bf16 v[36:39], v[196:199], v[220:223], v[36:39]
	v_mfma_f32_16x16x32_bf16 v[32:35], v[204:207], v[220:223], v[32:35]
	v_mfma_f32_16x16x32_bf16 v[20:23], v[196:199], v[228:231], v[20:23]
	v_mfma_f32_16x16x32_bf16 v[16:19], v[204:207], v[228:231], v[16:19]
	v_mfma_f32_16x16x32_bf16 v[4:7], v[196:199], v[236:239], v[4:7]
	v_mfma_f32_16x16x32_bf16 v[0:3], v[204:207], v[236:239], v[0:3]
	v_mfma_f32_16x16x32_bf16 v[52:55], v[200:203], v[216:219], v[52:55]
	v_mfma_f32_16x16x32_bf16 v[48:51], v[208:211], v[216:219], v[48:51]
	v_mfma_f32_16x16x32_bf16 v[36:39], v[200:203], v[224:227], v[36:39]
	v_mfma_f32_16x16x32_bf16 v[32:35], v[208:211], v[224:227], v[32:35]
	v_mfma_f32_16x16x32_bf16 v[20:23], v[200:203], v[232:235], v[20:23]
	v_mfma_f32_16x16x32_bf16 v[16:19], v[208:211], v[232:235], v[16:19]
	v_mfma_f32_16x16x32_bf16 v[4:7], v[200:203], v[240:243], v[4:7]
	v_mfma_f32_16x16x32_bf16 v[0:3], v[208:211], v[240:243], v[0:3]
	s_barrier
	s_setprio 0
	s_add_i32 s74, 0, 0x18000
	v_add_u32_e32 v128, s74, v151
	s_add_i32 s75, 0, 0x1c000
	ds_read_b128 v[156:159], v128
	ds_read_b128 v[160:163], v128 offset:1024
	ds_read_b128 v[184:187], v128 offset:2048
	ds_read_b128 v[188:191], v128 offset:3072
	v_add_u32_e32 v128, s75, v151
	ds_read_b128 v[196:199], v128
	ds_read_b128 v[200:203], v128 offset:1024
	ds_read_b128 v[204:207], v128 offset:2048
	ds_read_b128 v[208:211], v128 offset:3072
	s_add_u32 s22, s22, 0x40000
	s_addc_u32 s23, s23, 0
	s_mov_b32 m0, s51
	v_lshl_add_u64 v[246:247], s[22:23], 0, v[140:141]
	ds_read_b128 v[212:215], v167 offset:32768
	ds_read_b128 v[216:219], v167 offset:33792
	ds_read_b128 v[220:223], v167 offset:34816
	ds_read_b128 v[224:227], v167 offset:35840
	ds_read_b128 v[228:231], v167 offset:36864
	ds_read_b128 v[232:235], v167 offset:37888
	ds_read_b128 v[236:239], v167 offset:38912
	ds_read_b128 v[240:243], v167 offset:39936
	global_load_lds_dwordx4 v[246:247], off
	v_lshl_add_u64 v[246:247], s[22:23], 0, v[144:145]
	s_mov_b32 m0, s52
	s_nop 0
	global_load_lds_dwordx4 v[246:247], off
	s_waitcnt vmcnt(8)
	s_waitcnt lgkmcnt(0)
	s_barrier
	s_setprio 1
	v_mfma_f32_16x16x32_bf16 v[124:127], v[156:159], v[212:215], v[124:127]
	v_mfma_f32_16x16x32_bf16 v[120:123], v[184:187], v[212:215], v[120:123]
	v_mfma_f32_16x16x32_bf16 v[116:119], v[156:159], v[220:223], v[116:119]
	v_mfma_f32_16x16x32_bf16 v[112:115], v[184:187], v[220:223], v[112:115]
	v_mfma_f32_16x16x32_bf16 v[92:95], v[156:159], v[228:231], v[92:95]
	v_mfma_f32_16x16x32_bf16 v[88:91], v[184:187], v[228:231], v[88:91]
	v_mfma_f32_16x16x32_bf16 v[76:79], v[156:159], v[236:239], v[76:79]
	v_mfma_f32_16x16x32_bf16 v[72:75], v[184:187], v[236:239], v[72:75]
	v_mfma_f32_16x16x32_bf16 v[124:127], v[160:163], v[216:219], v[124:127]
	v_mfma_f32_16x16x32_bf16 v[120:123], v[188:191], v[216:219], v[120:123]
	v_mfma_f32_16x16x32_bf16 v[116:119], v[160:163], v[224:227], v[116:119]
	v_mfma_f32_16x16x32_bf16 v[112:115], v[188:191], v[224:227], v[112:115]
	v_mfma_f32_16x16x32_bf16 v[92:95], v[160:163], v[232:235], v[92:95]
	v_mfma_f32_16x16x32_bf16 v[88:91], v[188:191], v[232:235], v[88:91]
	v_mfma_f32_16x16x32_bf16 v[76:79], v[160:163], v[240:243], v[76:79]
	v_mfma_f32_16x16x32_bf16 v[72:75], v[188:191], v[240:243], v[72:75]
	v_mfma_f32_16x16x32_bf16 v[108:111], v[196:199], v[212:215], v[108:111]
	v_mfma_f32_16x16x32_bf16 v[104:107], v[204:207], v[212:215], v[104:107]
	v_mfma_f32_16x16x32_bf16 v[100:103], v[196:199], v[220:223], v[100:103]
	v_mfma_f32_16x16x32_bf16 v[96:99], v[204:207], v[220:223], v[96:99]
	v_mfma_f32_16x16x32_bf16 v[84:87], v[196:199], v[228:231], v[84:87]
	v_mfma_f32_16x16x32_bf16 v[80:83], v[204:207], v[228:231], v[80:83]
	v_mfma_f32_16x16x32_bf16 v[68:71], v[196:199], v[236:239], v[68:71]
	v_mfma_f32_16x16x32_bf16 v[64:67], v[204:207], v[236:239], v[64:67]
	v_mfma_f32_16x16x32_bf16 v[108:111], v[200:203], v[216:219], v[108:111]
	v_mfma_f32_16x16x32_bf16 v[104:107], v[208:211], v[216:219], v[104:107]
	v_mfma_f32_16x16x32_bf16 v[100:103], v[200:203], v[224:227], v[100:103]
	v_mfma_f32_16x16x32_bf16 v[96:99], v[208:211], v[224:227], v[96:99]
	v_mfma_f32_16x16x32_bf16 v[84:87], v[200:203], v[232:235], v[84:87]
	v_mfma_f32_16x16x32_bf16 v[80:83], v[208:211], v[232:235], v[80:83]
	v_mfma_f32_16x16x32_bf16 v[68:71], v[200:203], v[240:243], v[68:71]
	v_mfma_f32_16x16x32_bf16 v[64:67], v[208:211], v[240:243], v[64:67]
	s_barrier
	s_setprio 0
	s_add_i32 s22, s74, s46
	v_lshl_add_u64 v[138:139], v[138:139], 0, s[24:25]
	s_mov_b32 m0, s22
	ds_read_b128 v[212:215], v167 offset:49152
	ds_read_b128 v[216:219], v167 offset:50176
	ds_read_b128 v[220:223], v167 offset:51200
	ds_read_b128 v[224:227], v167 offset:52224
	ds_read_b128 v[228:231], v167 offset:53248
	ds_read_b128 v[232:235], v167 offset:54272
	ds_read_b128 v[236:239], v167 offset:55296
	ds_read_b128 v[240:243], v167 offset:56320
	global_load_lds_dwordx4 v[138:139], off
	s_add_i32 m0, s22, 0x2000
	s_add_u32 s2, s2, 0x40080
	v_lshl_add_u64 v[138:139], v[164:165], 0, s[24:25]
	s_addc_u32 s3, s3, 0
	s_add_i32 s22, s75, s46
	global_load_lds_dwordx4 v[138:139], off
	v_lshl_add_u64 v[138:139], s[2:3], 0, v[142:143]
	s_mov_b32 m0, s22
	s_nop 0
	global_load_lds_dwordx4 v[138:139], off
	v_lshl_add_u64 v[138:139], s[2:3], 0, v[146:147]
	s_add_i32 m0, s22, 0x2000
	s_nop 0
	global_load_lds_dwordx4 v[138:139], off
	v_lshl_add_u64 v[138:139], v[192:193], 0, s[24:25]
	s_mov_b32 m0, s54
	s_nop 0
	global_load_lds_dwordx4 v[138:139], off
	v_lshl_add_u64 v[138:139], v[244:245], 0, s[24:25]
	s_mov_b32 m0, s55
	s_nop 0
	global_load_lds_dwordx4 v[138:139], off
	s_waitcnt vmcnt(8)
	s_waitcnt lgkmcnt(0)
	s_barrier
	s_setprio 1
	v_mfma_f32_16x16x32_bf16 v[60:63], v[156:159], v[212:215], v[60:63]
	v_mfma_f32_16x16x32_bf16 v[56:59], v[184:187], v[212:215], v[56:59]
	v_mfma_f32_16x16x32_bf16 v[44:47], v[156:159], v[220:223], v[44:47]
	v_mfma_f32_16x16x32_bf16 v[40:43], v[184:187], v[220:223], v[40:43]
	v_mfma_f32_16x16x32_bf16 v[28:31], v[156:159], v[228:231], v[28:31]
	v_mfma_f32_16x16x32_bf16 v[24:27], v[184:187], v[228:231], v[24:27]
	v_mfma_f32_16x16x32_bf16 v[12:15], v[156:159], v[236:239], v[12:15]
	v_mfma_f32_16x16x32_bf16 v[8:11], v[184:187], v[236:239], v[8:11]
	v_mfma_f32_16x16x32_bf16 v[60:63], v[160:163], v[216:219], v[60:63]
	v_mfma_f32_16x16x32_bf16 v[56:59], v[188:191], v[216:219], v[56:59]
	v_mfma_f32_16x16x32_bf16 v[44:47], v[160:163], v[224:227], v[44:47]
	v_mfma_f32_16x16x32_bf16 v[40:43], v[188:191], v[224:227], v[40:43]
	v_mfma_f32_16x16x32_bf16 v[28:31], v[160:163], v[232:235], v[28:31]
	v_mfma_f32_16x16x32_bf16 v[24:27], v[188:191], v[232:235], v[24:27]
	v_mfma_f32_16x16x32_bf16 v[12:15], v[160:163], v[240:243], v[12:15]
	v_mfma_f32_16x16x32_bf16 v[8:11], v[188:191], v[240:243], v[8:11]
	v_mfma_f32_16x16x32_bf16 v[52:55], v[196:199], v[212:215], v[52:55]
	v_mfma_f32_16x16x32_bf16 v[48:51], v[204:207], v[212:215], v[48:51]
	v_mfma_f32_16x16x32_bf16 v[36:39], v[196:199], v[220:223], v[36:39]
	v_mfma_f32_16x16x32_bf16 v[32:35], v[204:207], v[220:223], v[32:35]
	v_mfma_f32_16x16x32_bf16 v[20:23], v[196:199], v[228:231], v[20:23]
	v_mfma_f32_16x16x32_bf16 v[16:19], v[204:207], v[228:231], v[16:19]
	v_mfma_f32_16x16x32_bf16 v[4:7], v[196:199], v[236:239], v[4:7]
	v_mfma_f32_16x16x32_bf16 v[0:3], v[204:207], v[236:239], v[0:3]
	v_mfma_f32_16x16x32_bf16 v[52:55], v[200:203], v[216:219], v[52:55]
	v_mfma_f32_16x16x32_bf16 v[48:51], v[208:211], v[216:219], v[48:51]
	v_mfma_f32_16x16x32_bf16 v[36:39], v[200:203], v[224:227], v[36:39]
	v_mfma_f32_16x16x32_bf16 v[32:35], v[208:211], v[224:227], v[32:35]
	v_mfma_f32_16x16x32_bf16 v[20:23], v[200:203], v[232:235], v[20:23]
	v_mfma_f32_16x16x32_bf16 v[16:19], v[208:211], v[232:235], v[16:19]
	v_mfma_f32_16x16x32_bf16 v[4:7], v[200:203], v[240:243], v[4:7]
	v_mfma_f32_16x16x32_bf16 v[0:3], v[208:211], v[240:243], v[0:3]
	s_barrier
	s_setprio 0
	s_add_i32 s73, s73, 2
	s_add_u32 s14, s14, 0x100
	s_addc_u32 s15, s15, 0
	s_add_u32 s71, s71, 0x100
	s_addc_u32 s72, s72, 0
	s_cmp_gt_u32 s73, 13
	s_cbranch_scc0 .LBB0_552

.LBB0_724:
	s_ashr_i32 s27, s26, 31
	s_lshl_b64 s[22:23], s[26:27], 19
	s_add_u32 s28, s16, s22
	s_addc_u32 s29, s17, s23
	s_and_b64 s[22:23], s[6:7], exec
	s_cselect_b32 s27, s29, s15
	s_cselect_b32 s59, s28, s14
	s_ashr_i32 s25, s24, 31
	s_lshl_b64 s[22:23], s[24:25], 19
	s_add_u32 s30, s35, s22
	s_addc_u32 s31, s38, s23
	s_and_b64 s[22:23], s[6:7], exec
	s_cselect_b32 s25, s31, s3
	s_cselect_b32 s64, s30, s2
	s_add_u32 s14, s14, 0x40080
	s_addc_u32 s15, s15, 0
	s_add_u32 s65, s2, 0x100
	s_addc_u32 s66, s3, 0
	s_mov_b32 s67, -2
	s_waitcnt lgkmcnt(0)
	s_waitcnt vmcnt(0)
	ds_read_b128 v[128:131], v155
	ds_read_b128 v[132:135], v155 offset:1024
	ds_read_b128 v[136:139], v155 offset:2048
	ds_read_b128 v[164:167], v155 offset:3072
	ds_read_b128 v[188:191], v184
	ds_read_b128 v[196:199], v184 offset:1024
	ds_read_b128 v[200:203], v184 offset:2048
	ds_read_b128 v[204:207], v184 offset:3072
	s_add_u32 s2, s14, 0xfffc0080
	s_addc_u32 s3, s15, -1
	s_cmp_eq_u32 s67, 12
	s_cselect_b32 s23, s27, s3
	s_cselect_b32 s22, s59, s2
	s_cselect_b32 s3, s25, s66
	s_cselect_b32 s2, s64, s65
	v_lshl_add_u64 v[168:169], s[14:15], 0, v[156:157]
	s_add_i32 m0, s37, 0xc000
	ds_read_b128 v[208:211], v185
	ds_read_b128 v[212:215], v185 offset:1024
	ds_read_b128 v[216:219], v185 offset:2048
	ds_read_b128 v[220:223], v185 offset:3072
	ds_read_b128 v[224:227], v185 offset:4096
	ds_read_b128 v[228:231], v185 offset:5120
	ds_read_b128 v[232:235], v185 offset:6144
	ds_read_b128 v[236:239], v185 offset:7168
	global_load_lds_dwordx4 v[168:169], off
	v_lshl_add_u64 v[168:169], s[14:15], 0, v[158:159]
	s_add_i32 m0, s37, 0xe000
	s_nop 0
	global_load_lds_dwordx4 v[168:169], off
	s_waitcnt vmcnt(8)
	s_waitcnt lgkmcnt(0)
	s_barrier
	s_setprio 1
	v_mfma_f32_16x16x32_bf16 v[124:127], v[128:131], v[208:211], 0
	v_mfma_f32_16x16x32_bf16 v[120:123], v[136:139], v[208:211], 0
	v_mfma_f32_16x16x32_bf16 v[108:111], v[128:131], v[216:219], 0
	v_mfma_f32_16x16x32_bf16 v[104:107], v[136:139], v[216:219], 0
	v_mfma_f32_16x16x32_bf16 v[92:95], v[128:131], v[224:227], 0
	v_mfma_f32_16x16x32_bf16 v[88:91], v[136:139], v[224:227], 0
	v_mfma_f32_16x16x32_bf16 v[76:79], v[128:131], v[232:235], 0
	v_mfma_f32_16x16x32_bf16 v[72:75], v[136:139], v[232:235], 0
	v_mfma_f32_16x16x32_bf16 v[124:127], v[132:135], v[212:215], v[124:127]
	v_mfma_f32_16x16x32_bf16 v[120:123], v[164:167], v[212:215], v[120:123]
	v_mfma_f32_16x16x32_bf16 v[108:111], v[132:135], v[220:223], v[108:111]
	v_mfma_f32_16x16x32_bf16 v[104:107], v[164:167], v[220:223], v[104:107]
	v_mfma_f32_16x16x32_bf16 v[92:95], v[132:135], v[228:231], v[92:95]
	v_mfma_f32_16x16x32_bf16 v[88:91], v[164:167], v[228:231], v[88:91]
	v_mfma_f32_16x16x32_bf16 v[76:79], v[132:135], v[236:239], v[76:79]
	v_mfma_f32_16x16x32_bf16 v[72:75], v[164:167], v[236:239], v[72:75]
	v_mfma_f32_16x16x32_bf16 v[116:119], v[188:191], v[208:211], 0
	v_mfma_f32_16x16x32_bf16 v[112:115], v[200:203], v[208:211], 0
	v_mfma_f32_16x16x32_bf16 v[100:103], v[188:191], v[216:219], 0
	v_mfma_f32_16x16x32_bf16 v[96:99], v[200:203], v[216:219], 0
	v_mfma_f32_16x16x32_bf16 v[84:87], v[188:191], v[224:227], 0
	v_mfma_f32_16x16x32_bf16 v[80:83], v[200:203], v[224:227], 0
	v_mfma_f32_16x16x32_bf16 v[68:71], v[188:191], v[232:235], 0
	v_mfma_f32_16x16x32_bf16 v[64:67], v[200:203], v[232:235], 0
	v_mfma_f32_16x16x32_bf16 v[116:119], v[196:199], v[212:215], v[116:119]
	v_mfma_f32_16x16x32_bf16 v[112:115], v[204:207], v[212:215], v[112:115]
	v_mfma_f32_16x16x32_bf16 v[100:103], v[196:199], v[220:223], v[100:103]
	v_mfma_f32_16x16x32_bf16 v[96:99], v[204:207], v[220:223], v[96:99]
	v_mfma_f32_16x16x32_bf16 v[84:87], v[196:199], v[228:231], v[84:87]
	v_mfma_f32_16x16x32_bf16 v[80:83], v[204:207], v[228:231], v[80:83]
	v_mfma_f32_16x16x32_bf16 v[68:71], v[196:199], v[236:239], v[68:71]
	v_mfma_f32_16x16x32_bf16 v[64:67], v[204:207], v[236:239], v[64:67]
	s_barrier
	s_setprio 0
	s_add_i32 s68, s52, s39
	v_lshl_add_u64 v[168:169], s[2:3], 0, v[142:143]
	s_mov_b32 m0, s68
	ds_read_b128 v[208:211], v185 offset:16384
	ds_read_b128 v[212:215], v185 offset:17408
	ds_read_b128 v[216:219], v185 offset:18432
	ds_read_b128 v[220:223], v185 offset:19456
	ds_read_b128 v[224:227], v185 offset:20480
	ds_read_b128 v[228:231], v185 offset:21504
	ds_read_b128 v[232:235], v185 offset:22528
	ds_read_b128 v[236:239], v185 offset:23552
	global_load_lds_dwordx4 v[168:169], off
	s_add_i32 m0, s68, 0x2000
	s_add_u32 s68, s2, 0x40000
	v_lshl_add_u64 v[192:193], s[2:3], 0, v[146:147]
	s_addc_u32 s69, s3, 0
	s_add_i32 s70, s53, s39
	global_load_lds_dwordx4 v[192:193], off
	v_lshl_add_u64 v[240:241], s[68:69], 0, v[142:143]
	s_mov_b32 m0, s70
	v_lshl_add_u64 v[242:243], s[22:23], 0, v[144:145]
	global_load_lds_dwordx4 v[240:241], off
	v_lshl_add_u64 v[240:241], s[68:69], 0, v[146:147]
	s_add_i32 m0, s70, 0x2000
	s_nop 0
	global_load_lds_dwordx4 v[240:241], off
	v_lshl_add_u64 v[240:241], s[22:23], 0, v[140:141]
	s_mov_b32 m0, s37
	s_nop 0
	global_load_lds_dwordx4 v[240:241], off
	s_mov_b32 m0, s40
	s_nop 0
	global_load_lds_dwordx4 v[242:243], off
	s_waitcnt vmcnt(8)
	s_waitcnt lgkmcnt(0)
	s_barrier
	s_setprio 1
	v_mfma_f32_16x16x32_bf16 v[60:63], v[128:131], v[208:211], 0
	v_mfma_f32_16x16x32_bf16 v[56:59], v[136:139], v[208:211], 0
	v_mfma_f32_16x16x32_bf16 v[44:47], v[128:131], v[216:219], 0
	v_mfma_f32_16x16x32_bf16 v[40:43], v[136:139], v[216:219], 0
	v_mfma_f32_16x16x32_bf16 v[28:31], v[128:131], v[224:227], 0
	v_mfma_f32_16x16x32_bf16 v[24:27], v[136:139], v[224:227], 0
	v_mfma_f32_16x16x32_bf16 v[12:15], v[128:131], v[232:235], 0
	v_mfma_f32_16x16x32_bf16 v[8:11], v[136:139], v[232:235], 0
	v_mfma_f32_16x16x32_bf16 v[60:63], v[132:135], v[212:215], v[60:63]
	v_mfma_f32_16x16x32_bf16 v[56:59], v[164:167], v[212:215], v[56:59]
	v_mfma_f32_16x16x32_bf16 v[44:47], v[132:135], v[220:223], v[44:47]
	v_mfma_f32_16x16x32_bf16 v[40:43], v[164:167], v[220:223], v[40:43]
	v_mfma_f32_16x16x32_bf16 v[28:31], v[132:135], v[228:231], v[28:31]
	v_mfma_f32_16x16x32_bf16 v[24:27], v[164:167], v[228:231], v[24:27]
	v_mfma_f32_16x16x32_bf16 v[12:15], v[132:135], v[236:239], v[12:15]
	v_mfma_f32_16x16x32_bf16 v[8:11], v[164:167], v[236:239], v[8:11]
	v_mfma_f32_16x16x32_bf16 v[52:55], v[188:191], v[208:211], 0
	v_mfma_f32_16x16x32_bf16 v[48:51], v[200:203], v[208:211], 0
	v_mfma_f32_16x16x32_bf16 v[36:39], v[188:191], v[216:219], 0
	v_mfma_f32_16x16x32_bf16 v[32:35], v[200:203], v[216:219], 0
	v_mfma_f32_16x16x32_bf16 v[20:23], v[188:191], v[224:227], 0
	v_mfma_f32_16x16x32_bf16 v[16:19], v[200:203], v[224:227], 0
	v_mfma_f32_16x16x32_bf16 v[4:7], v[188:191], v[232:235], 0
	v_mfma_f32_16x16x32_bf16 v[0:3], v[200:203], v[232:235], 0
	v_mfma_f32_16x16x32_bf16 v[52:55], v[196:199], v[212:215], v[52:55]
	v_mfma_f32_16x16x32_bf16 v[48:51], v[204:207], v[212:215], v[48:51]
	v_mfma_f32_16x16x32_bf16 v[36:39], v[196:199], v[220:223], v[36:39]
	v_mfma_f32_16x16x32_bf16 v[32:35], v[204:207], v[220:223], v[32:35]
	v_mfma_f32_16x16x32_bf16 v[20:23], v[196:199], v[228:231], v[20:23]
	v_mfma_f32_16x16x32_bf16 v[16:19], v[204:207], v[228:231], v[16:19]
	v_mfma_f32_16x16x32_bf16 v[4:7], v[196:199], v[236:239], v[4:7]
	v_mfma_f32_16x16x32_bf16 v[0:3], v[204:207], v[236:239], v[0:3]
	s_barrier
	s_setprio 0
	s_add_i32 s68, 0, 0x18000
	s_add_i32 s69, 0, 0x1c000
	v_add_u32_e32 v164, s68, v149
	v_add_u32_e32 v187, s69, v149
	ds_read_b128 v[128:131], v164
	ds_read_b128 v[132:135], v164 offset:1024
	ds_read_b128 v[136:139], v164 offset:2048
	ds_read_b128 v[164:167], v164 offset:3072
	ds_read_b128 v[188:191], v187
	ds_read_b128 v[196:199], v187 offset:1024
	ds_read_b128 v[200:203], v187 offset:2048
	ds_read_b128 v[204:207], v187 offset:3072
	s_add_u32 s22, s22, 0x40000
	s_addc_u32 s23, s23, 0
	s_mov_b32 m0, s41
	v_lshl_add_u64 v[244:245], s[22:23], 0, v[140:141]
	ds_read_b128 v[208:211], v185 offset:32768
	ds_read_b128 v[212:215], v185 offset:33792
	ds_read_b128 v[216:219], v185 offset:34816
	ds_read_b128 v[220:223], v185 offset:35840
	ds_read_b128 v[224:227], v185 offset:36864
	ds_read_b128 v[228:231], v185 offset:37888
	ds_read_b128 v[232:235], v185 offset:38912
	ds_read_b128 v[236:239], v185 offset:39936
	global_load_lds_dwordx4 v[244:245], off
	v_lshl_add_u64 v[244:245], s[22:23], 0, v[144:145]
	s_mov_b32 m0, s42
	s_nop 0
	global_load_lds_dwordx4 v[244:245], off
	s_waitcnt vmcnt(8)
	s_waitcnt lgkmcnt(0)
	s_barrier
	s_setprio 1
	v_mfma_f32_16x16x32_bf16 v[124:127], v[128:131], v[208:211], v[124:127]
	v_mfma_f32_16x16x32_bf16 v[120:123], v[136:139], v[208:211], v[120:123]
	v_mfma_f32_16x16x32_bf16 v[108:111], v[128:131], v[216:219], v[108:111]
	v_mfma_f32_16x16x32_bf16 v[104:107], v[136:139], v[216:219], v[104:107]
	v_mfma_f32_16x16x32_bf16 v[92:95], v[128:131], v[224:227], v[92:95]
	v_mfma_f32_16x16x32_bf16 v[88:91], v[136:139], v[224:227], v[88:91]
	v_mfma_f32_16x16x32_bf16 v[76:79], v[128:131], v[232:235], v[76:79]
	v_mfma_f32_16x16x32_bf16 v[72:75], v[136:139], v[232:235], v[72:75]
	v_mfma_f32_16x16x32_bf16 v[124:127], v[132:135], v[212:215], v[124:127]
	v_mfma_f32_16x16x32_bf16 v[120:123], v[164:167], v[212:215], v[120:123]
	v_mfma_f32_16x16x32_bf16 v[108:111], v[132:135], v[220:223], v[108:111]
	v_mfma_f32_16x16x32_bf16 v[104:107], v[164:167], v[220:223], v[104:107]
	v_mfma_f32_16x16x32_bf16 v[92:95], v[132:135], v[228:231], v[92:95]
	v_mfma_f32_16x16x32_bf16 v[88:91], v[164:167], v[228:231], v[88:91]
	v_mfma_f32_16x16x32_bf16 v[76:79], v[132:135], v[236:239], v[76:79]
	v_mfma_f32_16x16x32_bf16 v[72:75], v[164:167], v[236:239], v[72:75]
	v_mfma_f32_16x16x32_bf16 v[116:119], v[188:191], v[208:211], v[116:119]
	v_mfma_f32_16x16x32_bf16 v[112:115], v[200:203], v[208:211], v[112:115]
	v_mfma_f32_16x16x32_bf16 v[100:103], v[188:191], v[216:219], v[100:103]
	v_mfma_f32_16x16x32_bf16 v[96:99], v[200:203], v[216:219], v[96:99]
	v_mfma_f32_16x16x32_bf16 v[84:87], v[188:191], v[224:227], v[84:87]
	v_mfma_f32_16x16x32_bf16 v[80:83], v[200:203], v[224:227], v[80:83]
	v_mfma_f32_16x16x32_bf16 v[68:71], v[188:191], v[232:235], v[68:71]
	v_mfma_f32_16x16x32_bf16 v[64:67], v[200:203], v[232:235], v[64:67]
	v_mfma_f32_16x16x32_bf16 v[116:119], v[196:199], v[212:215], v[116:119]
	v_mfma_f32_16x16x32_bf16 v[112:115], v[204:207], v[212:215], v[112:115]
	v_mfma_f32_16x16x32_bf16 v[100:103], v[196:199], v[220:223], v[100:103]
	v_mfma_f32_16x16x32_bf16 v[96:99], v[204:207], v[220:223], v[96:99]
	v_mfma_f32_16x16x32_bf16 v[84:87], v[196:199], v[228:231], v[84:87]
	v_mfma_f32_16x16x32_bf16 v[80:83], v[204:207], v[228:231], v[80:83]
	v_mfma_f32_16x16x32_bf16 v[68:71], v[196:199], v[236:239], v[68:71]
	v_mfma_f32_16x16x32_bf16 v[64:67], v[204:207], v[236:239], v[64:67]
	s_barrier
	s_setprio 0
	s_add_i32 s22, s68, s39
	v_lshl_add_u64 v[168:169], v[168:169], 0, s[18:19]
	s_mov_b32 m0, s22
	ds_read_b128 v[208:211], v185 offset:49152
	ds_read_b128 v[212:215], v185 offset:50176
	ds_read_b128 v[216:219], v185 offset:51200
	ds_read_b128 v[220:223], v185 offset:52224
	ds_read_b128 v[224:227], v185 offset:53248
	ds_read_b128 v[228:231], v185 offset:54272
	ds_read_b128 v[232:235], v185 offset:55296
	ds_read_b128 v[236:239], v185 offset:56320
	global_load_lds_dwordx4 v[168:169], off
	s_add_i32 m0, s22, 0x2000
	s_add_u32 s2, s2, 0x40080
	v_lshl_add_u64 v[168:169], v[192:193], 0, s[18:19]
	s_addc_u32 s3, s3, 0
	s_add_i32 s22, s69, s39
	global_load_lds_dwordx4 v[168:169], off
	v_lshl_add_u64 v[168:169], s[2:3], 0, v[142:143]
	s_mov_b32 m0, s22
	s_nop 0
	global_load_lds_dwordx4 v[168:169], off
	v_lshl_add_u64 v[168:169], s[2:3], 0, v[146:147]
	s_add_i32 m0, s22, 0x2000
	s_nop 0
	global_load_lds_dwordx4 v[168:169], off
	v_lshl_add_u64 v[168:169], v[240:241], 0, s[18:19]
	s_mov_b32 m0, s46
	s_nop 0
	global_load_lds_dwordx4 v[168:169], off
	v_lshl_add_u64 v[168:169], v[242:243], 0, s[18:19]
	s_mov_b32 m0, s47
	s_nop 0
	global_load_lds_dwordx4 v[168:169], off
	s_waitcnt vmcnt(8)
	s_waitcnt lgkmcnt(0)
	s_barrier
	s_setprio 1
	v_mfma_f32_16x16x32_bf16 v[60:63], v[128:131], v[208:211], v[60:63]
	v_mfma_f32_16x16x32_bf16 v[56:59], v[136:139], v[208:211], v[56:59]
	v_mfma_f32_16x16x32_bf16 v[44:47], v[128:131], v[216:219], v[44:47]
	v_mfma_f32_16x16x32_bf16 v[40:43], v[136:139], v[216:219], v[40:43]
	v_mfma_f32_16x16x32_bf16 v[28:31], v[128:131], v[224:227], v[28:31]
	v_mfma_f32_16x16x32_bf16 v[24:27], v[136:139], v[224:227], v[24:27]
	v_mfma_f32_16x16x32_bf16 v[12:15], v[128:131], v[232:235], v[12:15]
	v_mfma_f32_16x16x32_bf16 v[8:11], v[136:139], v[232:235], v[8:11]
	v_mfma_f32_16x16x32_bf16 v[60:63], v[132:135], v[212:215], v[60:63]
	v_mfma_f32_16x16x32_bf16 v[56:59], v[164:167], v[212:215], v[56:59]
	v_mfma_f32_16x16x32_bf16 v[44:47], v[132:135], v[220:223], v[44:47]
	v_mfma_f32_16x16x32_bf16 v[40:43], v[164:167], v[220:223], v[40:43]
	v_mfma_f32_16x16x32_bf16 v[28:31], v[132:135], v[228:231], v[28:31]
	v_mfma_f32_16x16x32_bf16 v[24:27], v[164:167], v[228:231], v[24:27]
	v_mfma_f32_16x16x32_bf16 v[12:15], v[132:135], v[236:239], v[12:15]
	v_mfma_f32_16x16x32_bf16 v[8:11], v[164:167], v[236:239], v[8:11]
	v_mfma_f32_16x16x32_bf16 v[52:55], v[188:191], v[208:211], v[52:55]
	v_mfma_f32_16x16x32_bf16 v[48:51], v[200:203], v[208:211], v[48:51]
	v_mfma_f32_16x16x32_bf16 v[36:39], v[188:191], v[216:219], v[36:39]
	v_mfma_f32_16x16x32_bf16 v[32:35], v[200:203], v[216:219], v[32:35]
	v_mfma_f32_16x16x32_bf16 v[20:23], v[188:191], v[224:227], v[20:23]
	v_mfma_f32_16x16x32_bf16 v[16:19], v[200:203], v[224:227], v[16:19]
	v_mfma_f32_16x16x32_bf16 v[4:7], v[188:191], v[232:235], v[4:7]
	v_mfma_f32_16x16x32_bf16 v[0:3], v[200:203], v[232:235], v[0:3]
	v_mfma_f32_16x16x32_bf16 v[52:55], v[196:199], v[212:215], v[52:55]
	v_mfma_f32_16x16x32_bf16 v[48:51], v[204:207], v[212:215], v[48:51]
	v_mfma_f32_16x16x32_bf16 v[36:39], v[196:199], v[220:223], v[36:39]
	v_mfma_f32_16x16x32_bf16 v[32:35], v[204:207], v[220:223], v[32:35]
	v_mfma_f32_16x16x32_bf16 v[20:23], v[196:199], v[228:231], v[20:23]
	v_mfma_f32_16x16x32_bf16 v[16:19], v[204:207], v[228:231], v[16:19]
	v_mfma_f32_16x16x32_bf16 v[4:7], v[196:199], v[236:239], v[4:7]
	v_mfma_f32_16x16x32_bf16 v[0:3], v[204:207], v[236:239], v[0:3]
	s_barrier
	s_setprio 0
	s_add_i32 s67, s67, 2
	s_add_u32 s14, s14, 0x100
	s_addc_u32 s15, s15, 0
	s_add_u32 s65, s65, 0x100
	s_addc_u32 s66, s66, 0
	s_cmp_gt_u32 s67, 13
	s_cbranch_scc1 .Lgemm_kdone_4
.LBB0_725:
	ds_read_b128 v[128:131], v155
	ds_read_b128 v[132:135], v155 offset:1024
	ds_read_b128 v[136:139], v155 offset:2048
	ds_read_b128 v[164:167], v155 offset:3072
	ds_read_b128 v[188:191], v184
	ds_read_b128 v[196:199], v184 offset:1024
	ds_read_b128 v[200:203], v184 offset:2048
	ds_read_b128 v[204:207], v184 offset:3072
	s_add_u32 s2, s14, 0xfffc0080
	s_addc_u32 s3, s15, -1
	s_cmp_eq_u32 s67, 12
	s_cselect_b32 s23, s27, s3
	s_cselect_b32 s22, s59, s2
	s_cselect_b32 s3, s25, s66
	s_cselect_b32 s2, s64, s65
	v_lshl_add_u64 v[168:169], s[14:15], 0, v[156:157]
	s_add_i32 m0, s37, 0xc000
	ds_read_b128 v[208:211], v185
	ds_read_b128 v[212:215], v185 offset:1024
	ds_read_b128 v[216:219], v185 offset:2048
	ds_read_b128 v[220:223], v185 offset:3072
	ds_read_b128 v[224:227], v185 offset:4096
	ds_read_b128 v[228:231], v185 offset:5120
	ds_read_b128 v[232:235], v185 offset:6144
	ds_read_b128 v[236:239], v185 offset:7168
	global_load_lds_dwordx4 v[168:169], off
	v_lshl_add_u64 v[168:169], s[14:15], 0, v[158:159]
	s_add_i32 m0, s37, 0xe000
	s_nop 0
	global_load_lds_dwordx4 v[168:169], off
	s_waitcnt vmcnt(8)
	s_waitcnt lgkmcnt(0)
	s_barrier
	s_setprio 1
	v_mfma_f32_16x16x32_bf16 v[124:127], v[128:131], v[208:211], v[124:127]
	v_mfma_f32_16x16x32_bf16 v[120:123], v[136:139], v[208:211], v[120:123]
	v_mfma_f32_16x16x32_bf16 v[108:111], v[128:131], v[216:219], v[108:111]
	v_mfma_f32_16x16x32_bf16 v[104:107], v[136:139], v[216:219], v[104:107]
	v_mfma_f32_16x16x32_bf16 v[92:95], v[128:131], v[224:227], v[92:95]
	v_mfma_f32_16x16x32_bf16 v[88:91], v[136:139], v[224:227], v[88:91]
	v_mfma_f32_16x16x32_bf16 v[76:79], v[128:131], v[232:235], v[76:79]
	v_mfma_f32_16x16x32_bf16 v[72:75], v[136:139], v[232:235], v[72:75]
	v_mfma_f32_16x16x32_bf16 v[124:127], v[132:135], v[212:215], v[124:127]
	v_mfma_f32_16x16x32_bf16 v[120:123], v[164:167], v[212:215], v[120:123]
	v_mfma_f32_16x16x32_bf16 v[108:111], v[132:135], v[220:223], v[108:111]
	v_mfma_f32_16x16x32_bf16 v[104:107], v[164:167], v[220:223], v[104:107]
	v_mfma_f32_16x16x32_bf16 v[92:95], v[132:135], v[228:231], v[92:95]
	v_mfma_f32_16x16x32_bf16 v[88:91], v[164:167], v[228:231], v[88:91]
	v_mfma_f32_16x16x32_bf16 v[76:79], v[132:135], v[236:239], v[76:79]
	v_mfma_f32_16x16x32_bf16 v[72:75], v[164:167], v[236:239], v[72:75]
	v_mfma_f32_16x16x32_bf16 v[116:119], v[188:191], v[208:211], v[116:119]
	v_mfma_f32_16x16x32_bf16 v[112:115], v[200:203], v[208:211], v[112:115]
	v_mfma_f32_16x16x32_bf16 v[100:103], v[188:191], v[216:219], v[100:103]
	v_mfma_f32_16x16x32_bf16 v[96:99], v[200:203], v[216:219], v[96:99]
	v_mfma_f32_16x16x32_bf16 v[84:87], v[188:191], v[224:227], v[84:87]
	v_mfma_f32_16x16x32_bf16 v[80:83], v[200:203], v[224:227], v[80:83]
	v_mfma_f32_16x16x32_bf16 v[68:71], v[188:191], v[232:235], v[68:71]
	v_mfma_f32_16x16x32_bf16 v[64:67], v[200:203], v[232:235], v[64:67]
	v_mfma_f32_16x16x32_bf16 v[116:119], v[196:199], v[212:215], v[116:119]
	v_mfma_f32_16x16x32_bf16 v[112:115], v[204:207], v[212:215], v[112:115]
	v_mfma_f32_16x16x32_bf16 v[100:103], v[196:199], v[220:223], v[100:103]
	v_mfma_f32_16x16x32_bf16 v[96:99], v[204:207], v[220:223], v[96:99]
	v_mfma_f32_16x16x32_bf16 v[84:87], v[196:199], v[228:231], v[84:87]
	v_mfma_f32_16x16x32_bf16 v[80:83], v[204:207], v[228:231], v[80:83]
	v_mfma_f32_16x16x32_bf16 v[68:71], v[196:199], v[236:239], v[68:71]
	v_mfma_f32_16x16x32_bf16 v[64:67], v[204:207], v[236:239], v[64:67]
	s_barrier
	s_setprio 0
	s_add_i32 s68, s52, s39
	v_lshl_add_u64 v[168:169], s[2:3], 0, v[142:143]
	s_mov_b32 m0, s68
	ds_read_b128 v[208:211], v185 offset:16384
	ds_read_b128 v[212:215], v185 offset:17408
	ds_read_b128 v[216:219], v185 offset:18432
	ds_read_b128 v[220:223], v185 offset:19456
	ds_read_b128 v[224:227], v185 offset:20480
	ds_read_b128 v[228:231], v185 offset:21504
	ds_read_b128 v[232:235], v185 offset:22528
	ds_read_b128 v[236:239], v185 offset:23552
	global_load_lds_dwordx4 v[168:169], off
	s_add_i32 m0, s68, 0x2000
	s_add_u32 s68, s2, 0x40000
	v_lshl_add_u64 v[192:193], s[2:3], 0, v[146:147]
	s_addc_u32 s69, s3, 0
	s_add_i32 s70, s53, s39
	global_load_lds_dwordx4 v[192:193], off
	v_lshl_add_u64 v[240:241], s[68:69], 0, v[142:143]
	s_mov_b32 m0, s70
	v_lshl_add_u64 v[242:243], s[22:23], 0, v[144:145]
	global_load_lds_dwordx4 v[240:241], off
	v_lshl_add_u64 v[240:241], s[68:69], 0, v[146:147]
	s_add_i32 m0, s70, 0x2000
	s_nop 0
	global_load_lds_dwordx4 v[240:241], off
	v_lshl_add_u64 v[240:241], s[22:23], 0, v[140:141]
	s_mov_b32 m0, s37
	s_nop 0
	global_load_lds_dwordx4 v[240:241], off
	s_mov_b32 m0, s40
	s_nop 0
	global_load_lds_dwordx4 v[242:243], off
	s_waitcnt vmcnt(8)
	s_waitcnt lgkmcnt(0)
	s_barrier
	s_setprio 1
	v_mfma_f32_16x16x32_bf16 v[60:63], v[128:131], v[208:211], v[60:63]
	v_mfma_f32_16x16x32_bf16 v[56:59], v[136:139], v[208:211], v[56:59]
	v_mfma_f32_16x16x32_bf16 v[44:47], v[128:131], v[216:219], v[44:47]
	v_mfma_f32_16x16x32_bf16 v[40:43], v[136:139], v[216:219], v[40:43]
	v_mfma_f32_16x16x32_bf16 v[28:31], v[128:131], v[224:227], v[28:31]
	v_mfma_f32_16x16x32_bf16 v[24:27], v[136:139], v[224:227], v[24:27]
	v_mfma_f32_16x16x32_bf16 v[12:15], v[128:131], v[232:235], v[12:15]
	v_mfma_f32_16x16x32_bf16 v[8:11], v[136:139], v[232:235], v[8:11]
	v_mfma_f32_16x16x32_bf16 v[60:63], v[132:135], v[212:215], v[60:63]
	v_mfma_f32_16x16x32_bf16 v[56:59], v[164:167], v[212:215], v[56:59]
	v_mfma_f32_16x16x32_bf16 v[44:47], v[132:135], v[220:223], v[44:47]
	v_mfma_f32_16x16x32_bf16 v[40:43], v[164:167], v[220:223], v[40:43]
	v_mfma_f32_16x16x32_bf16 v[28:31], v[132:135], v[228:231], v[28:31]
	v_mfma_f32_16x16x32_bf16 v[24:27], v[164:167], v[228:231], v[24:27]
	v_mfma_f32_16x16x32_bf16 v[12:15], v[132:135], v[236:239], v[12:15]
	v_mfma_f32_16x16x32_bf16 v[8:11], v[164:167], v[236:239], v[8:11]
	v_mfma_f32_16x16x32_bf16 v[52:55], v[188:191], v[208:211], v[52:55]
	v_mfma_f32_16x16x32_bf16 v[48:51], v[200:203], v[208:211], v[48:51]
	v_mfma_f32_16x16x32_bf16 v[36:39], v[188:191], v[216:219], v[36:39]
	v_mfma_f32_16x16x32_bf16 v[32:35], v[200:203], v[216:219], v[32:35]
	v_mfma_f32_16x16x32_bf16 v[20:23], v[188:191], v[224:227], v[20:23]
	v_mfma_f32_16x16x32_bf16 v[16:19], v[200:203], v[224:227], v[16:19]
	v_mfma_f32_16x16x32_bf16 v[4:7], v[188:191], v[232:235], v[4:7]
	v_mfma_f32_16x16x32_bf16 v[0:3], v[200:203], v[232:235], v[0:3]
	v_mfma_f32_16x16x32_bf16 v[52:55], v[196:199], v[212:215], v[52:55]
	v_mfma_f32_16x16x32_bf16 v[48:51], v[204:207], v[212:215], v[48:51]
	v_mfma_f32_16x16x32_bf16 v[36:39], v[196:199], v[220:223], v[36:39]
	v_mfma_f32_16x16x32_bf16 v[32:35], v[204:207], v[220:223], v[32:35]
	v_mfma_f32_16x16x32_bf16 v[20:23], v[196:199], v[228:231], v[20:23]
	v_mfma_f32_16x16x32_bf16 v[16:19], v[204:207], v[228:231], v[16:19]
	v_mfma_f32_16x16x32_bf16 v[4:7], v[196:199], v[236:239], v[4:7]
	v_mfma_f32_16x16x32_bf16 v[0:3], v[204:207], v[236:239], v[0:3]
	s_barrier
	s_setprio 0
	s_add_i32 s68, 0, 0x18000
	s_add_i32 s69, 0, 0x1c000
	v_add_u32_e32 v164, s68, v149
	v_add_u32_e32 v187, s69, v149
	ds_read_b128 v[128:131], v164
	ds_read_b128 v[132:135], v164 offset:1024
	ds_read_b128 v[136:139], v164 offset:2048
	ds_read_b128 v[164:167], v164 offset:3072
	ds_read_b128 v[188:191], v187
	ds_read_b128 v[196:199], v187 offset:1024
	ds_read_b128 v[200:203], v187 offset:2048
	ds_read_b128 v[204:207], v187 offset:3072
	s_add_u32 s22, s22, 0x40000
	s_addc_u32 s23, s23, 0
	s_mov_b32 m0, s41
	v_lshl_add_u64 v[244:245], s[22:23], 0, v[140:141]
	ds_read_b128 v[208:211], v185 offset:32768
	ds_read_b128 v[212:215], v185 offset:33792
	ds_read_b128 v[216:219], v185 offset:34816
	ds_read_b128 v[220:223], v185 offset:35840
	ds_read_b128 v[224:227], v185 offset:36864
	ds_read_b128 v[228:231], v185 offset:37888
	ds_read_b128 v[232:235], v185 offset:38912
	ds_read_b128 v[236:239], v185 offset:39936
	global_load_lds_dwordx4 v[244:245], off
	v_lshl_add_u64 v[244:245], s[22:23], 0, v[144:145]
	s_mov_b32 m0, s42
	s_nop 0
	global_load_lds_dwordx4 v[244:245], off
	s_waitcnt vmcnt(8)
	s_waitcnt lgkmcnt(0)
	s_barrier
	s_setprio 1
	v_mfma_f32_16x16x32_bf16 v[124:127], v[128:131], v[208:211], v[124:127]
	v_mfma_f32_16x16x32_bf16 v[120:123], v[136:139], v[208:211], v[120:123]
	v_mfma_f32_16x16x32_bf16 v[108:111], v[128:131], v[216:219], v[108:111]
	v_mfma_f32_16x16x32_bf16 v[104:107], v[136:139], v[216:219], v[104:107]
	v_mfma_f32_16x16x32_bf16 v[92:95], v[128:131], v[224:227], v[92:95]
	v_mfma_f32_16x16x32_bf16 v[88:91], v[136:139], v[224:227], v[88:91]
	v_mfma_f32_16x16x32_bf16 v[76:79], v[128:131], v[232:235], v[76:79]
	v_mfma_f32_16x16x32_bf16 v[72:75], v[136:139], v[232:235], v[72:75]
	v_mfma_f32_16x16x32_bf16 v[124:127], v[132:135], v[212:215], v[124:127]
	v_mfma_f32_16x16x32_bf16 v[120:123], v[164:167], v[212:215], v[120:123]
	v_mfma_f32_16x16x32_bf16 v[108:111], v[132:135], v[220:223], v[108:111]
	v_mfma_f32_16x16x32_bf16 v[104:107], v[164:167], v[220:223], v[104:107]
	v_mfma_f32_16x16x32_bf16 v[92:95], v[132:135], v[228:231], v[92:95]
	v_mfma_f32_16x16x32_bf16 v[88:91], v[164:167], v[228:231], v[88:91]
	v_mfma_f32_16x16x32_bf16 v[76:79], v[132:135], v[236:239], v[76:79]
	v_mfma_f32_16x16x32_bf16 v[72:75], v[164:167], v[236:239], v[72:75]
	v_mfma_f32_16x16x32_bf16 v[116:119], v[188:191], v[208:211], v[116:119]
	v_mfma_f32_16x16x32_bf16 v[112:115], v[200:203], v[208:211], v[112:115]
	v_mfma_f32_16x16x32_bf16 v[100:103], v[188:191], v[216:219], v[100:103]
	v_mfma_f32_16x16x32_bf16 v[96:99], v[200:203], v[216:219], v[96:99]
	v_mfma_f32_16x16x32_bf16 v[84:87], v[188:191], v[224:227], v[84:87]
	v_mfma_f32_16x16x32_bf16 v[80:83], v[200:203], v[224:227], v[80:83]
	v_mfma_f32_16x16x32_bf16 v[68:71], v[188:191], v[232:235], v[68:71]
	v_mfma_f32_16x16x32_bf16 v[64:67], v[200:203], v[232:235], v[64:67]
	v_mfma_f32_16x16x32_bf16 v[116:119], v[196:199], v[212:215], v[116:119]
	v_mfma_f32_16x16x32_bf16 v[112:115], v[204:207], v[212:215], v[112:115]
	v_mfma_f32_16x16x32_bf16 v[100:103], v[196:199], v[220:223], v[100:103]
	v_mfma_f32_16x16x32_bf16 v[96:99], v[204:207], v[220:223], v[96:99]
	v_mfma_f32_16x16x32_bf16 v[84:87], v[196:199], v[228:231], v[84:87]
	v_mfma_f32_16x16x32_bf16 v[80:83], v[204:207], v[228:231], v[80:83]
	v_mfma_f32_16x16x32_bf16 v[68:71], v[196:199], v[236:239], v[68:71]
	v_mfma_f32_16x16x32_bf16 v[64:67], v[204:207], v[236:239], v[64:67]
	s_barrier
	s_setprio 0
	s_add_i32 s22, s68, s39
	v_lshl_add_u64 v[168:169], v[168:169], 0, s[18:19]
	s_mov_b32 m0, s22
	ds_read_b128 v[208:211], v185 offset:49152
	ds_read_b128 v[212:215], v185 offset:50176
	ds_read_b128 v[216:219], v185 offset:51200
	ds_read_b128 v[220:223], v185 offset:52224
	ds_read_b128 v[224:227], v185 offset:53248
	ds_read_b128 v[228:231], v185 offset:54272
	ds_read_b128 v[232:235], v185 offset:55296
	ds_read_b128 v[236:239], v185 offset:56320
	global_load_lds_dwordx4 v[168:169], off
	s_add_i32 m0, s22, 0x2000
	s_add_u32 s2, s2, 0x40080
	v_lshl_add_u64 v[168:169], v[192:193], 0, s[18:19]
	s_addc_u32 s3, s3, 0
	s_add_i32 s22, s69, s39
	global_load_lds_dwordx4 v[168:169], off
	v_lshl_add_u64 v[168:169], s[2:3], 0, v[142:143]
	s_mov_b32 m0, s22
	s_nop 0
	global_load_lds_dwordx4 v[168:169], off
	v_lshl_add_u64 v[168:169], s[2:3], 0, v[146:147]
	s_add_i32 m0, s22, 0x2000
	s_nop 0
	global_load_lds_dwordx4 v[168:169], off
	v_lshl_add_u64 v[168:169], v[240:241], 0, s[18:19]
	s_mov_b32 m0, s46
	s_nop 0
	global_load_lds_dwordx4 v[168:169], off
	v_lshl_add_u64 v[168:169], v[242:243], 0, s[18:19]
	s_mov_b32 m0, s47
	s_nop 0
	global_load_lds_dwordx4 v[168:169], off
	s_waitcnt vmcnt(8)
	s_waitcnt lgkmcnt(0)
	s_barrier
	s_setprio 1
	v_mfma_f32_16x16x32_bf16 v[60:63], v[128:131], v[208:211], v[60:63]
	v_mfma_f32_16x16x32_bf16 v[56:59], v[136:139], v[208:211], v[56:59]
	v_mfma_f32_16x16x32_bf16 v[44:47], v[128:131], v[216:219], v[44:47]
	v_mfma_f32_16x16x32_bf16 v[40:43], v[136:139], v[216:219], v[40:43]
	v_mfma_f32_16x16x32_bf16 v[28:31], v[128:131], v[224:227], v[28:31]
	v_mfma_f32_16x16x32_bf16 v[24:27], v[136:139], v[224:227], v[24:27]
	v_mfma_f32_16x16x32_bf16 v[12:15], v[128:131], v[232:235], v[12:15]
	v_mfma_f32_16x16x32_bf16 v[8:11], v[136:139], v[232:235], v[8:11]
	v_mfma_f32_16x16x32_bf16 v[60:63], v[132:135], v[212:215], v[60:63]
	v_mfma_f32_16x16x32_bf16 v[56:59], v[164:167], v[212:215], v[56:59]
	v_mfma_f32_16x16x32_bf16 v[44:47], v[132:135], v[220:223], v[44:47]
	v_mfma_f32_16x16x32_bf16 v[40:43], v[164:167], v[220:223], v[40:43]
	v_mfma_f32_16x16x32_bf16 v[28:31], v[132:135], v[228:231], v[28:31]
	v_mfma_f32_16x16x32_bf16 v[24:27], v[164:167], v[228:231], v[24:27]
	v_mfma_f32_16x16x32_bf16 v[12:15], v[132:135], v[236:239], v[12:15]
	v_mfma_f32_16x16x32_bf16 v[8:11], v[164:167], v[236:239], v[8:11]
	v_mfma_f32_16x16x32_bf16 v[52:55], v[188:191], v[208:211], v[52:55]
	v_mfma_f32_16x16x32_bf16 v[48:51], v[200:203], v[208:211], v[48:51]
	v_mfma_f32_16x16x32_bf16 v[36:39], v[188:191], v[216:219], v[36:39]
	v_mfma_f32_16x16x32_bf16 v[32:35], v[200:203], v[216:219], v[32:35]
	v_mfma_f32_16x16x32_bf16 v[20:23], v[188:191], v[224:227], v[20:23]
	v_mfma_f32_16x16x32_bf16 v[16:19], v[200:203], v[224:227], v[16:19]
	v_mfma_f32_16x16x32_bf16 v[4:7], v[188:191], v[232:235], v[4:7]
	v_mfma_f32_16x16x32_bf16 v[0:3], v[200:203], v[232:235], v[0:3]
	v_mfma_f32_16x16x32_bf16 v[52:55], v[196:199], v[212:215], v[52:55]
	v_mfma_f32_16x16x32_bf16 v[48:51], v[204:207], v[212:215], v[48:51]
	v_mfma_f32_16x16x32_bf16 v[36:39], v[196:199], v[220:223], v[36:39]
	v_mfma_f32_16x16x32_bf16 v[32:35], v[204:207], v[220:223], v[32:35]
	v_mfma_f32_16x16x32_bf16 v[20:23], v[196:199], v[228:231], v[20:23]
	v_mfma_f32_16x16x32_bf16 v[16:19], v[204:207], v[228:231], v[16:19]
	v_mfma_f32_16x16x32_bf16 v[4:7], v[196:199], v[236:239], v[4:7]
	v_mfma_f32_16x16x32_bf16 v[0:3], v[204:207], v[236:239], v[0:3]
	s_barrier
	s_setprio 0
	s_add_i32 s67, s67, 2
	s_add_u32 s14, s14, 0x100
	s_addc_u32 s15, s15, 0
	s_add_u32 s65, s65, 0x100
	s_addc_u32 s66, s66, 0
	s_cmp_gt_u32 s67, 13
	s_cbranch_scc0 .LBB0_725

.LBB0_808:
	s_ashr_i32 s25, s24, 31
	s_lshl_b64 s[22:23], s[24:25], 19
	s_add_u32 s26, s84, s22
	s_addc_u32 s27, s85, s23
	s_and_b64 s[22:23], s[4:5], exec
	s_cselect_b32 s25, s27, s15
	s_cselect_b32 s50, s26, s14
	s_ashr_i32 s21, s20, 31
	s_lshl_b64 s[22:23], s[20:21], 19
	s_add_u32 s28, s30, s22
	s_addc_u32 s29, s31, s23
	s_and_b64 s[22:23], s[4:5], exec
	s_cselect_b32 s21, s29, s3
	s_cselect_b32 s51, s28, s2
	s_add_u32 s14, s14, 0x40080
	s_addc_u32 s15, s15, 0
	s_add_u32 s52, s2, 0x100
	s_addc_u32 s53, s3, 0
	s_mov_b32 s54, -2
	s_waitcnt vmcnt(0)
	ds_read_b128 v[136:139], v155
	ds_read_b128 v[162:165], v155 offset:1024
	ds_read_b128 v[166:169], v155 offset:2048
	ds_read_b128 v[178:181], v155 offset:3072
	ds_read_b128 v[184:187], v158
	ds_read_b128 v[188:191], v158 offset:1024
	ds_read_b128 v[196:199], v158 offset:2048
	ds_read_b128 v[200:203], v158 offset:3072
	s_add_u32 s2, s14, 0xfffc0080
	s_addc_u32 s3, s15, -1
	s_cmp_eq_u32 s54, 12
	s_cselect_b32 s23, s25, s3
	s_cselect_b32 s22, s50, s2
	s_cselect_b32 s3, s21, s53
	s_cselect_b32 s2, s51, s52
	v_lshl_add_u64 v[156:157], s[14:15], 0, v[128:129]
	s_add_i32 m0, s37, 0xc000
	ds_read_b128 v[204:207], v159
	ds_read_b128 v[208:211], v159 offset:1024
	ds_read_b128 v[212:215], v159 offset:2048
	ds_read_b128 v[216:219], v159 offset:3072
	ds_read_b128 v[220:223], v159 offset:4096
	ds_read_b128 v[224:227], v159 offset:5120
	ds_read_b128 v[228:231], v159 offset:6144
	ds_read_b128 v[232:235], v159 offset:7168
	global_load_lds_dwordx4 v[156:157], off
	v_lshl_add_u64 v[156:157], s[14:15], 0, v[130:131]
	s_add_i32 m0, s37, 0xe000
	s_nop 0
	global_load_lds_dwordx4 v[156:157], off
	s_waitcnt vmcnt(8)
	s_waitcnt lgkmcnt(0)
	s_barrier
	s_setprio 1
	v_mfma_f32_16x16x32_bf16 v[112:115], v[136:139], v[204:207], 0
	v_mfma_f32_16x16x32_bf16 v[108:111], v[166:169], v[204:207], 0
	v_mfma_f32_16x16x32_bf16 v[104:107], v[136:139], v[212:215], 0
	v_mfma_f32_16x16x32_bf16 v[100:103], v[166:169], v[212:215], 0
	v_mfma_f32_16x16x32_bf16 v[92:95], v[136:139], v[220:223], 0
	v_mfma_f32_16x16x32_bf16 v[84:87], v[166:169], v[220:223], 0
	v_mfma_f32_16x16x32_bf16 v[76:79], v[136:139], v[228:231], 0
	v_mfma_f32_16x16x32_bf16 v[68:71], v[166:169], v[228:231], 0
	v_mfma_f32_16x16x32_bf16 v[112:115], v[162:165], v[208:211], v[112:115]
	v_mfma_f32_16x16x32_bf16 v[108:111], v[178:181], v[208:211], v[108:111]
	v_mfma_f32_16x16x32_bf16 v[104:107], v[162:165], v[216:219], v[104:107]
	v_mfma_f32_16x16x32_bf16 v[100:103], v[178:181], v[216:219], v[100:103]
	v_mfma_f32_16x16x32_bf16 v[92:95], v[162:165], v[224:227], v[92:95]
	v_mfma_f32_16x16x32_bf16 v[84:87], v[178:181], v[224:227], v[84:87]
	v_mfma_f32_16x16x32_bf16 v[76:79], v[162:165], v[232:235], v[76:79]
	v_mfma_f32_16x16x32_bf16 v[68:71], v[178:181], v[232:235], v[68:71]
	v_mfma_f32_16x16x32_bf16 v[124:127], v[184:187], v[204:207], 0
	v_mfma_f32_16x16x32_bf16 v[120:123], v[196:199], v[204:207], 0
	v_mfma_f32_16x16x32_bf16 v[116:119], v[184:187], v[212:215], 0
	v_mfma_f32_16x16x32_bf16 v[96:99], v[196:199], v[212:215], 0
	v_mfma_f32_16x16x32_bf16 v[88:91], v[184:187], v[220:223], 0
	v_mfma_f32_16x16x32_bf16 v[80:83], v[196:199], v[220:223], 0
	v_mfma_f32_16x16x32_bf16 v[72:75], v[184:187], v[228:231], 0
	v_mfma_f32_16x16x32_bf16 v[64:67], v[196:199], v[228:231], 0
	v_mfma_f32_16x16x32_bf16 v[124:127], v[188:191], v[208:211], v[124:127]
	v_mfma_f32_16x16x32_bf16 v[120:123], v[200:203], v[208:211], v[120:123]
	v_mfma_f32_16x16x32_bf16 v[116:119], v[188:191], v[216:219], v[116:119]
	v_mfma_f32_16x16x32_bf16 v[96:99], v[200:203], v[216:219], v[96:99]
	v_mfma_f32_16x16x32_bf16 v[88:91], v[188:191], v[224:227], v[88:91]
	v_mfma_f32_16x16x32_bf16 v[80:83], v[200:203], v[224:227], v[80:83]
	v_mfma_f32_16x16x32_bf16 v[72:75], v[188:191], v[232:235], v[72:75]
	v_mfma_f32_16x16x32_bf16 v[64:67], v[200:203], v[232:235], v[64:67]
	s_barrier
	s_setprio 0
	s_add_i32 s55, s46, s34
	v_lshl_add_u64 v[156:157], s[2:3], 0, v[142:143]
	s_mov_b32 m0, s55
	ds_read_b128 v[204:207], v159 offset:16384
	ds_read_b128 v[208:211], v159 offset:17408
	ds_read_b128 v[212:215], v159 offset:18432
	ds_read_b128 v[216:219], v159 offset:19456
	ds_read_b128 v[220:223], v159 offset:20480
	ds_read_b128 v[224:227], v159 offset:21504
	ds_read_b128 v[228:231], v159 offset:22528
	ds_read_b128 v[232:235], v159 offset:23552
	global_load_lds_dwordx4 v[156:157], off
	s_add_i32 m0, s55, 0x2000
	s_add_u32 s56, s2, 0x40000
	v_lshl_add_u64 v[192:193], s[2:3], 0, v[146:147]
	s_addc_u32 s57, s3, 0
	s_add_i32 s55, s47, s34
	global_load_lds_dwordx4 v[192:193], off
	v_lshl_add_u64 v[236:237], s[56:57], 0, v[142:143]
	s_mov_b32 m0, s55
	v_lshl_add_u64 v[238:239], s[22:23], 0, v[144:145]
	global_load_lds_dwordx4 v[236:237], off
	v_lshl_add_u64 v[236:237], s[56:57], 0, v[146:147]
	s_add_i32 m0, s55, 0x2000
	s_nop 0
	global_load_lds_dwordx4 v[236:237], off
	v_lshl_add_u64 v[236:237], s[22:23], 0, v[140:141]
	s_mov_b32 m0, s37
	s_nop 0
	global_load_lds_dwordx4 v[236:237], off
	s_mov_b32 m0, s38
	s_nop 0
	global_load_lds_dwordx4 v[238:239], off
	s_waitcnt vmcnt(8)
	s_waitcnt lgkmcnt(0)
	s_barrier
	s_setprio 1
	v_mfma_f32_16x16x32_bf16 v[60:63], v[136:139], v[204:207], 0
	v_mfma_f32_16x16x32_bf16 v[52:55], v[166:169], v[204:207], 0
	v_mfma_f32_16x16x32_bf16 v[44:47], v[136:139], v[212:215], 0
	v_mfma_f32_16x16x32_bf16 v[36:39], v[166:169], v[212:215], 0
	v_mfma_f32_16x16x32_bf16 v[28:31], v[136:139], v[220:223], 0
	v_mfma_f32_16x16x32_bf16 v[20:23], v[166:169], v[220:223], 0
	v_mfma_f32_16x16x32_bf16 v[12:15], v[136:139], v[228:231], 0
	v_mfma_f32_16x16x32_bf16 v[4:7], v[166:169], v[228:231], 0
	v_mfma_f32_16x16x32_bf16 v[60:63], v[162:165], v[208:211], v[60:63]
	v_mfma_f32_16x16x32_bf16 v[52:55], v[178:181], v[208:211], v[52:55]
	v_mfma_f32_16x16x32_bf16 v[44:47], v[162:165], v[216:219], v[44:47]
	v_mfma_f32_16x16x32_bf16 v[36:39], v[178:181], v[216:219], v[36:39]
	v_mfma_f32_16x16x32_bf16 v[28:31], v[162:165], v[224:227], v[28:31]
	v_mfma_f32_16x16x32_bf16 v[20:23], v[178:181], v[224:227], v[20:23]
	v_mfma_f32_16x16x32_bf16 v[12:15], v[162:165], v[232:235], v[12:15]
	v_mfma_f32_16x16x32_bf16 v[4:7], v[178:181], v[232:235], v[4:7]
	v_mfma_f32_16x16x32_bf16 v[56:59], v[184:187], v[204:207], 0
	v_mfma_f32_16x16x32_bf16 v[48:51], v[196:199], v[204:207], 0
	v_mfma_f32_16x16x32_bf16 v[40:43], v[184:187], v[212:215], 0
	v_mfma_f32_16x16x32_bf16 v[32:35], v[196:199], v[212:215], 0
	v_mfma_f32_16x16x32_bf16 v[24:27], v[184:187], v[220:223], 0
	v_mfma_f32_16x16x32_bf16 v[16:19], v[196:199], v[220:223], 0
	v_mfma_f32_16x16x32_bf16 v[8:11], v[184:187], v[228:231], 0
	v_mfma_f32_16x16x32_bf16 v[0:3], v[196:199], v[228:231], 0
	v_mfma_f32_16x16x32_bf16 v[56:59], v[188:191], v[208:211], v[56:59]
	v_mfma_f32_16x16x32_bf16 v[48:51], v[200:203], v[208:211], v[48:51]
	v_mfma_f32_16x16x32_bf16 v[40:43], v[188:191], v[216:219], v[40:43]
	v_mfma_f32_16x16x32_bf16 v[32:35], v[200:203], v[216:219], v[32:35]
	v_mfma_f32_16x16x32_bf16 v[24:27], v[188:191], v[224:227], v[24:27]
	v_mfma_f32_16x16x32_bf16 v[16:19], v[200:203], v[224:227], v[16:19]
	v_mfma_f32_16x16x32_bf16 v[8:11], v[188:191], v[232:235], v[8:11]
	v_mfma_f32_16x16x32_bf16 v[0:3], v[200:203], v[232:235], v[0:3]
	s_barrier
	s_setprio 0
	s_add_i32 s55, 0, 0x18000
	v_add_u32_e32 v161, s55, v151
	s_add_i32 s56, 0, 0x1c000
	ds_read_b128 v[136:139], v161
	ds_read_b128 v[162:165], v161 offset:1024
	ds_read_b128 v[166:169], v161 offset:2048
	ds_read_b128 v[178:181], v161 offset:3072
	v_add_u32_e32 v161, s56, v151
	ds_read_b128 v[184:187], v161
	ds_read_b128 v[188:191], v161 offset:1024
	ds_read_b128 v[196:199], v161 offset:2048
	ds_read_b128 v[200:203], v161 offset:3072
	s_add_u32 s22, s22, 0x40000
	s_addc_u32 s23, s23, 0
	s_mov_b32 m0, s39
	v_lshl_add_u64 v[240:241], s[22:23], 0, v[140:141]
	ds_read_b128 v[204:207], v159 offset:32768
	ds_read_b128 v[208:211], v159 offset:33792
	ds_read_b128 v[212:215], v159 offset:34816
	ds_read_b128 v[216:219], v159 offset:35840
	ds_read_b128 v[220:223], v159 offset:36864
	ds_read_b128 v[224:227], v159 offset:37888
	ds_read_b128 v[228:231], v159 offset:38912
	ds_read_b128 v[232:235], v159 offset:39936
	global_load_lds_dwordx4 v[240:241], off
	v_lshl_add_u64 v[240:241], s[22:23], 0, v[144:145]
	s_mov_b32 m0, s40
	s_nop 0
	global_load_lds_dwordx4 v[240:241], off
	s_waitcnt vmcnt(8)
	s_waitcnt lgkmcnt(0)
	s_barrier
	s_setprio 1
	v_mfma_f32_16x16x32_bf16 v[112:115], v[136:139], v[204:207], v[112:115]
	v_mfma_f32_16x16x32_bf16 v[108:111], v[166:169], v[204:207], v[108:111]
	v_mfma_f32_16x16x32_bf16 v[104:107], v[136:139], v[212:215], v[104:107]
	v_mfma_f32_16x16x32_bf16 v[100:103], v[166:169], v[212:215], v[100:103]
	v_mfma_f32_16x16x32_bf16 v[92:95], v[136:139], v[220:223], v[92:95]
	v_mfma_f32_16x16x32_bf16 v[84:87], v[166:169], v[220:223], v[84:87]
	v_mfma_f32_16x16x32_bf16 v[76:79], v[136:139], v[228:231], v[76:79]
	v_mfma_f32_16x16x32_bf16 v[68:71], v[166:169], v[228:231], v[68:71]
	v_mfma_f32_16x16x32_bf16 v[112:115], v[162:165], v[208:211], v[112:115]
	v_mfma_f32_16x16x32_bf16 v[108:111], v[178:181], v[208:211], v[108:111]
	v_mfma_f32_16x16x32_bf16 v[104:107], v[162:165], v[216:219], v[104:107]
	v_mfma_f32_16x16x32_bf16 v[100:103], v[178:181], v[216:219], v[100:103]
	v_mfma_f32_16x16x32_bf16 v[92:95], v[162:165], v[224:227], v[92:95]
	v_mfma_f32_16x16x32_bf16 v[84:87], v[178:181], v[224:227], v[84:87]
	v_mfma_f32_16x16x32_bf16 v[76:79], v[162:165], v[232:235], v[76:79]
	v_mfma_f32_16x16x32_bf16 v[68:71], v[178:181], v[232:235], v[68:71]
	v_mfma_f32_16x16x32_bf16 v[124:127], v[184:187], v[204:207], v[124:127]
	v_mfma_f32_16x16x32_bf16 v[120:123], v[196:199], v[204:207], v[120:123]
	v_mfma_f32_16x16x32_bf16 v[116:119], v[184:187], v[212:215], v[116:119]
	v_mfma_f32_16x16x32_bf16 v[96:99], v[196:199], v[212:215], v[96:99]
	v_mfma_f32_16x16x32_bf16 v[88:91], v[184:187], v[220:223], v[88:91]
	v_mfma_f32_16x16x32_bf16 v[80:83], v[196:199], v[220:223], v[80:83]
	v_mfma_f32_16x16x32_bf16 v[72:75], v[184:187], v[228:231], v[72:75]
	v_mfma_f32_16x16x32_bf16 v[64:67], v[196:199], v[228:231], v[64:67]
	v_mfma_f32_16x16x32_bf16 v[124:127], v[188:191], v[208:211], v[124:127]
	v_mfma_f32_16x16x32_bf16 v[120:123], v[200:203], v[208:211], v[120:123]
	v_mfma_f32_16x16x32_bf16 v[116:119], v[188:191], v[216:219], v[116:119]
	v_mfma_f32_16x16x32_bf16 v[96:99], v[200:203], v[216:219], v[96:99]
	v_mfma_f32_16x16x32_bf16 v[88:91], v[188:191], v[224:227], v[88:91]
	v_mfma_f32_16x16x32_bf16 v[80:83], v[200:203], v[224:227], v[80:83]
	v_mfma_f32_16x16x32_bf16 v[72:75], v[188:191], v[232:235], v[72:75]
	v_mfma_f32_16x16x32_bf16 v[64:67], v[200:203], v[232:235], v[64:67]
	s_barrier
	s_setprio 0
	s_add_i32 s22, s55, s34
	v_lshl_add_u64 v[156:157], v[156:157], 0, s[12:13]
	s_mov_b32 m0, s22
	ds_read_b128 v[204:207], v159 offset:49152
	ds_read_b128 v[208:211], v159 offset:50176
	ds_read_b128 v[212:215], v159 offset:51200
	ds_read_b128 v[216:219], v159 offset:52224
	ds_read_b128 v[220:223], v159 offset:53248
	ds_read_b128 v[224:227], v159 offset:54272
	ds_read_b128 v[228:231], v159 offset:55296
	ds_read_b128 v[232:235], v159 offset:56320
	global_load_lds_dwordx4 v[156:157], off
	s_add_i32 m0, s22, 0x2000
	s_add_u32 s2, s2, 0x40080
	v_lshl_add_u64 v[156:157], v[192:193], 0, s[12:13]
	s_addc_u32 s3, s3, 0
	s_add_i32 s22, s56, s34
	global_load_lds_dwordx4 v[156:157], off
	v_lshl_add_u64 v[156:157], s[2:3], 0, v[142:143]
	s_mov_b32 m0, s22
	s_nop 0
	global_load_lds_dwordx4 v[156:157], off
	v_lshl_add_u64 v[156:157], s[2:3], 0, v[146:147]
	s_add_i32 m0, s22, 0x2000
	s_nop 0
	global_load_lds_dwordx4 v[156:157], off
	v_lshl_add_u64 v[156:157], v[236:237], 0, s[12:13]
	s_mov_b32 m0, s42
	s_nop 0
	global_load_lds_dwordx4 v[156:157], off
	v_lshl_add_u64 v[156:157], v[238:239], 0, s[12:13]
	s_mov_b32 m0, s43
	s_nop 0
	global_load_lds_dwordx4 v[156:157], off
	s_waitcnt vmcnt(8)
	s_waitcnt lgkmcnt(0)
	s_barrier
	s_setprio 1
	v_mfma_f32_16x16x32_bf16 v[60:63], v[136:139], v[204:207], v[60:63]
	v_mfma_f32_16x16x32_bf16 v[52:55], v[166:169], v[204:207], v[52:55]
	v_mfma_f32_16x16x32_bf16 v[44:47], v[136:139], v[212:215], v[44:47]
	v_mfma_f32_16x16x32_bf16 v[36:39], v[166:169], v[212:215], v[36:39]
	v_mfma_f32_16x16x32_bf16 v[28:31], v[136:139], v[220:223], v[28:31]
	v_mfma_f32_16x16x32_bf16 v[20:23], v[166:169], v[220:223], v[20:23]
	v_mfma_f32_16x16x32_bf16 v[12:15], v[136:139], v[228:231], v[12:15]
	v_mfma_f32_16x16x32_bf16 v[4:7], v[166:169], v[228:231], v[4:7]
	v_mfma_f32_16x16x32_bf16 v[60:63], v[162:165], v[208:211], v[60:63]
	v_mfma_f32_16x16x32_bf16 v[52:55], v[178:181], v[208:211], v[52:55]
	v_mfma_f32_16x16x32_bf16 v[44:47], v[162:165], v[216:219], v[44:47]
	v_mfma_f32_16x16x32_bf16 v[36:39], v[178:181], v[216:219], v[36:39]
	v_mfma_f32_16x16x32_bf16 v[28:31], v[162:165], v[224:227], v[28:31]
	v_mfma_f32_16x16x32_bf16 v[20:23], v[178:181], v[224:227], v[20:23]
	v_mfma_f32_16x16x32_bf16 v[12:15], v[162:165], v[232:235], v[12:15]
	v_mfma_f32_16x16x32_bf16 v[4:7], v[178:181], v[232:235], v[4:7]
	v_mfma_f32_16x16x32_bf16 v[56:59], v[184:187], v[204:207], v[56:59]
	v_mfma_f32_16x16x32_bf16 v[48:51], v[196:199], v[204:207], v[48:51]
	v_mfma_f32_16x16x32_bf16 v[40:43], v[184:187], v[212:215], v[40:43]
	v_mfma_f32_16x16x32_bf16 v[32:35], v[196:199], v[212:215], v[32:35]
	v_mfma_f32_16x16x32_bf16 v[24:27], v[184:187], v[220:223], v[24:27]
	v_mfma_f32_16x16x32_bf16 v[16:19], v[196:199], v[220:223], v[16:19]
	v_mfma_f32_16x16x32_bf16 v[8:11], v[184:187], v[228:231], v[8:11]
	v_mfma_f32_16x16x32_bf16 v[0:3], v[196:199], v[228:231], v[0:3]
	v_mfma_f32_16x16x32_bf16 v[56:59], v[188:191], v[208:211], v[56:59]
	v_mfma_f32_16x16x32_bf16 v[48:51], v[200:203], v[208:211], v[48:51]
	v_mfma_f32_16x16x32_bf16 v[40:43], v[188:191], v[216:219], v[40:43]
	v_mfma_f32_16x16x32_bf16 v[32:35], v[200:203], v[216:219], v[32:35]
	v_mfma_f32_16x16x32_bf16 v[24:27], v[188:191], v[224:227], v[24:27]
	v_mfma_f32_16x16x32_bf16 v[16:19], v[200:203], v[224:227], v[16:19]
	v_mfma_f32_16x16x32_bf16 v[8:11], v[188:191], v[232:235], v[8:11]
	v_mfma_f32_16x16x32_bf16 v[0:3], v[200:203], v[232:235], v[0:3]
	s_barrier
	s_setprio 0
	s_add_i32 s54, s54, 2
	s_add_u32 s14, s14, 0x100
	s_addc_u32 s15, s15, 0
	s_add_u32 s52, s52, 0x100
	s_addc_u32 s53, s53, 0
	s_cmp_gt_u32 s54, 13
	s_cbranch_scc1 .Lgemm_kdone_5
.LBB0_809:
	ds_read_b128 v[136:139], v155
	ds_read_b128 v[162:165], v155 offset:1024
	ds_read_b128 v[166:169], v155 offset:2048
	ds_read_b128 v[178:181], v155 offset:3072
	ds_read_b128 v[184:187], v158
	ds_read_b128 v[188:191], v158 offset:1024
	ds_read_b128 v[196:199], v158 offset:2048
	ds_read_b128 v[200:203], v158 offset:3072
	s_add_u32 s2, s14, 0xfffc0080
	s_addc_u32 s3, s15, -1
	s_cmp_eq_u32 s54, 12
	s_cselect_b32 s23, s25, s3
	s_cselect_b32 s22, s50, s2
	s_cselect_b32 s3, s21, s53
	s_cselect_b32 s2, s51, s52
	v_lshl_add_u64 v[156:157], s[14:15], 0, v[128:129]
	s_add_i32 m0, s37, 0xc000
	ds_read_b128 v[204:207], v159
	ds_read_b128 v[208:211], v159 offset:1024
	ds_read_b128 v[212:215], v159 offset:2048
	ds_read_b128 v[216:219], v159 offset:3072
	ds_read_b128 v[220:223], v159 offset:4096
	ds_read_b128 v[224:227], v159 offset:5120
	ds_read_b128 v[228:231], v159 offset:6144
	ds_read_b128 v[232:235], v159 offset:7168
	global_load_lds_dwordx4 v[156:157], off
	v_lshl_add_u64 v[156:157], s[14:15], 0, v[130:131]
	s_add_i32 m0, s37, 0xe000
	s_nop 0
	global_load_lds_dwordx4 v[156:157], off
	s_waitcnt vmcnt(8)
	s_waitcnt lgkmcnt(0)
	s_barrier
	s_setprio 1
	v_mfma_f32_16x16x32_bf16 v[112:115], v[136:139], v[204:207], v[112:115]
	v_mfma_f32_16x16x32_bf16 v[108:111], v[166:169], v[204:207], v[108:111]
	v_mfma_f32_16x16x32_bf16 v[104:107], v[136:139], v[212:215], v[104:107]
	v_mfma_f32_16x16x32_bf16 v[100:103], v[166:169], v[212:215], v[100:103]
	v_mfma_f32_16x16x32_bf16 v[92:95], v[136:139], v[220:223], v[92:95]
	v_mfma_f32_16x16x32_bf16 v[84:87], v[166:169], v[220:223], v[84:87]
	v_mfma_f32_16x16x32_bf16 v[76:79], v[136:139], v[228:231], v[76:79]
	v_mfma_f32_16x16x32_bf16 v[68:71], v[166:169], v[228:231], v[68:71]
	v_mfma_f32_16x16x32_bf16 v[112:115], v[162:165], v[208:211], v[112:115]
	v_mfma_f32_16x16x32_bf16 v[108:111], v[178:181], v[208:211], v[108:111]
	v_mfma_f32_16x16x32_bf16 v[104:107], v[162:165], v[216:219], v[104:107]
	v_mfma_f32_16x16x32_bf16 v[100:103], v[178:181], v[216:219], v[100:103]
	v_mfma_f32_16x16x32_bf16 v[92:95], v[162:165], v[224:227], v[92:95]
	v_mfma_f32_16x16x32_bf16 v[84:87], v[178:181], v[224:227], v[84:87]
	v_mfma_f32_16x16x32_bf16 v[76:79], v[162:165], v[232:235], v[76:79]
	v_mfma_f32_16x16x32_bf16 v[68:71], v[178:181], v[232:235], v[68:71]
	v_mfma_f32_16x16x32_bf16 v[124:127], v[184:187], v[204:207], v[124:127]
	v_mfma_f32_16x16x32_bf16 v[120:123], v[196:199], v[204:207], v[120:123]
	v_mfma_f32_16x16x32_bf16 v[116:119], v[184:187], v[212:215], v[116:119]
	v_mfma_f32_16x16x32_bf16 v[96:99], v[196:199], v[212:215], v[96:99]
	v_mfma_f32_16x16x32_bf16 v[88:91], v[184:187], v[220:223], v[88:91]
	v_mfma_f32_16x16x32_bf16 v[80:83], v[196:199], v[220:223], v[80:83]
	v_mfma_f32_16x16x32_bf16 v[72:75], v[184:187], v[228:231], v[72:75]
	v_mfma_f32_16x16x32_bf16 v[64:67], v[196:199], v[228:231], v[64:67]
	v_mfma_f32_16x16x32_bf16 v[124:127], v[188:191], v[208:211], v[124:127]
	v_mfma_f32_16x16x32_bf16 v[120:123], v[200:203], v[208:211], v[120:123]
	v_mfma_f32_16x16x32_bf16 v[116:119], v[188:191], v[216:219], v[116:119]
	v_mfma_f32_16x16x32_bf16 v[96:99], v[200:203], v[216:219], v[96:99]
	v_mfma_f32_16x16x32_bf16 v[88:91], v[188:191], v[224:227], v[88:91]
	v_mfma_f32_16x16x32_bf16 v[80:83], v[200:203], v[224:227], v[80:83]
	v_mfma_f32_16x16x32_bf16 v[72:75], v[188:191], v[232:235], v[72:75]
	v_mfma_f32_16x16x32_bf16 v[64:67], v[200:203], v[232:235], v[64:67]
	s_barrier
	s_setprio 0
	s_add_i32 s55, s46, s34
	v_lshl_add_u64 v[156:157], s[2:3], 0, v[142:143]
	s_mov_b32 m0, s55
	ds_read_b128 v[204:207], v159 offset:16384
	ds_read_b128 v[208:211], v159 offset:17408
	ds_read_b128 v[212:215], v159 offset:18432
	ds_read_b128 v[216:219], v159 offset:19456
	ds_read_b128 v[220:223], v159 offset:20480
	ds_read_b128 v[224:227], v159 offset:21504
	ds_read_b128 v[228:231], v159 offset:22528
	ds_read_b128 v[232:235], v159 offset:23552
	global_load_lds_dwordx4 v[156:157], off
	s_add_i32 m0, s55, 0x2000
	s_add_u32 s56, s2, 0x40000
	v_lshl_add_u64 v[192:193], s[2:3], 0, v[146:147]
	s_addc_u32 s57, s3, 0
	s_add_i32 s55, s47, s34
	global_load_lds_dwordx4 v[192:193], off
	v_lshl_add_u64 v[236:237], s[56:57], 0, v[142:143]
	s_mov_b32 m0, s55
	v_lshl_add_u64 v[238:239], s[22:23], 0, v[144:145]
	global_load_lds_dwordx4 v[236:237], off
	v_lshl_add_u64 v[236:237], s[56:57], 0, v[146:147]
	s_add_i32 m0, s55, 0x2000
	s_nop 0
	global_load_lds_dwordx4 v[236:237], off
	v_lshl_add_u64 v[236:237], s[22:23], 0, v[140:141]
	s_mov_b32 m0, s37
	s_nop 0
	global_load_lds_dwordx4 v[236:237], off
	s_mov_b32 m0, s38
	s_nop 0
	global_load_lds_dwordx4 v[238:239], off
	s_waitcnt vmcnt(8)
	s_waitcnt lgkmcnt(0)
	s_barrier
	s_setprio 1
	v_mfma_f32_16x16x32_bf16 v[60:63], v[136:139], v[204:207], v[60:63]
	v_mfma_f32_16x16x32_bf16 v[52:55], v[166:169], v[204:207], v[52:55]
	v_mfma_f32_16x16x32_bf16 v[44:47], v[136:139], v[212:215], v[44:47]
	v_mfma_f32_16x16x32_bf16 v[36:39], v[166:169], v[212:215], v[36:39]
	v_mfma_f32_16x16x32_bf16 v[28:31], v[136:139], v[220:223], v[28:31]
	v_mfma_f32_16x16x32_bf16 v[20:23], v[166:169], v[220:223], v[20:23]
	v_mfma_f32_16x16x32_bf16 v[12:15], v[136:139], v[228:231], v[12:15]
	v_mfma_f32_16x16x32_bf16 v[4:7], v[166:169], v[228:231], v[4:7]
	v_mfma_f32_16x16x32_bf16 v[60:63], v[162:165], v[208:211], v[60:63]
	v_mfma_f32_16x16x32_bf16 v[52:55], v[178:181], v[208:211], v[52:55]
	v_mfma_f32_16x16x32_bf16 v[44:47], v[162:165], v[216:219], v[44:47]
	v_mfma_f32_16x16x32_bf16 v[36:39], v[178:181], v[216:219], v[36:39]
	v_mfma_f32_16x16x32_bf16 v[28:31], v[162:165], v[224:227], v[28:31]
	v_mfma_f32_16x16x32_bf16 v[20:23], v[178:181], v[224:227], v[20:23]
	v_mfma_f32_16x16x32_bf16 v[12:15], v[162:165], v[232:235], v[12:15]
	v_mfma_f32_16x16x32_bf16 v[4:7], v[178:181], v[232:235], v[4:7]
	v_mfma_f32_16x16x32_bf16 v[56:59], v[184:187], v[204:207], v[56:59]
	v_mfma_f32_16x16x32_bf16 v[48:51], v[196:199], v[204:207], v[48:51]
	v_mfma_f32_16x16x32_bf16 v[40:43], v[184:187], v[212:215], v[40:43]
	v_mfma_f32_16x16x32_bf16 v[32:35], v[196:199], v[212:215], v[32:35]
	v_mfma_f32_16x16x32_bf16 v[24:27], v[184:187], v[220:223], v[24:27]
	v_mfma_f32_16x16x32_bf16 v[16:19], v[196:199], v[220:223], v[16:19]
	v_mfma_f32_16x16x32_bf16 v[8:11], v[184:187], v[228:231], v[8:11]
	v_mfma_f32_16x16x32_bf16 v[0:3], v[196:199], v[228:231], v[0:3]
	v_mfma_f32_16x16x32_bf16 v[56:59], v[188:191], v[208:211], v[56:59]
	v_mfma_f32_16x16x32_bf16 v[48:51], v[200:203], v[208:211], v[48:51]
	v_mfma_f32_16x16x32_bf16 v[40:43], v[188:191], v[216:219], v[40:43]
	v_mfma_f32_16x16x32_bf16 v[32:35], v[200:203], v[216:219], v[32:35]
	v_mfma_f32_16x16x32_bf16 v[24:27], v[188:191], v[224:227], v[24:27]
	v_mfma_f32_16x16x32_bf16 v[16:19], v[200:203], v[224:227], v[16:19]
	v_mfma_f32_16x16x32_bf16 v[8:11], v[188:191], v[232:235], v[8:11]
	v_mfma_f32_16x16x32_bf16 v[0:3], v[200:203], v[232:235], v[0:3]
	s_barrier
	s_setprio 0
	s_add_i32 s55, 0, 0x18000
	v_add_u32_e32 v161, s55, v151
	s_add_i32 s56, 0, 0x1c000
	ds_read_b128 v[136:139], v161
	ds_read_b128 v[162:165], v161 offset:1024
	ds_read_b128 v[166:169], v161 offset:2048
	ds_read_b128 v[178:181], v161 offset:3072
	v_add_u32_e32 v161, s56, v151
	ds_read_b128 v[184:187], v161
	ds_read_b128 v[188:191], v161 offset:1024
	ds_read_b128 v[196:199], v161 offset:2048
	ds_read_b128 v[200:203], v161 offset:3072
	s_add_u32 s22, s22, 0x40000
	s_addc_u32 s23, s23, 0
	s_mov_b32 m0, s39
	v_lshl_add_u64 v[240:241], s[22:23], 0, v[140:141]
	ds_read_b128 v[204:207], v159 offset:32768
	ds_read_b128 v[208:211], v159 offset:33792
	ds_read_b128 v[212:215], v159 offset:34816
	ds_read_b128 v[216:219], v159 offset:35840
	ds_read_b128 v[220:223], v159 offset:36864
	ds_read_b128 v[224:227], v159 offset:37888
	ds_read_b128 v[228:231], v159 offset:38912
	ds_read_b128 v[232:235], v159 offset:39936
	global_load_lds_dwordx4 v[240:241], off
	v_lshl_add_u64 v[240:241], s[22:23], 0, v[144:145]
	s_mov_b32 m0, s40
	s_nop 0
	global_load_lds_dwordx4 v[240:241], off
	s_waitcnt vmcnt(8)
	s_waitcnt lgkmcnt(0)
	s_barrier
	s_setprio 1
	v_mfma_f32_16x16x32_bf16 v[112:115], v[136:139], v[204:207], v[112:115]
	v_mfma_f32_16x16x32_bf16 v[108:111], v[166:169], v[204:207], v[108:111]
	v_mfma_f32_16x16x32_bf16 v[104:107], v[136:139], v[212:215], v[104:107]
	v_mfma_f32_16x16x32_bf16 v[100:103], v[166:169], v[212:215], v[100:103]
	v_mfma_f32_16x16x32_bf16 v[92:95], v[136:139], v[220:223], v[92:95]
	v_mfma_f32_16x16x32_bf16 v[84:87], v[166:169], v[220:223], v[84:87]
	v_mfma_f32_16x16x32_bf16 v[76:79], v[136:139], v[228:231], v[76:79]
	v_mfma_f32_16x16x32_bf16 v[68:71], v[166:169], v[228:231], v[68:71]
	v_mfma_f32_16x16x32_bf16 v[112:115], v[162:165], v[208:211], v[112:115]
	v_mfma_f32_16x16x32_bf16 v[108:111], v[178:181], v[208:211], v[108:111]
	v_mfma_f32_16x16x32_bf16 v[104:107], v[162:165], v[216:219], v[104:107]
	v_mfma_f32_16x16x32_bf16 v[100:103], v[178:181], v[216:219], v[100:103]
	v_mfma_f32_16x16x32_bf16 v[92:95], v[162:165], v[224:227], v[92:95]
	v_mfma_f32_16x16x32_bf16 v[84:87], v[178:181], v[224:227], v[84:87]
	v_mfma_f32_16x16x32_bf16 v[76:79], v[162:165], v[232:235], v[76:79]
	v_mfma_f32_16x16x32_bf16 v[68:71], v[178:181], v[232:235], v[68:71]
	v_mfma_f32_16x16x32_bf16 v[124:127], v[184:187], v[204:207], v[124:127]
	v_mfma_f32_16x16x32_bf16 v[120:123], v[196:199], v[204:207], v[120:123]
	v_mfma_f32_16x16x32_bf16 v[116:119], v[184:187], v[212:215], v[116:119]
	v_mfma_f32_16x16x32_bf16 v[96:99], v[196:199], v[212:215], v[96:99]
	v_mfma_f32_16x16x32_bf16 v[88:91], v[184:187], v[220:223], v[88:91]
	v_mfma_f32_16x16x32_bf16 v[80:83], v[196:199], v[220:223], v[80:83]
	v_mfma_f32_16x16x32_bf16 v[72:75], v[184:187], v[228:231], v[72:75]
	v_mfma_f32_16x16x32_bf16 v[64:67], v[196:199], v[228:231], v[64:67]
	v_mfma_f32_16x16x32_bf16 v[124:127], v[188:191], v[208:211], v[124:127]
	v_mfma_f32_16x16x32_bf16 v[120:123], v[200:203], v[208:211], v[120:123]
	v_mfma_f32_16x16x32_bf16 v[116:119], v[188:191], v[216:219], v[116:119]
	v_mfma_f32_16x16x32_bf16 v[96:99], v[200:203], v[216:219], v[96:99]
	v_mfma_f32_16x16x32_bf16 v[88:91], v[188:191], v[224:227], v[88:91]
	v_mfma_f32_16x16x32_bf16 v[80:83], v[200:203], v[224:227], v[80:83]
	v_mfma_f32_16x16x32_bf16 v[72:75], v[188:191], v[232:235], v[72:75]
	v_mfma_f32_16x16x32_bf16 v[64:67], v[200:203], v[232:235], v[64:67]
	s_barrier
	s_setprio 0
	s_add_i32 s22, s55, s34
	v_lshl_add_u64 v[156:157], v[156:157], 0, s[12:13]
	s_mov_b32 m0, s22
	ds_read_b128 v[204:207], v159 offset:49152
	ds_read_b128 v[208:211], v159 offset:50176
	ds_read_b128 v[212:215], v159 offset:51200
	ds_read_b128 v[216:219], v159 offset:52224
	ds_read_b128 v[220:223], v159 offset:53248
	ds_read_b128 v[224:227], v159 offset:54272
	ds_read_b128 v[228:231], v159 offset:55296
	ds_read_b128 v[232:235], v159 offset:56320
	global_load_lds_dwordx4 v[156:157], off
	s_add_i32 m0, s22, 0x2000
	s_add_u32 s2, s2, 0x40080
	v_lshl_add_u64 v[156:157], v[192:193], 0, s[12:13]
	s_addc_u32 s3, s3, 0
	s_add_i32 s22, s56, s34
	global_load_lds_dwordx4 v[156:157], off
	v_lshl_add_u64 v[156:157], s[2:3], 0, v[142:143]
	s_mov_b32 m0, s22
	s_nop 0
	global_load_lds_dwordx4 v[156:157], off
	v_lshl_add_u64 v[156:157], s[2:3], 0, v[146:147]
	s_add_i32 m0, s22, 0x2000
	s_nop 0
	global_load_lds_dwordx4 v[156:157], off
	v_lshl_add_u64 v[156:157], v[236:237], 0, s[12:13]
	s_mov_b32 m0, s42
	s_nop 0
	global_load_lds_dwordx4 v[156:157], off
	v_lshl_add_u64 v[156:157], v[238:239], 0, s[12:13]
	s_mov_b32 m0, s43
	s_nop 0
	global_load_lds_dwordx4 v[156:157], off
	s_waitcnt vmcnt(8)
	s_waitcnt lgkmcnt(0)
	s_barrier
	s_setprio 1
	v_mfma_f32_16x16x32_bf16 v[60:63], v[136:139], v[204:207], v[60:63]
	v_mfma_f32_16x16x32_bf16 v[52:55], v[166:169], v[204:207], v[52:55]
	v_mfma_f32_16x16x32_bf16 v[44:47], v[136:139], v[212:215], v[44:47]
	v_mfma_f32_16x16x32_bf16 v[36:39], v[166:169], v[212:215], v[36:39]
	v_mfma_f32_16x16x32_bf16 v[28:31], v[136:139], v[220:223], v[28:31]
	v_mfma_f32_16x16x32_bf16 v[20:23], v[166:169], v[220:223], v[20:23]
	v_mfma_f32_16x16x32_bf16 v[12:15], v[136:139], v[228:231], v[12:15]
	v_mfma_f32_16x16x32_bf16 v[4:7], v[166:169], v[228:231], v[4:7]
	v_mfma_f32_16x16x32_bf16 v[60:63], v[162:165], v[208:211], v[60:63]
	v_mfma_f32_16x16x32_bf16 v[52:55], v[178:181], v[208:211], v[52:55]
	v_mfma_f32_16x16x32_bf16 v[44:47], v[162:165], v[216:219], v[44:47]
	v_mfma_f32_16x16x32_bf16 v[36:39], v[178:181], v[216:219], v[36:39]
	v_mfma_f32_16x16x32_bf16 v[28:31], v[162:165], v[224:227], v[28:31]
	v_mfma_f32_16x16x32_bf16 v[20:23], v[178:181], v[224:227], v[20:23]
	v_mfma_f32_16x16x32_bf16 v[12:15], v[162:165], v[232:235], v[12:15]
	v_mfma_f32_16x16x32_bf16 v[4:7], v[178:181], v[232:235], v[4:7]
	v_mfma_f32_16x16x32_bf16 v[56:59], v[184:187], v[204:207], v[56:59]
	v_mfma_f32_16x16x32_bf16 v[48:51], v[196:199], v[204:207], v[48:51]
	v_mfma_f32_16x16x32_bf16 v[40:43], v[184:187], v[212:215], v[40:43]
	v_mfma_f32_16x16x32_bf16 v[32:35], v[196:199], v[212:215], v[32:35]
	v_mfma_f32_16x16x32_bf16 v[24:27], v[184:187], v[220:223], v[24:27]
	v_mfma_f32_16x16x32_bf16 v[16:19], v[196:199], v[220:223], v[16:19]
	v_mfma_f32_16x16x32_bf16 v[8:11], v[184:187], v[228:231], v[8:11]
	v_mfma_f32_16x16x32_bf16 v[0:3], v[196:199], v[228:231], v[0:3]
	v_mfma_f32_16x16x32_bf16 v[56:59], v[188:191], v[208:211], v[56:59]
	v_mfma_f32_16x16x32_bf16 v[48:51], v[200:203], v[208:211], v[48:51]
	v_mfma_f32_16x16x32_bf16 v[40:43], v[188:191], v[216:219], v[40:43]
	v_mfma_f32_16x16x32_bf16 v[32:35], v[200:203], v[216:219], v[32:35]
	v_mfma_f32_16x16x32_bf16 v[24:27], v[188:191], v[224:227], v[24:27]
	v_mfma_f32_16x16x32_bf16 v[16:19], v[200:203], v[224:227], v[16:19]
	v_mfma_f32_16x16x32_bf16 v[8:11], v[188:191], v[232:235], v[8:11]
	v_mfma_f32_16x16x32_bf16 v[0:3], v[200:203], v[232:235], v[0:3]
	s_barrier
	s_setprio 0
	s_add_i32 s54, s54, 2
	s_add_u32 s14, s14, 0x100
	s_addc_u32 s15, s15, 0
	s_add_u32 s52, s52, 0x100
	s_addc_u32 s53, s53, 0
	s_cmp_gt_u32 s54, 13
	s_cbranch_scc0 .LBB0_809

.LBB0_890:
	s_add_u32 s14, s14, 0xb0080
	s_addc_u32 s15, s15, 0
	s_add_u32 s53, s2, 0x100
	s_addc_u32 s54, s3, 0
	s_mov_b32 s55, -2
	s_waitcnt lgkmcnt(0)
	s_waitcnt vmcnt(0)
	ds_read_b128 v[128:131], v165
	ds_read_b128 v[132:135], v165 offset:1024
	ds_read_b128 v[136:139], v165 offset:2048
	ds_read_b128 v[156:159], v165 offset:3072
	ds_read_b128 v[172:175], v166
	ds_read_b128 v[176:179], v166 offset:1024
	ds_read_b128 v[180:183], v166 offset:2048
	ds_read_b128 v[184:187], v166 offset:3072
	s_add_u32 s2, s14, 0xfff50080
	s_addc_u32 s3, s15, -1
	s_cmp_eq_u32 s55, 40
	s_cselect_b32 s23, s1, s3
	s_cselect_b32 s22, s0, s2
	s_cselect_b32 s3, s21, s54
	s_cselect_b32 s2, s20, s53
	v_lshl_add_u64 v[160:161], s[14:15], 0, v[140:141]
	s_add_i32 m0, s27, 0xc000
	ds_read_b128 v[188:191], v167
	ds_read_b128 v[196:199], v167 offset:1024
	ds_read_b128 v[200:203], v167 offset:2048
	ds_read_b128 v[204:207], v167 offset:3072
	ds_read_b128 v[208:211], v167 offset:4096
	ds_read_b128 v[212:215], v167 offset:5120
	ds_read_b128 v[216:219], v167 offset:6144
	ds_read_b128 v[220:223], v167 offset:7168
	global_load_lds_dwordx4 v[160:161], off
	v_lshl_add_u64 v[160:161], s[14:15], 0, v[142:143]
	s_add_i32 m0, s27, 0xe000
	s_nop 0
	global_load_lds_dwordx4 v[160:161], off
	s_waitcnt vmcnt(8)
	s_waitcnt lgkmcnt(0)
	s_barrier
	s_setprio 1
	v_mfma_f32_16x16x32_bf16 v[124:127], v[128:131], v[188:191], 0
	v_mfma_f32_16x16x32_bf16 v[120:123], v[136:139], v[188:191], 0
	v_mfma_f32_16x16x32_bf16 v[108:111], v[128:131], v[200:203], 0
	v_mfma_f32_16x16x32_bf16 v[104:107], v[136:139], v[200:203], 0
	v_mfma_f32_16x16x32_bf16 v[92:95], v[128:131], v[208:211], 0
	v_mfma_f32_16x16x32_bf16 v[88:91], v[136:139], v[208:211], 0
	v_mfma_f32_16x16x32_bf16 v[76:79], v[128:131], v[216:219], 0
	v_mfma_f32_16x16x32_bf16 v[72:75], v[136:139], v[216:219], 0
	v_mfma_f32_16x16x32_bf16 v[124:127], v[132:135], v[196:199], v[124:127]
	v_mfma_f32_16x16x32_bf16 v[120:123], v[156:159], v[196:199], v[120:123]
	v_mfma_f32_16x16x32_bf16 v[108:111], v[132:135], v[204:207], v[108:111]
	v_mfma_f32_16x16x32_bf16 v[104:107], v[156:159], v[204:207], v[104:107]
	v_mfma_f32_16x16x32_bf16 v[92:95], v[132:135], v[212:215], v[92:95]
	v_mfma_f32_16x16x32_bf16 v[88:91], v[156:159], v[212:215], v[88:91]
	v_mfma_f32_16x16x32_bf16 v[76:79], v[132:135], v[220:223], v[76:79]
	v_mfma_f32_16x16x32_bf16 v[72:75], v[156:159], v[220:223], v[72:75]
	v_mfma_f32_16x16x32_bf16 v[116:119], v[172:175], v[188:191], 0
	v_mfma_f32_16x16x32_bf16 v[112:115], v[180:183], v[188:191], 0
	v_mfma_f32_16x16x32_bf16 v[100:103], v[172:175], v[200:203], 0
	v_mfma_f32_16x16x32_bf16 v[96:99], v[180:183], v[200:203], 0
	v_mfma_f32_16x16x32_bf16 v[84:87], v[172:175], v[208:211], 0
	v_mfma_f32_16x16x32_bf16 v[80:83], v[180:183], v[208:211], 0
	v_mfma_f32_16x16x32_bf16 v[68:71], v[172:175], v[216:219], 0
	v_mfma_f32_16x16x32_bf16 v[64:67], v[180:183], v[216:219], 0
	v_mfma_f32_16x16x32_bf16 v[116:119], v[176:179], v[196:199], v[116:119]
	v_mfma_f32_16x16x32_bf16 v[112:115], v[184:187], v[196:199], v[112:115]
	v_mfma_f32_16x16x32_bf16 v[100:103], v[176:179], v[204:207], v[100:103]
	v_mfma_f32_16x16x32_bf16 v[96:99], v[184:187], v[204:207], v[96:99]
	v_mfma_f32_16x16x32_bf16 v[84:87], v[176:179], v[212:215], v[84:87]
	v_mfma_f32_16x16x32_bf16 v[80:83], v[184:187], v[212:215], v[80:83]
	v_mfma_f32_16x16x32_bf16 v[68:71], v[176:179], v[220:223], v[68:71]
	v_mfma_f32_16x16x32_bf16 v[64:67], v[184:187], v[220:223], v[64:67]
	s_barrier
	s_setprio 0
	s_add_i32 s56, s43, s26
	v_lshl_add_u64 v[160:161], s[2:3], 0, v[150:151]
	s_mov_b32 m0, s56
	ds_read_b128 v[188:191], v167 offset:16384
	ds_read_b128 v[196:199], v167 offset:17408
	ds_read_b128 v[200:203], v167 offset:18432
	ds_read_b128 v[204:207], v167 offset:19456
	ds_read_b128 v[208:211], v167 offset:20480
	ds_read_b128 v[212:215], v167 offset:21504
	ds_read_b128 v[216:219], v167 offset:22528
	ds_read_b128 v[220:223], v167 offset:23552
	global_load_lds_dwordx4 v[160:161], off
	s_add_i32 m0, s56, 0x2000
	s_add_u32 s56, s2, 0xb0000
	v_lshl_add_u64 v[192:193], s[2:3], 0, v[154:155]
	s_addc_u32 s57, s3, 0
	s_add_i32 s58, s44, s26
	global_load_lds_dwordx4 v[192:193], off
	v_lshl_add_u64 v[224:225], s[56:57], 0, v[150:151]
	s_mov_b32 m0, s58
	v_lshl_add_u64 v[226:227], s[22:23], 0, v[152:153]
	global_load_lds_dwordx4 v[224:225], off
	v_lshl_add_u64 v[224:225], s[56:57], 0, v[154:155]
	s_add_i32 m0, s58, 0x2000
	s_nop 0
	global_load_lds_dwordx4 v[224:225], off
	v_lshl_add_u64 v[224:225], s[22:23], 0, v[148:149]
	s_mov_b32 m0, s27
	s_nop 0
	global_load_lds_dwordx4 v[224:225], off
	s_mov_b32 m0, s28
	s_nop 0
	global_load_lds_dwordx4 v[226:227], off
	s_waitcnt vmcnt(8)
	s_waitcnt lgkmcnt(0)
	s_barrier
	s_setprio 1
	v_mfma_f32_16x16x32_bf16 v[60:63], v[128:131], v[188:191], 0
	v_mfma_f32_16x16x32_bf16 v[56:59], v[136:139], v[188:191], 0
	v_mfma_f32_16x16x32_bf16 v[44:47], v[128:131], v[200:203], 0
	v_mfma_f32_16x16x32_bf16 v[40:43], v[136:139], v[200:203], 0
	v_mfma_f32_16x16x32_bf16 v[28:31], v[128:131], v[208:211], 0
	v_mfma_f32_16x16x32_bf16 v[24:27], v[136:139], v[208:211], 0
	v_mfma_f32_16x16x32_bf16 v[12:15], v[128:131], v[216:219], 0
	v_mfma_f32_16x16x32_bf16 v[8:11], v[136:139], v[216:219], 0
	v_mfma_f32_16x16x32_bf16 v[60:63], v[132:135], v[196:199], v[60:63]
	v_mfma_f32_16x16x32_bf16 v[56:59], v[156:159], v[196:199], v[56:59]
	v_mfma_f32_16x16x32_bf16 v[44:47], v[132:135], v[204:207], v[44:47]
	v_mfma_f32_16x16x32_bf16 v[40:43], v[156:159], v[204:207], v[40:43]
	v_mfma_f32_16x16x32_bf16 v[28:31], v[132:135], v[212:215], v[28:31]
	v_mfma_f32_16x16x32_bf16 v[24:27], v[156:159], v[212:215], v[24:27]
	v_mfma_f32_16x16x32_bf16 v[12:15], v[132:135], v[220:223], v[12:15]
	v_mfma_f32_16x16x32_bf16 v[8:11], v[156:159], v[220:223], v[8:11]
	v_mfma_f32_16x16x32_bf16 v[52:55], v[172:175], v[188:191], 0
	v_mfma_f32_16x16x32_bf16 v[48:51], v[180:183], v[188:191], 0
	v_mfma_f32_16x16x32_bf16 v[36:39], v[172:175], v[200:203], 0
	v_mfma_f32_16x16x32_bf16 v[32:35], v[180:183], v[200:203], 0
	v_mfma_f32_16x16x32_bf16 v[20:23], v[172:175], v[208:211], 0
	v_mfma_f32_16x16x32_bf16 v[16:19], v[180:183], v[208:211], 0
	v_mfma_f32_16x16x32_bf16 v[4:7], v[172:175], v[216:219], 0
	v_mfma_f32_16x16x32_bf16 v[0:3], v[180:183], v[216:219], 0
	v_mfma_f32_16x16x32_bf16 v[52:55], v[176:179], v[196:199], v[52:55]
	v_mfma_f32_16x16x32_bf16 v[48:51], v[184:187], v[196:199], v[48:51]
	v_mfma_f32_16x16x32_bf16 v[36:39], v[176:179], v[204:207], v[36:39]
	v_mfma_f32_16x16x32_bf16 v[32:35], v[184:187], v[204:207], v[32:35]
	v_mfma_f32_16x16x32_bf16 v[20:23], v[176:179], v[212:215], v[20:23]
	v_mfma_f32_16x16x32_bf16 v[16:19], v[184:187], v[212:215], v[16:19]
	v_mfma_f32_16x16x32_bf16 v[4:7], v[176:179], v[220:223], v[4:7]
	v_mfma_f32_16x16x32_bf16 v[0:3], v[184:187], v[220:223], v[0:3]
	s_barrier
	s_setprio 0
	s_add_i32 s56, 0, 0x18000
	s_add_i32 s57, 0, 0x1c000
	v_add_u32_e32 v156, s56, v162
	v_add_u32_e32 v169, s57, v162
	ds_read_b128 v[128:131], v156
	ds_read_b128 v[132:135], v156 offset:1024
	ds_read_b128 v[136:139], v156 offset:2048
	ds_read_b128 v[156:159], v156 offset:3072
	ds_read_b128 v[172:175], v169
	ds_read_b128 v[176:179], v169 offset:1024
	ds_read_b128 v[180:183], v169 offset:2048
	ds_read_b128 v[184:187], v169 offset:3072
	s_add_u32 s22, s22, 0xb0000
	s_addc_u32 s23, s23, 0
	s_mov_b32 m0, s29
	v_lshl_add_u64 v[228:229], s[22:23], 0, v[148:149]
	ds_read_b128 v[188:191], v167 offset:32768
	ds_read_b128 v[196:199], v167 offset:33792
	ds_read_b128 v[200:203], v167 offset:34816
	ds_read_b128 v[204:207], v167 offset:35840
	ds_read_b128 v[208:211], v167 offset:36864
	ds_read_b128 v[212:215], v167 offset:37888
	ds_read_b128 v[216:219], v167 offset:38912
	ds_read_b128 v[220:223], v167 offset:39936
	global_load_lds_dwordx4 v[228:229], off
	v_lshl_add_u64 v[228:229], s[22:23], 0, v[152:153]
	s_mov_b32 m0, s30
	s_nop 0
	global_load_lds_dwordx4 v[228:229], off
	s_waitcnt vmcnt(8)
	s_waitcnt lgkmcnt(0)
	s_barrier
	s_setprio 1
	v_mfma_f32_16x16x32_bf16 v[124:127], v[128:131], v[188:191], v[124:127]
	v_mfma_f32_16x16x32_bf16 v[120:123], v[136:139], v[188:191], v[120:123]
	v_mfma_f32_16x16x32_bf16 v[108:111], v[128:131], v[200:203], v[108:111]
	v_mfma_f32_16x16x32_bf16 v[104:107], v[136:139], v[200:203], v[104:107]
	v_mfma_f32_16x16x32_bf16 v[92:95], v[128:131], v[208:211], v[92:95]
	v_mfma_f32_16x16x32_bf16 v[88:91], v[136:139], v[208:211], v[88:91]
	v_mfma_f32_16x16x32_bf16 v[76:79], v[128:131], v[216:219], v[76:79]
	v_mfma_f32_16x16x32_bf16 v[72:75], v[136:139], v[216:219], v[72:75]
	v_mfma_f32_16x16x32_bf16 v[124:127], v[132:135], v[196:199], v[124:127]
	v_mfma_f32_16x16x32_bf16 v[120:123], v[156:159], v[196:199], v[120:123]
	v_mfma_f32_16x16x32_bf16 v[108:111], v[132:135], v[204:207], v[108:111]
	v_mfma_f32_16x16x32_bf16 v[104:107], v[156:159], v[204:207], v[104:107]
	v_mfma_f32_16x16x32_bf16 v[92:95], v[132:135], v[212:215], v[92:95]
	v_mfma_f32_16x16x32_bf16 v[88:91], v[156:159], v[212:215], v[88:91]
	v_mfma_f32_16x16x32_bf16 v[76:79], v[132:135], v[220:223], v[76:79]
	v_mfma_f32_16x16x32_bf16 v[72:75], v[156:159], v[220:223], v[72:75]
	v_mfma_f32_16x16x32_bf16 v[116:119], v[172:175], v[188:191], v[116:119]
	v_mfma_f32_16x16x32_bf16 v[112:115], v[180:183], v[188:191], v[112:115]
	v_mfma_f32_16x16x32_bf16 v[100:103], v[172:175], v[200:203], v[100:103]
	v_mfma_f32_16x16x32_bf16 v[96:99], v[180:183], v[200:203], v[96:99]
	v_mfma_f32_16x16x32_bf16 v[84:87], v[172:175], v[208:211], v[84:87]
	v_mfma_f32_16x16x32_bf16 v[80:83], v[180:183], v[208:211], v[80:83]
	v_mfma_f32_16x16x32_bf16 v[68:71], v[172:175], v[216:219], v[68:71]
	v_mfma_f32_16x16x32_bf16 v[64:67], v[180:183], v[216:219], v[64:67]
	v_mfma_f32_16x16x32_bf16 v[116:119], v[176:179], v[196:199], v[116:119]
	v_mfma_f32_16x16x32_bf16 v[112:115], v[184:187], v[196:199], v[112:115]
	v_mfma_f32_16x16x32_bf16 v[100:103], v[176:179], v[204:207], v[100:103]
	v_mfma_f32_16x16x32_bf16 v[96:99], v[184:187], v[204:207], v[96:99]
	v_mfma_f32_16x16x32_bf16 v[84:87], v[176:179], v[212:215], v[84:87]
	v_mfma_f32_16x16x32_bf16 v[80:83], v[184:187], v[212:215], v[80:83]
	v_mfma_f32_16x16x32_bf16 v[68:71], v[176:179], v[220:223], v[68:71]
	v_mfma_f32_16x16x32_bf16 v[64:67], v[184:187], v[220:223], v[64:67]
	s_barrier
	s_setprio 0
	s_add_i32 s22, s56, s26
	v_lshl_add_u64 v[160:161], v[160:161], 0, s[12:13]
	s_mov_b32 m0, s22
	ds_read_b128 v[188:191], v167 offset:49152
	ds_read_b128 v[196:199], v167 offset:50176
	ds_read_b128 v[200:203], v167 offset:51200
	ds_read_b128 v[204:207], v167 offset:52224
	ds_read_b128 v[208:211], v167 offset:53248
	ds_read_b128 v[212:215], v167 offset:54272
	ds_read_b128 v[216:219], v167 offset:55296
	ds_read_b128 v[220:223], v167 offset:56320
	global_load_lds_dwordx4 v[160:161], off
	s_add_i32 m0, s22, 0x2000
	s_add_u32 s2, s2, 0xb0080
	v_lshl_add_u64 v[160:161], v[192:193], 0, s[12:13]
	s_addc_u32 s3, s3, 0
	s_add_i32 s22, s57, s26
	global_load_lds_dwordx4 v[160:161], off
	v_lshl_add_u64 v[160:161], s[2:3], 0, v[150:151]
	s_mov_b32 m0, s22
	s_nop 0
	global_load_lds_dwordx4 v[160:161], off
	v_lshl_add_u64 v[160:161], s[2:3], 0, v[154:155]
	s_add_i32 m0, s22, 0x2000
	s_nop 0
	global_load_lds_dwordx4 v[160:161], off
	v_lshl_add_u64 v[160:161], v[224:225], 0, s[12:13]
	s_mov_b32 m0, s36
	s_nop 0
	global_load_lds_dwordx4 v[160:161], off
	v_lshl_add_u64 v[160:161], v[226:227], 0, s[12:13]
	s_mov_b32 m0, s37
	s_nop 0
	global_load_lds_dwordx4 v[160:161], off
	s_waitcnt vmcnt(8)
	s_waitcnt lgkmcnt(0)
	s_barrier
	s_setprio 1
	v_mfma_f32_16x16x32_bf16 v[60:63], v[128:131], v[188:191], v[60:63]
	v_mfma_f32_16x16x32_bf16 v[56:59], v[136:139], v[188:191], v[56:59]
	v_mfma_f32_16x16x32_bf16 v[44:47], v[128:131], v[200:203], v[44:47]
	v_mfma_f32_16x16x32_bf16 v[40:43], v[136:139], v[200:203], v[40:43]
	v_mfma_f32_16x16x32_bf16 v[28:31], v[128:131], v[208:211], v[28:31]
	v_mfma_f32_16x16x32_bf16 v[24:27], v[136:139], v[208:211], v[24:27]
	v_mfma_f32_16x16x32_bf16 v[12:15], v[128:131], v[216:219], v[12:15]
	v_mfma_f32_16x16x32_bf16 v[8:11], v[136:139], v[216:219], v[8:11]
	v_mfma_f32_16x16x32_bf16 v[60:63], v[132:135], v[196:199], v[60:63]
	v_mfma_f32_16x16x32_bf16 v[56:59], v[156:159], v[196:199], v[56:59]
	v_mfma_f32_16x16x32_bf16 v[44:47], v[132:135], v[204:207], v[44:47]
	v_mfma_f32_16x16x32_bf16 v[40:43], v[156:159], v[204:207], v[40:43]
	v_mfma_f32_16x16x32_bf16 v[28:31], v[132:135], v[212:215], v[28:31]
	v_mfma_f32_16x16x32_bf16 v[24:27], v[156:159], v[212:215], v[24:27]
	v_mfma_f32_16x16x32_bf16 v[12:15], v[132:135], v[220:223], v[12:15]
	v_mfma_f32_16x16x32_bf16 v[8:11], v[156:159], v[220:223], v[8:11]
	v_mfma_f32_16x16x32_bf16 v[52:55], v[172:175], v[188:191], v[52:55]
	v_mfma_f32_16x16x32_bf16 v[48:51], v[180:183], v[188:191], v[48:51]
	v_mfma_f32_16x16x32_bf16 v[36:39], v[172:175], v[200:203], v[36:39]
	v_mfma_f32_16x16x32_bf16 v[32:35], v[180:183], v[200:203], v[32:35]
	v_mfma_f32_16x16x32_bf16 v[20:23], v[172:175], v[208:211], v[20:23]
	v_mfma_f32_16x16x32_bf16 v[16:19], v[180:183], v[208:211], v[16:19]
	v_mfma_f32_16x16x32_bf16 v[4:7], v[172:175], v[216:219], v[4:7]
	v_mfma_f32_16x16x32_bf16 v[0:3], v[180:183], v[216:219], v[0:3]
	v_mfma_f32_16x16x32_bf16 v[52:55], v[176:179], v[196:199], v[52:55]
	v_mfma_f32_16x16x32_bf16 v[48:51], v[184:187], v[196:199], v[48:51]
	v_mfma_f32_16x16x32_bf16 v[36:39], v[176:179], v[204:207], v[36:39]
	v_mfma_f32_16x16x32_bf16 v[32:35], v[184:187], v[204:207], v[32:35]
	v_mfma_f32_16x16x32_bf16 v[20:23], v[176:179], v[212:215], v[20:23]
	v_mfma_f32_16x16x32_bf16 v[16:19], v[184:187], v[212:215], v[16:19]
	v_mfma_f32_16x16x32_bf16 v[4:7], v[176:179], v[220:223], v[4:7]
	v_mfma_f32_16x16x32_bf16 v[0:3], v[184:187], v[220:223], v[0:3]
	s_barrier
	s_setprio 0
	s_add_i32 s55, s55, 2
	s_add_u32 s14, s14, 0x100
	s_addc_u32 s15, s15, 0
	s_add_u32 s53, s53, 0x100
	s_addc_u32 s54, s54, 0
	s_cmp_gt_u32 s55, 41
	s_cbranch_scc1 .Lgemm_kdone_6
.LBB0_891:
	ds_read_b128 v[128:131], v165
	ds_read_b128 v[132:135], v165 offset:1024
	ds_read_b128 v[136:139], v165 offset:2048
	ds_read_b128 v[156:159], v165 offset:3072
	ds_read_b128 v[172:175], v166
	ds_read_b128 v[176:179], v166 offset:1024
	ds_read_b128 v[180:183], v166 offset:2048
	ds_read_b128 v[184:187], v166 offset:3072
	s_add_u32 s2, s14, 0xfff50080
	s_addc_u32 s3, s15, -1
	s_cmp_eq_u32 s55, 40
	s_cselect_b32 s23, s1, s3
	s_cselect_b32 s22, s0, s2
	s_cselect_b32 s3, s21, s54
	s_cselect_b32 s2, s20, s53
	v_lshl_add_u64 v[160:161], s[14:15], 0, v[140:141]
	s_add_i32 m0, s27, 0xc000
	ds_read_b128 v[188:191], v167
	ds_read_b128 v[196:199], v167 offset:1024
	ds_read_b128 v[200:203], v167 offset:2048
	ds_read_b128 v[204:207], v167 offset:3072
	ds_read_b128 v[208:211], v167 offset:4096
	ds_read_b128 v[212:215], v167 offset:5120
	ds_read_b128 v[216:219], v167 offset:6144
	ds_read_b128 v[220:223], v167 offset:7168
	global_load_lds_dwordx4 v[160:161], off
	v_lshl_add_u64 v[160:161], s[14:15], 0, v[142:143]
	s_add_i32 m0, s27, 0xe000
	s_nop 0
	global_load_lds_dwordx4 v[160:161], off
	s_waitcnt vmcnt(8)
	s_waitcnt lgkmcnt(0)
	s_barrier
	s_setprio 1
	v_mfma_f32_16x16x32_bf16 v[124:127], v[128:131], v[188:191], v[124:127]
	v_mfma_f32_16x16x32_bf16 v[120:123], v[136:139], v[188:191], v[120:123]
	v_mfma_f32_16x16x32_bf16 v[108:111], v[128:131], v[200:203], v[108:111]
	v_mfma_f32_16x16x32_bf16 v[104:107], v[136:139], v[200:203], v[104:107]
	v_mfma_f32_16x16x32_bf16 v[92:95], v[128:131], v[208:211], v[92:95]
	v_mfma_f32_16x16x32_bf16 v[88:91], v[136:139], v[208:211], v[88:91]
	v_mfma_f32_16x16x32_bf16 v[76:79], v[128:131], v[216:219], v[76:79]
	v_mfma_f32_16x16x32_bf16 v[72:75], v[136:139], v[216:219], v[72:75]
	v_mfma_f32_16x16x32_bf16 v[124:127], v[132:135], v[196:199], v[124:127]
	v_mfma_f32_16x16x32_bf16 v[120:123], v[156:159], v[196:199], v[120:123]
	v_mfma_f32_16x16x32_bf16 v[108:111], v[132:135], v[204:207], v[108:111]
	v_mfma_f32_16x16x32_bf16 v[104:107], v[156:159], v[204:207], v[104:107]
	v_mfma_f32_16x16x32_bf16 v[92:95], v[132:135], v[212:215], v[92:95]
	v_mfma_f32_16x16x32_bf16 v[88:91], v[156:159], v[212:215], v[88:91]
	v_mfma_f32_16x16x32_bf16 v[76:79], v[132:135], v[220:223], v[76:79]
	v_mfma_f32_16x16x32_bf16 v[72:75], v[156:159], v[220:223], v[72:75]
	v_mfma_f32_16x16x32_bf16 v[116:119], v[172:175], v[188:191], v[116:119]
	v_mfma_f32_16x16x32_bf16 v[112:115], v[180:183], v[188:191], v[112:115]
	v_mfma_f32_16x16x32_bf16 v[100:103], v[172:175], v[200:203], v[100:103]
	v_mfma_f32_16x16x32_bf16 v[96:99], v[180:183], v[200:203], v[96:99]
	v_mfma_f32_16x16x32_bf16 v[84:87], v[172:175], v[208:211], v[84:87]
	v_mfma_f32_16x16x32_bf16 v[80:83], v[180:183], v[208:211], v[80:83]
	v_mfma_f32_16x16x32_bf16 v[68:71], v[172:175], v[216:219], v[68:71]
	v_mfma_f32_16x16x32_bf16 v[64:67], v[180:183], v[216:219], v[64:67]
	v_mfma_f32_16x16x32_bf16 v[116:119], v[176:179], v[196:199], v[116:119]
	v_mfma_f32_16x16x32_bf16 v[112:115], v[184:187], v[196:199], v[112:115]
	v_mfma_f32_16x16x32_bf16 v[100:103], v[176:179], v[204:207], v[100:103]
	v_mfma_f32_16x16x32_bf16 v[96:99], v[184:187], v[204:207], v[96:99]
	v_mfma_f32_16x16x32_bf16 v[84:87], v[176:179], v[212:215], v[84:87]
	v_mfma_f32_16x16x32_bf16 v[80:83], v[184:187], v[212:215], v[80:83]
	v_mfma_f32_16x16x32_bf16 v[68:71], v[176:179], v[220:223], v[68:71]
	v_mfma_f32_16x16x32_bf16 v[64:67], v[184:187], v[220:223], v[64:67]
	s_barrier
	s_setprio 0
	s_add_i32 s56, s43, s26
	v_lshl_add_u64 v[160:161], s[2:3], 0, v[150:151]
	s_mov_b32 m0, s56
	ds_read_b128 v[188:191], v167 offset:16384
	ds_read_b128 v[196:199], v167 offset:17408
	ds_read_b128 v[200:203], v167 offset:18432
	ds_read_b128 v[204:207], v167 offset:19456
	ds_read_b128 v[208:211], v167 offset:20480
	ds_read_b128 v[212:215], v167 offset:21504
	ds_read_b128 v[216:219], v167 offset:22528
	ds_read_b128 v[220:223], v167 offset:23552
	global_load_lds_dwordx4 v[160:161], off
	s_add_i32 m0, s56, 0x2000
	s_add_u32 s56, s2, 0xb0000
	v_lshl_add_u64 v[192:193], s[2:3], 0, v[154:155]
	s_addc_u32 s57, s3, 0
	s_add_i32 s58, s44, s26
	global_load_lds_dwordx4 v[192:193], off
	v_lshl_add_u64 v[224:225], s[56:57], 0, v[150:151]
	s_mov_b32 m0, s58
	v_lshl_add_u64 v[226:227], s[22:23], 0, v[152:153]
	global_load_lds_dwordx4 v[224:225], off
	v_lshl_add_u64 v[224:225], s[56:57], 0, v[154:155]
	s_add_i32 m0, s58, 0x2000
	s_nop 0
	global_load_lds_dwordx4 v[224:225], off
	v_lshl_add_u64 v[224:225], s[22:23], 0, v[148:149]
	s_mov_b32 m0, s27
	s_nop 0
	global_load_lds_dwordx4 v[224:225], off
	s_mov_b32 m0, s28
	s_nop 0
	global_load_lds_dwordx4 v[226:227], off
	s_waitcnt vmcnt(8)
	s_waitcnt lgkmcnt(0)
	s_barrier
	s_setprio 1
	v_mfma_f32_16x16x32_bf16 v[60:63], v[128:131], v[188:191], v[60:63]
	v_mfma_f32_16x16x32_bf16 v[56:59], v[136:139], v[188:191], v[56:59]
	v_mfma_f32_16x16x32_bf16 v[44:47], v[128:131], v[200:203], v[44:47]
	v_mfma_f32_16x16x32_bf16 v[40:43], v[136:139], v[200:203], v[40:43]
	v_mfma_f32_16x16x32_bf16 v[28:31], v[128:131], v[208:211], v[28:31]
	v_mfma_f32_16x16x32_bf16 v[24:27], v[136:139], v[208:211], v[24:27]
	v_mfma_f32_16x16x32_bf16 v[12:15], v[128:131], v[216:219], v[12:15]
	v_mfma_f32_16x16x32_bf16 v[8:11], v[136:139], v[216:219], v[8:11]
	v_mfma_f32_16x16x32_bf16 v[60:63], v[132:135], v[196:199], v[60:63]
	v_mfma_f32_16x16x32_bf16 v[56:59], v[156:159], v[196:199], v[56:59]
	v_mfma_f32_16x16x32_bf16 v[44:47], v[132:135], v[204:207], v[44:47]
	v_mfma_f32_16x16x32_bf16 v[40:43], v[156:159], v[204:207], v[40:43]
	v_mfma_f32_16x16x32_bf16 v[28:31], v[132:135], v[212:215], v[28:31]
	v_mfma_f32_16x16x32_bf16 v[24:27], v[156:159], v[212:215], v[24:27]
	v_mfma_f32_16x16x32_bf16 v[12:15], v[132:135], v[220:223], v[12:15]
	v_mfma_f32_16x16x32_bf16 v[8:11], v[156:159], v[220:223], v[8:11]
	v_mfma_f32_16x16x32_bf16 v[52:55], v[172:175], v[188:191], v[52:55]
	v_mfma_f32_16x16x32_bf16 v[48:51], v[180:183], v[188:191], v[48:51]
	v_mfma_f32_16x16x32_bf16 v[36:39], v[172:175], v[200:203], v[36:39]
	v_mfma_f32_16x16x32_bf16 v[32:35], v[180:183], v[200:203], v[32:35]
	v_mfma_f32_16x16x32_bf16 v[20:23], v[172:175], v[208:211], v[20:23]
	v_mfma_f32_16x16x32_bf16 v[16:19], v[180:183], v[208:211], v[16:19]
	v_mfma_f32_16x16x32_bf16 v[4:7], v[172:175], v[216:219], v[4:7]
	v_mfma_f32_16x16x32_bf16 v[0:3], v[180:183], v[216:219], v[0:3]
	v_mfma_f32_16x16x32_bf16 v[52:55], v[176:179], v[196:199], v[52:55]
	v_mfma_f32_16x16x32_bf16 v[48:51], v[184:187], v[196:199], v[48:51]
	v_mfma_f32_16x16x32_bf16 v[36:39], v[176:179], v[204:207], v[36:39]
	v_mfma_f32_16x16x32_bf16 v[32:35], v[184:187], v[204:207], v[32:35]
	v_mfma_f32_16x16x32_bf16 v[20:23], v[176:179], v[212:215], v[20:23]
	v_mfma_f32_16x16x32_bf16 v[16:19], v[184:187], v[212:215], v[16:19]
	v_mfma_f32_16x16x32_bf16 v[4:7], v[176:179], v[220:223], v[4:7]
	v_mfma_f32_16x16x32_bf16 v[0:3], v[184:187], v[220:223], v[0:3]
	s_barrier
	s_setprio 0
	s_add_i32 s56, 0, 0x18000
	s_add_i32 s57, 0, 0x1c000
	v_add_u32_e32 v156, s56, v162
	v_add_u32_e32 v169, s57, v162
	ds_read_b128 v[128:131], v156
	ds_read_b128 v[132:135], v156 offset:1024
	ds_read_b128 v[136:139], v156 offset:2048
	ds_read_b128 v[156:159], v156 offset:3072
	ds_read_b128 v[172:175], v169
	ds_read_b128 v[176:179], v169 offset:1024
	ds_read_b128 v[180:183], v169 offset:2048
	ds_read_b128 v[184:187], v169 offset:3072
	s_add_u32 s22, s22, 0xb0000
	s_addc_u32 s23, s23, 0
	s_mov_b32 m0, s29
	v_lshl_add_u64 v[228:229], s[22:23], 0, v[148:149]
	ds_read_b128 v[188:191], v167 offset:32768
	ds_read_b128 v[196:199], v167 offset:33792
	ds_read_b128 v[200:203], v167 offset:34816
	ds_read_b128 v[204:207], v167 offset:35840
	ds_read_b128 v[208:211], v167 offset:36864
	ds_read_b128 v[212:215], v167 offset:37888
	ds_read_b128 v[216:219], v167 offset:38912
	ds_read_b128 v[220:223], v167 offset:39936
	global_load_lds_dwordx4 v[228:229], off
	v_lshl_add_u64 v[228:229], s[22:23], 0, v[152:153]
	s_mov_b32 m0, s30
	s_nop 0
	global_load_lds_dwordx4 v[228:229], off
	s_waitcnt vmcnt(8)
	s_waitcnt lgkmcnt(0)
	s_barrier
	s_setprio 1
	v_mfma_f32_16x16x32_bf16 v[124:127], v[128:131], v[188:191], v[124:127]
	v_mfma_f32_16x16x32_bf16 v[120:123], v[136:139], v[188:191], v[120:123]
	v_mfma_f32_16x16x32_bf16 v[108:111], v[128:131], v[200:203], v[108:111]
	v_mfma_f32_16x16x32_bf16 v[104:107], v[136:139], v[200:203], v[104:107]
	v_mfma_f32_16x16x32_bf16 v[92:95], v[128:131], v[208:211], v[92:95]
	v_mfma_f32_16x16x32_bf16 v[88:91], v[136:139], v[208:211], v[88:91]
	v_mfma_f32_16x16x32_bf16 v[76:79], v[128:131], v[216:219], v[76:79]
	v_mfma_f32_16x16x32_bf16 v[72:75], v[136:139], v[216:219], v[72:75]
	v_mfma_f32_16x16x32_bf16 v[124:127], v[132:135], v[196:199], v[124:127]
	v_mfma_f32_16x16x32_bf16 v[120:123], v[156:159], v[196:199], v[120:123]
	v_mfma_f32_16x16x32_bf16 v[108:111], v[132:135], v[204:207], v[108:111]
	v_mfma_f32_16x16x32_bf16 v[104:107], v[156:159], v[204:207], v[104:107]
	v_mfma_f32_16x16x32_bf16 v[92:95], v[132:135], v[212:215], v[92:95]
	v_mfma_f32_16x16x32_bf16 v[88:91], v[156:159], v[212:215], v[88:91]
	v_mfma_f32_16x16x32_bf16 v[76:79], v[132:135], v[220:223], v[76:79]
	v_mfma_f32_16x16x32_bf16 v[72:75], v[156:159], v[220:223], v[72:75]
	v_mfma_f32_16x16x32_bf16 v[116:119], v[172:175], v[188:191], v[116:119]
	v_mfma_f32_16x16x32_bf16 v[112:115], v[180:183], v[188:191], v[112:115]
	v_mfma_f32_16x16x32_bf16 v[100:103], v[172:175], v[200:203], v[100:103]
	v_mfma_f32_16x16x32_bf16 v[96:99], v[180:183], v[200:203], v[96:99]
	v_mfma_f32_16x16x32_bf16 v[84:87], v[172:175], v[208:211], v[84:87]
	v_mfma_f32_16x16x32_bf16 v[80:83], v[180:183], v[208:211], v[80:83]
	v_mfma_f32_16x16x32_bf16 v[68:71], v[172:175], v[216:219], v[68:71]
	v_mfma_f32_16x16x32_bf16 v[64:67], v[180:183], v[216:219], v[64:67]
	v_mfma_f32_16x16x32_bf16 v[116:119], v[176:179], v[196:199], v[116:119]
	v_mfma_f32_16x16x32_bf16 v[112:115], v[184:187], v[196:199], v[112:115]
	v_mfma_f32_16x16x32_bf16 v[100:103], v[176:179], v[204:207], v[100:103]
	v_mfma_f32_16x16x32_bf16 v[96:99], v[184:187], v[204:207], v[96:99]
	v_mfma_f32_16x16x32_bf16 v[84:87], v[176:179], v[212:215], v[84:87]
	v_mfma_f32_16x16x32_bf16 v[80:83], v[184:187], v[212:215], v[80:83]
	v_mfma_f32_16x16x32_bf16 v[68:71], v[176:179], v[220:223], v[68:71]
	v_mfma_f32_16x16x32_bf16 v[64:67], v[184:187], v[220:223], v[64:67]
	s_barrier
	s_setprio 0
	s_add_i32 s22, s56, s26
	v_lshl_add_u64 v[160:161], v[160:161], 0, s[12:13]
	s_mov_b32 m0, s22
	ds_read_b128 v[188:191], v167 offset:49152
	ds_read_b128 v[196:199], v167 offset:50176
	ds_read_b128 v[200:203], v167 offset:51200
	ds_read_b128 v[204:207], v167 offset:52224
	ds_read_b128 v[208:211], v167 offset:53248
	ds_read_b128 v[212:215], v167 offset:54272
	ds_read_b128 v[216:219], v167 offset:55296
	ds_read_b128 v[220:223], v167 offset:56320
	global_load_lds_dwordx4 v[160:161], off
	s_add_i32 m0, s22, 0x2000
	s_add_u32 s2, s2, 0xb0080
	v_lshl_add_u64 v[160:161], v[192:193], 0, s[12:13]
	s_addc_u32 s3, s3, 0
	s_add_i32 s22, s57, s26
	global_load_lds_dwordx4 v[160:161], off
	v_lshl_add_u64 v[160:161], s[2:3], 0, v[150:151]
	s_mov_b32 m0, s22
	s_nop 0
	global_load_lds_dwordx4 v[160:161], off
	v_lshl_add_u64 v[160:161], s[2:3], 0, v[154:155]
	s_add_i32 m0, s22, 0x2000
	s_nop 0
	global_load_lds_dwordx4 v[160:161], off
	v_lshl_add_u64 v[160:161], v[224:225], 0, s[12:13]
	s_mov_b32 m0, s36
	s_nop 0
	global_load_lds_dwordx4 v[160:161], off
	v_lshl_add_u64 v[160:161], v[226:227], 0, s[12:13]
	s_mov_b32 m0, s37
	s_nop 0
	global_load_lds_dwordx4 v[160:161], off
	s_waitcnt vmcnt(8)
	s_waitcnt lgkmcnt(0)
	s_barrier
	s_setprio 1
	v_mfma_f32_16x16x32_bf16 v[60:63], v[128:131], v[188:191], v[60:63]
	v_mfma_f32_16x16x32_bf16 v[56:59], v[136:139], v[188:191], v[56:59]
	v_mfma_f32_16x16x32_bf16 v[44:47], v[128:131], v[200:203], v[44:47]
	v_mfma_f32_16x16x32_bf16 v[40:43], v[136:139], v[200:203], v[40:43]
	v_mfma_f32_16x16x32_bf16 v[28:31], v[128:131], v[208:211], v[28:31]
	v_mfma_f32_16x16x32_bf16 v[24:27], v[136:139], v[208:211], v[24:27]
	v_mfma_f32_16x16x32_bf16 v[12:15], v[128:131], v[216:219], v[12:15]
	v_mfma_f32_16x16x32_bf16 v[8:11], v[136:139], v[216:219], v[8:11]
	v_mfma_f32_16x16x32_bf16 v[60:63], v[132:135], v[196:199], v[60:63]
	v_mfma_f32_16x16x32_bf16 v[56:59], v[156:159], v[196:199], v[56:59]
	v_mfma_f32_16x16x32_bf16 v[44:47], v[132:135], v[204:207], v[44:47]
	v_mfma_f32_16x16x32_bf16 v[40:43], v[156:159], v[204:207], v[40:43]
	v_mfma_f32_16x16x32_bf16 v[28:31], v[132:135], v[212:215], v[28:31]
	v_mfma_f32_16x16x32_bf16 v[24:27], v[156:159], v[212:215], v[24:27]
	v_mfma_f32_16x16x32_bf16 v[12:15], v[132:135], v[220:223], v[12:15]
	v_mfma_f32_16x16x32_bf16 v[8:11], v[156:159], v[220:223], v[8:11]
	v_mfma_f32_16x16x32_bf16 v[52:55], v[172:175], v[188:191], v[52:55]
	v_mfma_f32_16x16x32_bf16 v[48:51], v[180:183], v[188:191], v[48:51]
	v_mfma_f32_16x16x32_bf16 v[36:39], v[172:175], v[200:203], v[36:39]
	v_mfma_f32_16x16x32_bf16 v[32:35], v[180:183], v[200:203], v[32:35]
	v_mfma_f32_16x16x32_bf16 v[20:23], v[172:175], v[208:211], v[20:23]
	v_mfma_f32_16x16x32_bf16 v[16:19], v[180:183], v[208:211], v[16:19]
	v_mfma_f32_16x16x32_bf16 v[4:7], v[172:175], v[216:219], v[4:7]
	v_mfma_f32_16x16x32_bf16 v[0:3], v[180:183], v[216:219], v[0:3]
	v_mfma_f32_16x16x32_bf16 v[52:55], v[176:179], v[196:199], v[52:55]
	v_mfma_f32_16x16x32_bf16 v[48:51], v[184:187], v[196:199], v[48:51]
	v_mfma_f32_16x16x32_bf16 v[36:39], v[176:179], v[204:207], v[36:39]
	v_mfma_f32_16x16x32_bf16 v[32:35], v[184:187], v[204:207], v[32:35]
	v_mfma_f32_16x16x32_bf16 v[20:23], v[176:179], v[212:215], v[20:23]
	v_mfma_f32_16x16x32_bf16 v[16:19], v[184:187], v[212:215], v[16:19]
	v_mfma_f32_16x16x32_bf16 v[4:7], v[176:179], v[220:223], v[4:7]
	v_mfma_f32_16x16x32_bf16 v[0:3], v[184:187], v[220:223], v[0:3]
	s_barrier
	s_setprio 0
	s_add_i32 s55, s55, 2
	s_add_u32 s14, s14, 0x100
	s_addc_u32 s15, s15, 0
	s_add_u32 s53, s53, 0x100
	s_addc_u32 s54, s54, 0
	s_cmp_gt_u32 s55, 41
	s_cbranch_scc0 .LBB0_891
